# GEMM main loops: all s_setprio flips removed (6x-amplified gate_up phase timing showed about 1.5 percent less GEMM time without them)
# speedup vs baseline: 1.0084x; 1.0084x over previous
; #define PG8_STAGE(bufoff, gbase, voff) do { _Pragma("unroll") for (int _i = 0; _i < 2; ++_i) \
;         __builtin_amdgcn_global_load_lds((const unsigned*)((const char*)(gbase) + (voff)[_i]), (LAS unsigned*)(lds + (bufoff) + ldsw + _i * 8192), 16, 0, 0); } while (0)
; #define PG8_LDA(dst, b, h) do { _Pragma("unroll") for (int m = 0; m < 4; ++m) _Pragma("unroll") for (int k = 0; k < 2; ++k) dst[m][k] = *(const LAS bf16x8*)(lds + PG8_SA(b, h) + aoff + m * 2048 + k * 1024); } while (0)
; #define PG8_LDB(dst, b, h) do { _Pragma("unroll") for (int n = 0; n < 2; ++n) _Pragma("unroll") for (int k = 0; k < 2; ++k) dst[n][k] = *(const LAS bf16x8*)(lds + PG8_SB(b, h) + boff + n * 2048 + k * 1024); } while (0)
; #define PG8_MMA(ai, bj, At, Bt) do { __builtin_amdgcn_s_setprio(1); _Pragma("unroll") for (int m = 0; m < 4; ++m) _Pragma("unroll") for (int n = 0; n < 2; ++n) _Pragma("unroll") for (int k = 0; k < 2; ++k) \
;         acc[ai][bj][m][n] = __builtin_amdgcn_mfma_f32_16x16x32_bf16(Bt[n][k], At[m][k], acc[ai][bj][m][n], 0, 0, 0); __builtin_amdgcn_s_setprio(0); } while (0)
; #define PG8_WAIT_V(n) asm volatile("s_waitcnt vmcnt(" #n ")" ::: "memory")
; #define PG8_WAIT_L(n) asm volatile("s_waitcnt lgkmcnt(" #n ")" ::: "memory")
; #define PG8_BAR __builtin_amdgcn_s_barrier()
; #define PG8_SCHED __builtin_amdgcn_sched_barrier(0)
; template <class Epi>
; __device__ __forceinline__ void gemm_phase(LAS unsigned char* lds, const Gemm g, const Epi& E) {
;     ...
;             PG8_LDB(B0, 0, 0); PG8_SCHED; PG8_LDA(At, 0, 0); PG8_STAGE(PG8_SA(1, 1), a1 + hstep, voffA);
;             PG8_WAIT_L(8); PG8_BAR; PG8_WAIT_L(0); PG8_MMA(0, 0, At, B0); PG8_BAR; PG8_SCHED;
;             PG8_LDB(B1, 0, 1); PG8_STAGE(PG8_SB(0, 0), b2, voffB);
;             PG8_BAR; PG8_WAIT_L(0); PG8_MMA(0, 1, At, B1); PG8_BAR;
;             PG8_LDA(At, 0, 1); PG8_STAGE(PG8_SA(0, 0), a2, voffA);
;             PG8_BAR; PG8_WAIT_L(0); PG8_MMA(1, 0, At, B0); PG8_BAR; PG8_SCHED;
;             PG8_STAGE(PG8_SB(0, 1), b2 + hstep, voffB);
;             PG8_WAIT_V(6); PG8_BAR; PG8_MMA(1, 1, At, B1); PG8_BAR;
.LBB0_30:
	s_add_u32 s28, s26, 0xfff80080
	s_addc_u32 s29, s27, -1
	s_add_i32 s34, 0, 0x10000
	v_add_u32_e32 v143, s34, v141
	ds_read_b128 v[144:147], v143
	ds_read_b128 v[148:151], v143 offset:1024
	ds_read_b128 v[152:155], v143 offset:2048
	ds_read_b128 v[156:159], v143 offset:3072
	s_cmp_eq_u32 s89, 28
	s_cselect_b32 s37, s45, s29
	s_cselect_b32 s36, s78, s28
	s_cselect_b32 s29, s43, s83
	s_cselect_b32 s28, s79, s82
	s_add_i32 m0, s39, 0xc000
	ds_read_b128 v[160:163], v142
	ds_read_b128 v[164:167], v142 offset:1024
	ds_read_b128 v[168:171], v142 offset:2048
	ds_read_b128 v[172:175], v142 offset:3072
	ds_read_b128 v[176:179], v142 offset:4096
	ds_read_b128 v[180:183], v142 offset:5120
	ds_read_b128 v[184:187], v142 offset:6144
	ds_read_b128 v[188:191], v142 offset:7168
	global_load_lds_dwordx4 v136, s[26:27]
	s_add_i32 m0, s39, 0xe000
	s_nop 0
	global_load_lds_dwordx4 v138, s[26:27]
	s_waitcnt lgkmcnt(8)
	s_barrier
	s_waitcnt lgkmcnt(0)
	v_mfma_f32_16x16x32_bf16 v[124:127], v[144:147], v[160:163], v[124:127]
	v_mfma_f32_16x16x32_bf16 v[116:119], v[152:155], v[160:163], v[116:119]
	v_mfma_f32_16x16x32_bf16 v[108:111], v[144:147], v[168:171], v[108:111]
	v_mfma_f32_16x16x32_bf16 v[100:103], v[152:155], v[168:171], v[100:103]
	v_mfma_f32_16x16x32_bf16 v[92:95], v[144:147], v[176:179], v[92:95]
	v_mfma_f32_16x16x32_bf16 v[84:87], v[152:155], v[176:179], v[84:87]
	v_mfma_f32_16x16x32_bf16 v[76:79], v[144:147], v[184:187], v[76:79]
	v_mfma_f32_16x16x32_bf16 v[68:71], v[152:155], v[184:187], v[68:71]
	v_mfma_f32_16x16x32_bf16 v[124:127], v[148:151], v[164:167], v[124:127]
	v_mfma_f32_16x16x32_bf16 v[116:119], v[156:159], v[164:167], v[116:119]
	v_mfma_f32_16x16x32_bf16 v[108:111], v[148:151], v[172:175], v[108:111]
	v_mfma_f32_16x16x32_bf16 v[100:103], v[156:159], v[172:175], v[100:103]
	v_mfma_f32_16x16x32_bf16 v[92:95], v[148:151], v[180:183], v[92:95]
	v_mfma_f32_16x16x32_bf16 v[84:87], v[156:159], v[180:183], v[84:87]
	v_mfma_f32_16x16x32_bf16 v[76:79], v[148:151], v[188:191], v[76:79]
	v_mfma_f32_16x16x32_bf16 v[68:71], v[156:159], v[188:191], v[68:71]
	s_barrier
	s_add_i32 s46, 0, 0x14000
	s_add_i32 s34, s34, s31
	v_add_u32_e32 v143, s46, v141
	s_mov_b32 m0, s34
	ds_read_b128 v[192:195], v143
	ds_read_b128 v[196:199], v143 offset:1024
	ds_read_b128 v[200:203], v143 offset:2048
	ds_read_b128 v[204:207], v143 offset:3072
	global_load_lds_dwordx4 v132, s[28:29]
	s_add_i32 m0, s34, 0x2000
	s_nop 0
	global_load_lds_dwordx4 v128, s[28:29]
	s_barrier
	s_waitcnt lgkmcnt(0)
	v_mfma_f32_16x16x32_bf16 v[120:123], v[192:195], v[160:163], v[120:123]
	v_mfma_f32_16x16x32_bf16 v[112:115], v[200:203], v[160:163], v[112:115]
	v_mfma_f32_16x16x32_bf16 v[104:107], v[192:195], v[168:171], v[104:107]
	v_mfma_f32_16x16x32_bf16 v[96:99], v[200:203], v[168:171], v[96:99]
	v_mfma_f32_16x16x32_bf16 v[88:91], v[192:195], v[176:179], v[88:91]
	v_mfma_f32_16x16x32_bf16 v[80:83], v[200:203], v[176:179], v[80:83]
	v_mfma_f32_16x16x32_bf16 v[72:75], v[192:195], v[184:187], v[72:75]
	v_mfma_f32_16x16x32_bf16 v[64:67], v[200:203], v[184:187], v[64:67]
	v_mfma_f32_16x16x32_bf16 v[120:123], v[196:199], v[164:167], v[120:123]
	v_mfma_f32_16x16x32_bf16 v[112:115], v[204:207], v[164:167], v[112:115]
	v_mfma_f32_16x16x32_bf16 v[104:107], v[196:199], v[172:175], v[104:107]
	v_mfma_f32_16x16x32_bf16 v[96:99], v[204:207], v[172:175], v[96:99]
	v_mfma_f32_16x16x32_bf16 v[88:91], v[196:199], v[180:183], v[88:91]
	v_mfma_f32_16x16x32_bf16 v[80:83], v[204:207], v[180:183], v[80:83]
	v_mfma_f32_16x16x32_bf16 v[72:75], v[196:199], v[188:191], v[72:75]
	v_mfma_f32_16x16x32_bf16 v[64:67], v[204:207], v[188:191], v[64:67]
	s_barrier
	s_mov_b32 m0, s39
	ds_read_b128 v[160:163], v142 offset:16384
	ds_read_b128 v[164:167], v142 offset:17408
	ds_read_b128 v[168:171], v142 offset:18432
	ds_read_b128 v[172:175], v142 offset:19456
	ds_read_b128 v[176:179], v142 offset:20480
	ds_read_b128 v[180:183], v142 offset:21504
	ds_read_b128 v[184:187], v142 offset:22528
	ds_read_b128 v[188:191], v142 offset:23552
	global_load_lds_dwordx4 v134, s[36:37]
	s_mov_b32 m0, s68
	s_nop 0
	global_load_lds_dwordx4 v130, s[36:37]
	s_barrier
	s_waitcnt lgkmcnt(0)
	v_mfma_f32_16x16x32_bf16 v[60:63], v[144:147], v[160:163], v[60:63]
	v_mfma_f32_16x16x32_bf16 v[52:55], v[152:155], v[160:163], v[52:55]
	v_mfma_f32_16x16x32_bf16 v[44:47], v[144:147], v[168:171], v[44:47]
	v_mfma_f32_16x16x32_bf16 v[36:39], v[152:155], v[168:171], v[36:39]
	v_mfma_f32_16x16x32_bf16 v[28:31], v[144:147], v[176:179], v[28:31]
	v_mfma_f32_16x16x32_bf16 v[20:23], v[152:155], v[176:179], v[20:23]
	v_mfma_f32_16x16x32_bf16 v[12:15], v[144:147], v[184:187], v[12:15]
	v_mfma_f32_16x16x32_bf16 v[4:7], v[152:155], v[184:187], v[4:7]
	v_mfma_f32_16x16x32_bf16 v[60:63], v[148:151], v[164:167], v[60:63]
	v_mfma_f32_16x16x32_bf16 v[52:55], v[156:159], v[164:167], v[52:55]
	v_mfma_f32_16x16x32_bf16 v[44:47], v[148:151], v[172:175], v[44:47]
	v_mfma_f32_16x16x32_bf16 v[36:39], v[156:159], v[172:175], v[36:39]
	v_mfma_f32_16x16x32_bf16 v[28:31], v[148:151], v[180:183], v[28:31]
	v_mfma_f32_16x16x32_bf16 v[20:23], v[156:159], v[180:183], v[20:23]
	v_mfma_f32_16x16x32_bf16 v[12:15], v[148:151], v[188:191], v[12:15]
	v_mfma_f32_16x16x32_bf16 v[4:7], v[156:159], v[188:191], v[4:7]
	s_barrier
	s_add_u32 s34, s28, 0x80000
	s_addc_u32 s35, s29, 0
	s_add_i32 s46, s46, s31
	s_mov_b32 m0, s46
	s_nop 0
	global_load_lds_dwordx4 v132, s[34:35]
	s_add_i32 m0, s46, 0x2000
	s_nop 0
	global_load_lds_dwordx4 v128, s[34:35]
	s_waitcnt vmcnt(6)
	s_barrier
; #define PG8_STAGE(bufoff, gbase, voff) do { _Pragma("unroll") for (int _i = 0; _i < 2; ++_i) \
;         __builtin_amdgcn_global_load_lds((const unsigned*)((const char*)(gbase) + (voff)[_i]), (LAS unsigned*)(lds + (bufoff) + ldsw + _i * 8192), 16, 0, 0); } while (0)
; #define PG8_LDA(dst, b, h) do { _Pragma("unroll") for (int m = 0; m < 4; ++m) _Pragma("unroll") for (int k = 0; k < 2; ++k) dst[m][k] = *(const LAS bf16x8*)(lds + PG8_SA(b, h) + aoff + m * 2048 + k * 1024); } while (0)
; #define PG8_LDB(dst, b, h) do { _Pragma("unroll") for (int n = 0; n < 2; ++n) _Pragma("unroll") for (int k = 0; k < 2; ++k) dst[n][k] = *(const LAS bf16x8*)(lds + PG8_SB(b, h) + boff + n * 2048 + k * 1024); } while (0)
; #define PG8_MMA(ai, bj, At, Bt) do { __builtin_amdgcn_s_setprio(1); _Pragma("unroll") for (int m = 0; m < 4; ++m) _Pragma("unroll") for (int n = 0; n < 2; ++n) _Pragma("unroll") for (int k = 0; k < 2; ++k) \
;         acc[ai][bj][m][n] = __builtin_amdgcn_mfma_f32_16x16x32_bf16(Bt[n][k], At[m][k], acc[ai][bj][m][n], 0, 0, 0); __builtin_amdgcn_s_setprio(0); } while (0)
; #define PG8_WAIT_V(n) asm volatile("s_waitcnt vmcnt(" #n ")" ::: "memory")
; #define PG8_WAIT_L(n) asm volatile("s_waitcnt lgkmcnt(" #n ")" ::: "memory")
; #define PG8_BAR __builtin_amdgcn_s_barrier()
; #define PG8_SCHED __builtin_amdgcn_sched_barrier(0)
; template <class Epi>
; __device__ __forceinline__ void gemm_phase(LAS unsigned char* lds, const Gemm g, const Epi& E) {
;     ...
;             PG8_WAIT_V(6); PG8_BAR; PG8_MMA(1, 1, At, B1); PG8_BAR;
;             PG8_LDB(B0, 1, 0); PG8_SCHED; PG8_LDA(At, 1, 0); PG8_STAGE(PG8_SA(0, 1), a2 + hstep, voffA);
;             PG8_WAIT_L(8); PG8_BAR; PG8_WAIT_L(0); PG8_MMA(0, 0, At, B0); PG8_BAR; PG8_SCHED;
;             PG8_LDB(B1, 1, 1); PG8_STAGE(PG8_SB(1, 0), b3, voffB);
;             PG8_BAR; PG8_WAIT_L(0); PG8_MMA(0, 1, At, B1); PG8_BAR;
;             PG8_LDA(At, 1, 1); PG8_STAGE(PG8_SA(1, 0), a3, voffA);
;             PG8_BAR; PG8_WAIT_L(0); PG8_MMA(1, 0, At, B0); PG8_BAR; PG8_SCHED;
	v_mfma_f32_16x16x32_bf16 v[56:59], v[192:195], v[160:163], v[56:59]
	v_mfma_f32_16x16x32_bf16 v[48:51], v[200:203], v[160:163], v[48:51]
	v_mfma_f32_16x16x32_bf16 v[40:43], v[192:195], v[168:171], v[40:43]
	v_mfma_f32_16x16x32_bf16 v[32:35], v[200:203], v[168:171], v[32:35]
	v_mfma_f32_16x16x32_bf16 v[24:27], v[192:195], v[176:179], v[24:27]
	v_mfma_f32_16x16x32_bf16 v[16:19], v[200:203], v[176:179], v[16:19]
	v_mfma_f32_16x16x32_bf16 v[8:11], v[192:195], v[184:187], v[8:11]
	v_mfma_f32_16x16x32_bf16 v[0:3], v[200:203], v[184:187], v[0:3]
	v_mfma_f32_16x16x32_bf16 v[56:59], v[196:199], v[164:167], v[56:59]
	v_mfma_f32_16x16x32_bf16 v[48:51], v[204:207], v[164:167], v[48:51]
	v_mfma_f32_16x16x32_bf16 v[40:43], v[196:199], v[172:175], v[40:43]
	v_mfma_f32_16x16x32_bf16 v[32:35], v[204:207], v[172:175], v[32:35]
	v_mfma_f32_16x16x32_bf16 v[24:27], v[196:199], v[180:183], v[24:27]
	v_mfma_f32_16x16x32_bf16 v[16:19], v[204:207], v[180:183], v[16:19]
	v_mfma_f32_16x16x32_bf16 v[8:11], v[196:199], v[188:191], v[8:11]
	v_mfma_f32_16x16x32_bf16 v[0:3], v[204:207], v[188:191], v[0:3]
	s_barrier
	s_add_i32 s46, 0, 0x18000
	v_add_u32_e32 v143, s46, v141
	ds_read_b128 v[144:147], v143
	ds_read_b128 v[148:151], v143 offset:1024
	ds_read_b128 v[152:155], v143 offset:2048
	ds_read_b128 v[156:159], v143 offset:3072
	s_add_u32 s34, s36, 0x80000
	s_addc_u32 s35, s37, 0
	s_mov_b32 m0, s69
	ds_read_b128 v[160:163], v142 offset:32768
	ds_read_b128 v[164:167], v142 offset:33792
	ds_read_b128 v[168:171], v142 offset:34816
	ds_read_b128 v[172:175], v142 offset:35840
	ds_read_b128 v[176:179], v142 offset:36864
	ds_read_b128 v[180:183], v142 offset:37888
	ds_read_b128 v[184:187], v142 offset:38912
	ds_read_b128 v[188:191], v142 offset:39936
	global_load_lds_dwordx4 v134, s[34:35]
	s_mov_b32 m0, s70
	s_nop 0
	global_load_lds_dwordx4 v130, s[34:35]
	s_waitcnt lgkmcnt(8)
	s_barrier
	s_waitcnt lgkmcnt(0)
	v_mfma_f32_16x16x32_bf16 v[124:127], v[144:147], v[160:163], v[124:127]
	v_mfma_f32_16x16x32_bf16 v[116:119], v[152:155], v[160:163], v[116:119]
	v_mfma_f32_16x16x32_bf16 v[108:111], v[144:147], v[168:171], v[108:111]
	v_mfma_f32_16x16x32_bf16 v[100:103], v[152:155], v[168:171], v[100:103]
	v_mfma_f32_16x16x32_bf16 v[92:95], v[144:147], v[176:179], v[92:95]
	v_mfma_f32_16x16x32_bf16 v[84:87], v[152:155], v[176:179], v[84:87]
	v_mfma_f32_16x16x32_bf16 v[76:79], v[144:147], v[184:187], v[76:79]
	v_mfma_f32_16x16x32_bf16 v[68:71], v[152:155], v[184:187], v[68:71]
	v_mfma_f32_16x16x32_bf16 v[124:127], v[148:151], v[164:167], v[124:127]
	v_mfma_f32_16x16x32_bf16 v[116:119], v[156:159], v[164:167], v[116:119]
	v_mfma_f32_16x16x32_bf16 v[108:111], v[148:151], v[172:175], v[108:111]
	v_mfma_f32_16x16x32_bf16 v[100:103], v[156:159], v[172:175], v[100:103]
	v_mfma_f32_16x16x32_bf16 v[92:95], v[148:151], v[180:183], v[92:95]
	v_mfma_f32_16x16x32_bf16 v[84:87], v[156:159], v[180:183], v[84:87]
	v_mfma_f32_16x16x32_bf16 v[76:79], v[148:151], v[188:191], v[76:79]
	v_mfma_f32_16x16x32_bf16 v[68:71], v[156:159], v[188:191], v[68:71]
	s_barrier
	s_add_i32 s34, 0, 0x1c000
	s_add_i32 s35, s46, s31
	v_add_u32_e32 v143, s34, v141
	s_mov_b32 m0, s35
	ds_read_b128 v[192:195], v143
	ds_read_b128 v[196:199], v143 offset:1024
	ds_read_b128 v[200:203], v143 offset:2048
	ds_read_b128 v[204:207], v143 offset:3072
	s_add_u32 s98, s28, 0x80
	s_addc_u32 s99, s29, 0
	global_load_lds_dwordx4 v132, s[98:99]
	s_add_i32 m0, s35, 0x2000
	s_add_u32 s100, s28, 0x80
	s_addc_u32 s101, s29, 0
	global_load_lds_dwordx4 v128, s[100:101]
	s_barrier
	s_waitcnt lgkmcnt(0)
	v_mfma_f32_16x16x32_bf16 v[120:123], v[192:195], v[160:163], v[120:123]
	v_mfma_f32_16x16x32_bf16 v[112:115], v[200:203], v[160:163], v[112:115]
	v_mfma_f32_16x16x32_bf16 v[104:107], v[192:195], v[168:171], v[104:107]
	v_mfma_f32_16x16x32_bf16 v[96:99], v[200:203], v[168:171], v[96:99]
	v_mfma_f32_16x16x32_bf16 v[88:91], v[192:195], v[176:179], v[88:91]
	v_mfma_f32_16x16x32_bf16 v[80:83], v[200:203], v[176:179], v[80:83]
	v_mfma_f32_16x16x32_bf16 v[72:75], v[192:195], v[184:187], v[72:75]
	v_mfma_f32_16x16x32_bf16 v[64:67], v[200:203], v[184:187], v[64:67]
	v_mfma_f32_16x16x32_bf16 v[120:123], v[196:199], v[164:167], v[120:123]
	v_mfma_f32_16x16x32_bf16 v[112:115], v[204:207], v[164:167], v[112:115]
	v_mfma_f32_16x16x32_bf16 v[104:107], v[196:199], v[172:175], v[104:107]
	v_mfma_f32_16x16x32_bf16 v[96:99], v[204:207], v[172:175], v[96:99]
	v_mfma_f32_16x16x32_bf16 v[88:91], v[196:199], v[180:183], v[88:91]
	v_mfma_f32_16x16x32_bf16 v[80:83], v[204:207], v[180:183], v[80:83]
	v_mfma_f32_16x16x32_bf16 v[72:75], v[196:199], v[188:191], v[72:75]
	v_mfma_f32_16x16x32_bf16 v[64:67], v[204:207], v[188:191], v[64:67]
	s_barrier
	s_mov_b32 m0, s2
	ds_read_b128 v[160:163], v142 offset:49152
	ds_read_b128 v[164:167], v142 offset:50176
	ds_read_b128 v[168:171], v142 offset:51200
	ds_read_b128 v[172:175], v142 offset:52224
	ds_read_b128 v[176:179], v142 offset:53248
	ds_read_b128 v[180:183], v142 offset:54272
	ds_read_b128 v[184:187], v142 offset:55296
	ds_read_b128 v[188:191], v142 offset:56320
	s_add_u32 s98, s36, 0x80
	s_addc_u32 s99, s37, 0
	global_load_lds_dwordx4 v134, s[98:99]
	s_mov_b32 m0, s71
	s_add_u32 s100, s36, 0x80
	s_addc_u32 s101, s37, 0
	global_load_lds_dwordx4 v130, s[100:101]
	s_barrier
; __device__ __forceinline__ u32x4 pack8u(f32x4 a, f32x4 b) { u32x4 w = {cvt_pk_bf16(a[0], a[1]), cvt_pk_bf16(a[2], a[3]), cvt_pk_bf16(b[0], b[1]), cvt_pk_bf16(b[2], b[3])}; return w; }
; __device__ __forceinline__ float siluf_(float x) { return x * __builtin_amdgcn_rcpf(1.0f + __expf(-x)); }
; #define PG8_STAGE(bufoff, gbase, voff) do { _Pragma("unroll") for (int _i = 0; _i < 2; ++_i) \
;         __builtin_amdgcn_global_load_lds((const unsigned*)((const char*)(gbase) + (voff)[_i]), (LAS unsigned*)(lds + (bufoff) + ldsw + _i * 8192), 16, 0, 0); } while (0)
; #define PG8_MMA(ai, bj, At, Bt) do { __builtin_amdgcn_s_setprio(1); _Pragma("unroll") for (int m = 0; m < 4; ++m) _Pragma("unroll") for (int n = 0; n < 2; ++n) _Pragma("unroll") for (int k = 0; k < 2; ++k) \
;         acc[ai][bj][m][n] = __builtin_amdgcn_mfma_f32_16x16x32_bf16(Bt[n][k], At[m][k], acc[ai][bj][m][n], 0, 0, 0); __builtin_amdgcn_s_setprio(0); } while (0)
; #define PG8_WAIT_V(n) asm volatile("s_waitcnt vmcnt(" #n ")" ::: "memory")
; #define PG8_WAIT_L(n) asm volatile("s_waitcnt lgkmcnt(" #n ")" ::: "memory")
; #define PG8_BAR __builtin_amdgcn_s_barrier()
; #define PG8_SCHED __builtin_amdgcn_sched_barrier(0)
; template <class Epi>
; __device__ __forceinline__ void gemm_phase(LAS unsigned char* lds, const Gemm g, const Epi& E) {
;     ...
;             PG8_BAR; PG8_WAIT_L(0); PG8_MMA(1, 0, At, B0); PG8_BAR; PG8_SCHED;
;             PG8_STAGE(PG8_SB(1, 1), b3 + hstep, voffB);
;             PG8_WAIT_V(6); PG8_BAR; PG8_MMA(1, 1, At, B1); PG8_BAR;
;         }
;     __device__ __forceinline__ void operator()(const AccT& acc, const Unit& u, int wr, int wc, int fr, int fq) const {
; #pragma unroll
;         for (int ai = 0; ai < 2; ++ai)
; #pragma unroll
;             for (int m = 0; m < 4; ++m) {
;                 const int row = u.pm * 256 + ai * 128 + wr * 64 + m * 16 + fr;
;                 f32x4 o0, o1;
; #pragma unroll
;                 for (int j = 0; j < 4; ++j) { o0[j] = siluf_(acc[ai][0][m][0][j]) * acc[ai][1][m][0][j]; o1[j] = siluf_(acc[ai][0][m][1][j]) * acc[ai][1][m][1][j]; }
;                 *(u32x4*)(ACT + (size_t)row * DFF + u.pn * 128 + wc * 32 + fq * 8) = pack8u(o0, o1);
	s_waitcnt lgkmcnt(0)
	v_mfma_f32_16x16x32_bf16 v[60:63], v[144:147], v[160:163], v[60:63]
	v_mfma_f32_16x16x32_bf16 v[52:55], v[152:155], v[160:163], v[52:55]
	v_mfma_f32_16x16x32_bf16 v[44:47], v[144:147], v[168:171], v[44:47]
	v_mfma_f32_16x16x32_bf16 v[36:39], v[152:155], v[168:171], v[36:39]
	v_mfma_f32_16x16x32_bf16 v[28:31], v[144:147], v[176:179], v[28:31]
	v_mfma_f32_16x16x32_bf16 v[20:23], v[152:155], v[176:179], v[20:23]
	v_mfma_f32_16x16x32_bf16 v[12:15], v[144:147], v[184:187], v[12:15]
	v_mfma_f32_16x16x32_bf16 v[4:7], v[152:155], v[184:187], v[4:7]
	v_mfma_f32_16x16x32_bf16 v[60:63], v[148:151], v[164:167], v[60:63]
	v_mfma_f32_16x16x32_bf16 v[52:55], v[156:159], v[164:167], v[52:55]
	v_mfma_f32_16x16x32_bf16 v[44:47], v[148:151], v[172:175], v[44:47]
	v_mfma_f32_16x16x32_bf16 v[36:39], v[156:159], v[172:175], v[36:39]
	v_mfma_f32_16x16x32_bf16 v[28:31], v[148:151], v[180:183], v[28:31]
	v_mfma_f32_16x16x32_bf16 v[20:23], v[156:159], v[180:183], v[20:23]
	v_mfma_f32_16x16x32_bf16 v[12:15], v[148:151], v[188:191], v[12:15]
	v_mfma_f32_16x16x32_bf16 v[4:7], v[156:159], v[188:191], v[4:7]
	s_barrier
	s_add_u32 s28, s28, 0x80080
	s_addc_u32 s29, s29, 0
	s_add_i32 s34, s34, s31
	s_mov_b32 m0, s34
	s_nop 0
	global_load_lds_dwordx4 v132, s[28:29]
	s_add_i32 m0, s34, 0x2000
	s_nop 0
	global_load_lds_dwordx4 v128, s[28:29]
	s_waitcnt vmcnt(6)
	s_barrier
	v_mfma_f32_16x16x32_bf16 v[56:59], v[192:195], v[160:163], v[56:59]
	v_mfma_f32_16x16x32_bf16 v[48:51], v[200:203], v[160:163], v[48:51]
	v_mfma_f32_16x16x32_bf16 v[40:43], v[192:195], v[168:171], v[40:43]
	v_mfma_f32_16x16x32_bf16 v[32:35], v[200:203], v[168:171], v[32:35]
	v_mfma_f32_16x16x32_bf16 v[24:27], v[192:195], v[176:179], v[24:27]
	v_mfma_f32_16x16x32_bf16 v[16:19], v[200:203], v[176:179], v[16:19]
	v_mfma_f32_16x16x32_bf16 v[8:11], v[192:195], v[184:187], v[8:11]
	v_mfma_f32_16x16x32_bf16 v[0:3], v[200:203], v[184:187], v[0:3]
	v_mfma_f32_16x16x32_bf16 v[56:59], v[196:199], v[164:167], v[56:59]
	v_mfma_f32_16x16x32_bf16 v[48:51], v[204:207], v[164:167], v[48:51]
	v_mfma_f32_16x16x32_bf16 v[40:43], v[196:199], v[172:175], v[40:43]
	v_mfma_f32_16x16x32_bf16 v[32:35], v[204:207], v[172:175], v[32:35]
	v_mfma_f32_16x16x32_bf16 v[24:27], v[196:199], v[180:183], v[24:27]
	v_mfma_f32_16x16x32_bf16 v[16:19], v[204:207], v[180:183], v[16:19]
	v_mfma_f32_16x16x32_bf16 v[8:11], v[196:199], v[188:191], v[8:11]
	v_mfma_f32_16x16x32_bf16 v[0:3], v[204:207], v[188:191], v[0:3]
	s_barrier
	s_add_i32 s89, s89, 2
	s_add_u32 s26, s26, 0x100
	s_addc_u32 s27, s27, 0
	s_add_u32 s82, s82, 0x100
	s_addc_u32 s83, s83, 0
	s_cmp_gt_u32 s89, 29
	s_cbranch_scc0 .LBB0_30
	v_mul_f32_e32 v145, 0xbfb8aa3b, v116
	v_exp_f32_e32 v145, v145
	v_mul_f32_e32 v144, 0xbfb8aa3b, v124
	v_exp_f32_e32 v144, v144
	v_readlane_b32 s28, v252, 37
	v_add_f32_e32 v145, 1.0, v145
	v_rcp_f32_e32 v146, v145
	v_mul_f32_e32 v145, 0xbfb8aa3b, v125
	v_exp_f32_e32 v145, v145
	v_add_f32_e32 v144, 1.0, v144
	v_rcp_f32_e32 v144, v144
	s_lshl_b32 s26, s76, 7
	v_add_f32_e32 v145, 1.0, v145
	v_rcp_f32_e32 v145, v145
	v_readlane_b32 s29, v252, 38
	v_lshl_add_u32 v143, s88, 8, v140
	s_ashr_i32 s27, s26, 31
	v_pk_mul_f32 v[124:125], v[124:125], v[144:145]
	s_movk_i32 s34, 0x2c00
	v_pk_mul_f32 v[120:121], v[124:125], v[120:121]
	v_mul_f32_e32 v124, 0xbfb8aa3b, v117
	v_exp_f32_e32 v124, v124
	s_lshl_b64 s[88:89], s[26:27], 1
	s_and_b64 vcc, exec, s[40:41]
	s_mov_b32 s76, s42
	v_add_f32_e32 v124, 1.0, v124
	v_rcp_f32_e32 v147, v124
	s_nop 0
	v_pk_mul_f32 v[116:117], v[116:117], v[146:147]
	s_nop 0
	v_pk_mul_f32 v[112:113], v[116:117], v[112:113]
	v_mul_f32_e32 v117, 0xbfb8aa3b, v118
	v_exp_f32_e32 v117, v117
	v_mul_f32_e32 v116, 0xbfb8aa3b, v126
	v_exp_f32_e32 v116, v116
	v_add_f32_e32 v117, 1.0, v117
	v_rcp_f32_e32 v124, v117
	v_mul_f32_e32 v117, 0xbfb8aa3b, v127
	v_exp_f32_e32 v117, v117
	v_add_f32_e32 v116, 1.0, v116
	v_rcp_f32_e32 v116, v116
	v_add_f32_e32 v117, 1.0, v117
	v_rcp_f32_e32 v117, v117
	s_nop 0
	v_pk_mul_f32 v[116:117], v[126:127], v[116:117]
	s_nop 0
	v_pk_mul_f32 v[116:117], v[116:117], v[122:123]
	v_mul_f32_e32 v122, 0xbfb8aa3b, v119
	v_exp_f32_e32 v122, v122
	s_nop 0
	v_add_f32_e32 v122, 1.0, v122
	v_rcp_f32_e32 v125, v122
	s_nop 0
	v_pk_mul_f32 v[118:119], v[118:119], v[124:125]
	s_nop 0
	v_pk_mul_f32 v[118:119], v[118:119], v[114:115]
	v_cvt_pk_bf16_f32 v115, v116, v117
	v_cvt_pk_bf16_f32 v116, v112, v113
	v_mov_b64_e32 v[112:113], s[28:29]
	v_cvt_pk_bf16_f32 v117, v118, v119
	v_mad_i64_i32 v[118:119], s[28:29], v143, s34, v[112:113]
	v_lshl_add_u64 v[118:119], v[118:119], 0, s[88:89]
	s_mov_b64 s[28:29], s[90:91]
	v_lshl_add_u64 v[118:119], v[118:119], 0, s[28:29]
	v_cvt_pk_bf16_f32 v114, v120, v121
	v_lshl_add_u64 v[118:119], v[118:119], 0, v[208:209]
	global_store_dwordx4 v[118:119], v[114:117], off
	s_nop 1
	v_mul_f32_e32 v115, 0xbfb8aa3b, v100
	v_exp_f32_e32 v115, v115
	v_mul_f32_e32 v114, 0xbfb8aa3b, v108
	v_exp_f32_e32 v114, v114
	v_add_f32_e32 v115, 1.0, v115
	v_rcp_f32_e32 v116, v115
	v_mul_f32_e32 v115, 0xbfb8aa3b, v109
	v_exp_f32_e32 v115, v115
	v_add_f32_e32 v114, 1.0, v114
	v_rcp_f32_e32 v114, v114
	v_add_f32_e32 v115, 1.0, v115
	v_rcp_f32_e32 v115, v115
	s_nop 0
	v_pk_mul_f32 v[108:109], v[108:109], v[114:115]
	s_nop 0
	v_pk_mul_f32 v[104:105], v[108:109], v[104:105]
	v_mul_f32_e32 v108, 0xbfb8aa3b, v101
	v_exp_f32_e32 v108, v108
	s_nop 0
	v_add_f32_e32 v108, 1.0, v108
	v_rcp_f32_e32 v117, v108
	s_nop 0
	v_pk_mul_f32 v[100:101], v[100:101], v[116:117]
	s_nop 0
	v_pk_mul_f32 v[100:101], v[100:101], v[96:97]
	v_mul_f32_e32 v97, 0xbfb8aa3b, v102
	v_exp_f32_e32 v97, v97
	v_mul_f32_e32 v96, 0xbfb8aa3b, v110
; __device__ __forceinline__ u32x4 pack8u(f32x4 a, f32x4 b) { u32x4 w = {cvt_pk_bf16(a[0], a[1]), cvt_pk_bf16(a[2], a[3]), cvt_pk_bf16(b[0], b[1]), cvt_pk_bf16(b[2], b[3])}; return w; }
; __device__ __forceinline__ float siluf_(float x) { return x * __builtin_amdgcn_rcpf(1.0f + __expf(-x)); }
;     __device__ __forceinline__ void operator()(const AccT& acc, const Unit& u, int wr, int wc, int fr, int fq) const {
; #pragma unroll
;         for (int ai = 0; ai < 2; ++ai)
; #pragma unroll
;             for (int m = 0; m < 4; ++m) {
;                 const int row = u.pm * 256 + ai * 128 + wr * 64 + m * 16 + fr;
;                 f32x4 o0, o1;
; #pragma unroll
;                 for (int j = 0; j < 4; ++j) { o0[j] = siluf_(acc[ai][0][m][0][j]) * acc[ai][1][m][0][j]; o1[j] = siluf_(acc[ai][0][m][1][j]) * acc[ai][1][m][1][j]; }
;                 *(u32x4*)(ACT + (size_t)row * DFF + u.pn * 128 + wc * 32 + fq * 8) = pack8u(o0, o1);
	v_exp_f32_e32 v96, v96
	v_add_f32_e32 v97, 1.0, v97
	v_rcp_f32_e32 v108, v97
	v_mul_f32_e32 v97, 0xbfb8aa3b, v111
	v_exp_f32_e32 v97, v97
	v_add_f32_e32 v96, 1.0, v96
	v_rcp_f32_e32 v96, v96
	v_add_f32_e32 v97, 1.0, v97
	v_rcp_f32_e32 v97, v97
	s_nop 0
	v_pk_mul_f32 v[96:97], v[110:111], v[96:97]
	s_nop 0
	v_pk_mul_f32 v[106:107], v[96:97], v[106:107]
	v_mul_f32_e32 v96, 0xbfb8aa3b, v103
	v_exp_f32_e32 v96, v96
	s_nop 0
	v_add_f32_e32 v96, 1.0, v96
	v_rcp_f32_e32 v109, v96
	s_nop 0
	v_pk_mul_f32 v[96:97], v[102:103], v[108:109]
	v_or_b32_e32 v108, 16, v143
	v_pk_mul_f32 v[102:103], v[96:97], v[98:99]
	v_cvt_pk_bf16_f32 v98, v100, v101
	v_mad_i64_i32 v[100:101], s[26:27], v108, s34, v[112:113]
	v_lshl_add_u64 v[100:101], v[100:101], 0, s[88:89]
	v_lshl_add_u64 v[100:101], v[100:101], 0, s[28:29]
	v_cvt_pk_bf16_f32 v96, v104, v105
	v_cvt_pk_bf16_f32 v97, v106, v107
	v_cvt_pk_bf16_f32 v99, v102, v103
	v_lshl_add_u64 v[100:101], v[100:101], 0, v[208:209]
	global_store_dwordx4 v[100:101], v[96:99], off
	s_nop 1
	v_mul_f32_e32 v97, 0xbfb8aa3b, v84
	v_exp_f32_e32 v97, v97
	v_mul_f32_e32 v96, 0xbfb8aa3b, v92
	v_exp_f32_e32 v96, v96
	v_add_f32_e32 v97, 1.0, v97
	v_rcp_f32_e32 v98, v97
	v_mul_f32_e32 v97, 0xbfb8aa3b, v93
	v_exp_f32_e32 v97, v97
	v_add_f32_e32 v96, 1.0, v96
	v_rcp_f32_e32 v96, v96
	v_add_f32_e32 v97, 1.0, v97
	v_rcp_f32_e32 v97, v97
	s_nop 0
	v_pk_mul_f32 v[92:93], v[92:93], v[96:97]
	s_nop 0
	v_pk_mul_f32 v[88:89], v[92:93], v[88:89]
	v_mul_f32_e32 v92, 0xbfb8aa3b, v85
	v_exp_f32_e32 v92, v92
	s_nop 0
	v_add_f32_e32 v92, 1.0, v92
	v_rcp_f32_e32 v99, v92
	s_nop 0
	v_pk_mul_f32 v[84:85], v[84:85], v[98:99]
	s_nop 0
	v_pk_mul_f32 v[84:85], v[84:85], v[80:81]
	v_mul_f32_e32 v81, 0xbfb8aa3b, v86
	v_exp_f32_e32 v81, v81
	v_mul_f32_e32 v80, 0xbfb8aa3b, v94
	v_exp_f32_e32 v80, v80
	v_add_f32_e32 v81, 1.0, v81
	v_rcp_f32_e32 v92, v81
	v_mul_f32_e32 v81, 0xbfb8aa3b, v95
	v_exp_f32_e32 v81, v81
	v_add_f32_e32 v80, 1.0, v80
	v_rcp_f32_e32 v80, v80
	v_add_f32_e32 v81, 1.0, v81
	v_rcp_f32_e32 v81, v81
	s_nop 0
	v_pk_mul_f32 v[80:81], v[94:95], v[80:81]
	s_nop 0
	v_pk_mul_f32 v[90:91], v[80:81], v[90:91]
	v_mul_f32_e32 v80, 0xbfb8aa3b, v87
	v_exp_f32_e32 v80, v80
	s_nop 0
	v_add_f32_e32 v80, 1.0, v80
	v_rcp_f32_e32 v93, v80
	s_nop 0
	v_pk_mul_f32 v[80:81], v[86:87], v[92:93]
	v_or_b32_e32 v92, 32, v143
	v_pk_mul_f32 v[86:87], v[80:81], v[82:83]
	v_cvt_pk_bf16_f32 v82, v84, v85
	v_mad_i64_i32 v[84:85], s[26:27], v92, s34, v[112:113]
	v_lshl_add_u64 v[84:85], v[84:85], 0, s[88:89]
	v_lshl_add_u64 v[84:85], v[84:85], 0, s[28:29]
	v_cvt_pk_bf16_f32 v80, v88, v89
	v_cvt_pk_bf16_f32 v81, v90, v91
	v_cvt_pk_bf16_f32 v83, v86, v87
	v_lshl_add_u64 v[84:85], v[84:85], 0, v[208:209]
	global_store_dwordx4 v[84:85], v[80:83], off
	s_nop 1
	v_mul_f32_e32 v81, 0xbfb8aa3b, v68
	v_exp_f32_e32 v81, v81
	v_mul_f32_e32 v80, 0xbfb8aa3b, v76
	v_exp_f32_e32 v80, v80
	v_add_f32_e32 v81, 1.0, v81
	v_rcp_f32_e32 v82, v81
	v_mul_f32_e32 v81, 0xbfb8aa3b, v77
	v_exp_f32_e32 v81, v81
	v_add_f32_e32 v80, 1.0, v80
	v_rcp_f32_e32 v80, v80
	v_add_f32_e32 v81, 1.0, v81
	v_rcp_f32_e32 v81, v81
	s_nop 0
	v_pk_mul_f32 v[76:77], v[76:77], v[80:81]
	s_nop 0
	v_pk_mul_f32 v[72:73], v[76:77], v[72:73]
	v_mul_f32_e32 v76, 0xbfb8aa3b, v69
	v_exp_f32_e32 v76, v76
	s_nop 0
	v_add_f32_e32 v76, 1.0, v76
	v_rcp_f32_e32 v83, v76
	s_nop 0
	v_pk_mul_f32 v[68:69], v[68:69], v[82:83]
	s_nop 0
	v_pk_mul_f32 v[68:69], v[68:69], v[64:65]
	v_mul_f32_e32 v65, 0xbfb8aa3b, v70
	v_exp_f32_e32 v65, v65
	v_mul_f32_e32 v64, 0xbfb8aa3b, v78
	v_exp_f32_e32 v64, v64
	v_add_f32_e32 v65, 1.0, v65
	v_rcp_f32_e32 v76, v65
	v_mul_f32_e32 v65, 0xbfb8aa3b, v79
	v_exp_f32_e32 v65, v65
	v_add_f32_e32 v64, 1.0, v64
	v_rcp_f32_e32 v64, v64
	v_add_f32_e32 v65, 1.0, v65
	v_rcp_f32_e32 v65, v65
	s_nop 0
	v_pk_mul_f32 v[64:65], v[78:79], v[64:65]
	s_nop 0
	v_pk_mul_f32 v[74:75], v[64:65], v[74:75]
	v_mul_f32_e32 v64, 0xbfb8aa3b, v71
	v_exp_f32_e32 v64, v64
	s_nop 0
	v_add_f32_e32 v64, 1.0, v64
	v_rcp_f32_e32 v77, v64
	s_nop 0
	v_pk_mul_f32 v[64:65], v[70:71], v[76:77]
	v_or_b32_e32 v76, 48, v143
	v_pk_mul_f32 v[70:71], v[64:65], v[66:67]
	v_cvt_pk_bf16_f32 v66, v68, v69
	v_mad_i64_i32 v[68:69], s[26:27], v76, s34, v[112:113]
	v_lshl_add_u64 v[68:69], v[68:69], 0, s[88:89]
	v_lshl_add_u64 v[68:69], v[68:69], 0, s[28:29]
	v_cvt_pk_bf16_f32 v64, v72, v73
	v_cvt_pk_bf16_f32 v65, v74, v75
	v_cvt_pk_bf16_f32 v67, v70, v71
	v_lshl_add_u64 v[68:69], v[68:69], 0, v[208:209]
	global_store_dwordx4 v[68:69], v[64:67], off
	v_add_u32_e32 v68, 0x80, v143
	s_nop 0
	v_mul_f32_e32 v65, 0xbfb8aa3b, v52
	v_exp_f32_e32 v65, v65
	v_mul_f32_e32 v64, 0xbfb8aa3b, v60
	v_exp_f32_e32 v64, v64
	v_add_f32_e32 v65, 1.0, v65
	v_rcp_f32_e32 v66, v65
	v_mul_f32_e32 v65, 0xbfb8aa3b, v61
	v_exp_f32_e32 v65, v65
	v_add_f32_e32 v64, 1.0, v64
	v_rcp_f32_e32 v64, v64
	v_add_f32_e32 v65, 1.0, v65
	v_rcp_f32_e32 v65, v65
	s_nop 0
	v_pk_mul_f32 v[60:61], v[60:61], v[64:65]
	s_nop 0
	v_pk_mul_f32 v[56:57], v[60:61], v[56:57]
	v_mul_f32_e32 v60, 0xbfb8aa3b, v53
	v_exp_f32_e32 v60, v60
	s_nop 0
	v_add_f32_e32 v60, 1.0, v60
	v_rcp_f32_e32 v67, v60
	s_nop 0
	v_pk_mul_f32 v[52:53], v[52:53], v[66:67]
	s_nop 0
	v_pk_mul_f32 v[52:53], v[52:53], v[48:49]
	v_mul_f32_e32 v49, 0xbfb8aa3b, v54
	v_exp_f32_e32 v49, v49
	v_mul_f32_e32 v48, 0xbfb8aa3b, v62
	v_exp_f32_e32 v48, v48
	v_add_f32_e32 v49, 1.0, v49
	v_rcp_f32_e32 v60, v49
	v_mul_f32_e32 v49, 0xbfb8aa3b, v63
	v_exp_f32_e32 v49, v49
	v_add_f32_e32 v48, 1.0, v48
	v_rcp_f32_e32 v48, v48
	v_add_f32_e32 v49, 1.0, v49
	v_rcp_f32_e32 v49, v49
	s_nop 0
	v_pk_mul_f32 v[48:49], v[62:63], v[48:49]
	s_nop 0
	v_pk_mul_f32 v[58:59], v[48:49], v[58:59]
; __device__ __forceinline__ u32x4 pack8u(f32x4 a, f32x4 b) { u32x4 w = {cvt_pk_bf16(a[0], a[1]), cvt_pk_bf16(a[2], a[3]), cvt_pk_bf16(b[0], b[1]), cvt_pk_bf16(b[2], b[3])}; return w; }
; __device__ __forceinline__ float siluf_(float x) { return x * __builtin_amdgcn_rcpf(1.0f + __expf(-x)); }
; #define PG8_WAIT_V(n) asm volatile("s_waitcnt vmcnt(" #n ")" ::: "memory")
; #define PG8_BAR __builtin_amdgcn_s_barrier()
; template <class Epi>
; __device__ __forceinline__ void gemm_phase(LAS unsigned char* lds, const Gemm g, const Epi& E) {
;     ...
;         E(acc, cur, wr, wc, fr, fq);
;         if (!has_next) break;
; #pragma unroll
;         for (int a = 0; a < 2; ++a)
; #pragma unroll
;             for (int b = 0; b < 2; ++b)
; #pragma unroll
;                 for (int m = 0; m < 4; ++m)
; #pragma unroll
;                     for (int n = 0; n < 2; ++n) acc[a][b][m][n] = (f32x4){0.f, 0.f, 0.f, 0.f};
;         cur = nxt; cA = nA; cB = nB; ++ui;
;     }
;     PG8_WAIT_V(0);
;     if (wr == 0) PG8_BAR;
;     __device__ __forceinline__ void operator()(const AccT& acc, const Unit& u, int wr, int wc, int fr, int fq) const {
; #pragma unroll
;         for (int ai = 0; ai < 2; ++ai)
; #pragma unroll
;             for (int m = 0; m < 4; ++m) {
;                 const int row = u.pm * 256 + ai * 128 + wr * 64 + m * 16 + fr;
;                 f32x4 o0, o1;
; #pragma unroll
;                 for (int j = 0; j < 4; ++j) { o0[j] = siluf_(acc[ai][0][m][0][j]) * acc[ai][1][m][0][j]; o1[j] = siluf_(acc[ai][0][m][1][j]) * acc[ai][1][m][1][j]; }
;                 *(u32x4*)(ACT + (size_t)row * DFF + u.pn * 128 + wc * 32 + fq * 8) = pack8u(o0, o1);
	v_mul_f32_e32 v48, 0xbfb8aa3b, v55
	v_exp_f32_e32 v48, v48
	s_nop 0
	v_add_f32_e32 v48, 1.0, v48
	v_rcp_f32_e32 v61, v48
	s_nop 0
	v_pk_mul_f32 v[48:49], v[54:55], v[60:61]
	s_nop 0
	v_pk_mul_f32 v[54:55], v[48:49], v[50:51]
	v_cvt_pk_bf16_f32 v50, v52, v53
	v_mad_i64_i32 v[52:53], s[26:27], v68, s34, v[112:113]
	v_lshl_add_u64 v[52:53], v[52:53], 0, s[88:89]
	v_lshl_add_u64 v[52:53], v[52:53], 0, s[28:29]
	v_cvt_pk_bf16_f32 v48, v56, v57
	v_cvt_pk_bf16_f32 v49, v58, v59
	v_cvt_pk_bf16_f32 v51, v54, v55
	v_lshl_add_u64 v[52:53], v[52:53], 0, v[208:209]
	global_store_dwordx4 v[52:53], v[48:51], off
	s_nop 1
	v_mul_f32_e32 v49, 0xbfb8aa3b, v36
	v_exp_f32_e32 v49, v49
	v_mul_f32_e32 v48, 0xbfb8aa3b, v44
	v_exp_f32_e32 v48, v48
	v_add_f32_e32 v49, 1.0, v49
	v_rcp_f32_e32 v50, v49
	v_mul_f32_e32 v49, 0xbfb8aa3b, v45
	v_exp_f32_e32 v49, v49
	v_add_f32_e32 v48, 1.0, v48
	v_rcp_f32_e32 v48, v48
	v_add_f32_e32 v49, 1.0, v49
	v_rcp_f32_e32 v49, v49
	s_nop 0
	v_pk_mul_f32 v[44:45], v[44:45], v[48:49]
	s_nop 0
	v_pk_mul_f32 v[40:41], v[44:45], v[40:41]
	v_mul_f32_e32 v44, 0xbfb8aa3b, v37
	v_exp_f32_e32 v44, v44
	s_nop 0
	v_add_f32_e32 v44, 1.0, v44
	v_rcp_f32_e32 v51, v44
	s_nop 0
	v_pk_mul_f32 v[36:37], v[36:37], v[50:51]
	s_nop 0
	v_pk_mul_f32 v[36:37], v[36:37], v[32:33]
	v_mul_f32_e32 v33, 0xbfb8aa3b, v38
	v_exp_f32_e32 v33, v33
	v_mul_f32_e32 v32, 0xbfb8aa3b, v46
	v_exp_f32_e32 v32, v32
	v_add_f32_e32 v33, 1.0, v33
	v_rcp_f32_e32 v44, v33
	v_mul_f32_e32 v33, 0xbfb8aa3b, v47
	v_exp_f32_e32 v33, v33
	v_add_f32_e32 v32, 1.0, v32
	v_rcp_f32_e32 v32, v32
	v_add_f32_e32 v33, 1.0, v33
	v_rcp_f32_e32 v33, v33
	s_nop 0
	v_pk_mul_f32 v[32:33], v[46:47], v[32:33]
	s_nop 0
	v_pk_mul_f32 v[42:43], v[32:33], v[42:43]
	v_mul_f32_e32 v32, 0xbfb8aa3b, v39
	v_exp_f32_e32 v32, v32
	s_nop 0
	v_add_f32_e32 v32, 1.0, v32
	v_rcp_f32_e32 v45, v32
	s_nop 0
	v_pk_mul_f32 v[32:33], v[38:39], v[44:45]
	v_add_u32_e32 v44, 0x90, v143
	v_pk_mul_f32 v[38:39], v[32:33], v[34:35]
	v_cvt_pk_bf16_f32 v34, v36, v37
	v_mad_i64_i32 v[36:37], s[26:27], v44, s34, v[112:113]
	v_lshl_add_u64 v[36:37], v[36:37], 0, s[88:89]
	v_lshl_add_u64 v[36:37], v[36:37], 0, s[28:29]
	v_cvt_pk_bf16_f32 v32, v40, v41
	v_cvt_pk_bf16_f32 v33, v42, v43
	v_cvt_pk_bf16_f32 v35, v38, v39
	v_lshl_add_u64 v[36:37], v[36:37], 0, v[208:209]
	global_store_dwordx4 v[36:37], v[32:35], off
	s_nop 1
	v_mul_f32_e32 v33, 0xbfb8aa3b, v20
	v_exp_f32_e32 v33, v33
	v_mul_f32_e32 v32, 0xbfb8aa3b, v28
	v_exp_f32_e32 v32, v32
	v_add_f32_e32 v33, 1.0, v33
	v_rcp_f32_e32 v34, v33
	v_mul_f32_e32 v33, 0xbfb8aa3b, v29
	v_exp_f32_e32 v33, v33
	v_add_f32_e32 v32, 1.0, v32
	v_rcp_f32_e32 v32, v32
	v_add_f32_e32 v33, 1.0, v33
	v_rcp_f32_e32 v33, v33
	s_nop 0
	v_pk_mul_f32 v[28:29], v[28:29], v[32:33]
	s_nop 0
	v_pk_mul_f32 v[24:25], v[28:29], v[24:25]
	v_mul_f32_e32 v28, 0xbfb8aa3b, v21
	v_exp_f32_e32 v28, v28
	s_nop 0
	v_add_f32_e32 v28, 1.0, v28
	v_rcp_f32_e32 v35, v28
	s_nop 0
	v_pk_mul_f32 v[20:21], v[20:21], v[34:35]
	s_nop 0
	v_pk_mul_f32 v[20:21], v[20:21], v[16:17]
	v_mul_f32_e32 v17, 0xbfb8aa3b, v22
	v_exp_f32_e32 v17, v17
	v_mul_f32_e32 v16, 0xbfb8aa3b, v30
	v_exp_f32_e32 v16, v16
	v_add_f32_e32 v17, 1.0, v17
	v_rcp_f32_e32 v28, v17
	v_mul_f32_e32 v17, 0xbfb8aa3b, v31
	v_exp_f32_e32 v17, v17
	v_add_f32_e32 v16, 1.0, v16
	v_rcp_f32_e32 v16, v16
	v_add_f32_e32 v17, 1.0, v17
	v_rcp_f32_e32 v17, v17
	s_nop 0
	v_pk_mul_f32 v[16:17], v[30:31], v[16:17]
	s_nop 0
	v_pk_mul_f32 v[26:27], v[16:17], v[26:27]
	v_mul_f32_e32 v16, 0xbfb8aa3b, v23
	v_exp_f32_e32 v16, v16
	s_nop 0
	v_add_f32_e32 v16, 1.0, v16
	v_rcp_f32_e32 v29, v16
	s_nop 0
	v_pk_mul_f32 v[16:17], v[22:23], v[28:29]
	v_add_u32_e32 v28, 0xa0, v143
	v_pk_mul_f32 v[22:23], v[16:17], v[18:19]
	v_cvt_pk_bf16_f32 v18, v20, v21
	v_mad_i64_i32 v[20:21], s[26:27], v28, s34, v[112:113]
	v_lshl_add_u64 v[20:21], v[20:21], 0, s[88:89]
	v_lshl_add_u64 v[20:21], v[20:21], 0, s[28:29]
	v_cvt_pk_bf16_f32 v16, v24, v25
	v_cvt_pk_bf16_f32 v17, v26, v27
	v_cvt_pk_bf16_f32 v19, v22, v23
	v_lshl_add_u64 v[20:21], v[20:21], 0, v[208:209]
	global_store_dwordx4 v[20:21], v[16:19], off
	s_nop 1
	v_mul_f32_e32 v17, 0xbfb8aa3b, v4
	v_exp_f32_e32 v17, v17
	v_mul_f32_e32 v16, 0xbfb8aa3b, v12
	v_exp_f32_e32 v16, v16
	v_add_f32_e32 v17, 1.0, v17
	v_rcp_f32_e32 v18, v17
	v_mul_f32_e32 v17, 0xbfb8aa3b, v13
	v_exp_f32_e32 v17, v17
	v_add_f32_e32 v16, 1.0, v16
	v_rcp_f32_e32 v16, v16
	v_add_f32_e32 v17, 1.0, v17
	v_rcp_f32_e32 v17, v17
	s_nop 0
	v_pk_mul_f32 v[12:13], v[12:13], v[16:17]
	s_nop 0
	v_pk_mul_f32 v[8:9], v[12:13], v[8:9]
	v_mul_f32_e32 v12, 0xbfb8aa3b, v5
	v_exp_f32_e32 v12, v12
	s_nop 0
	v_add_f32_e32 v12, 1.0, v12
	v_rcp_f32_e32 v19, v12
	s_nop 0
	v_pk_mul_f32 v[4:5], v[4:5], v[18:19]
	s_nop 0
	v_pk_mul_f32 v[4:5], v[4:5], v[0:1]
	v_mul_f32_e32 v1, 0xbfb8aa3b, v6
	v_exp_f32_e32 v1, v1
	v_mul_f32_e32 v0, 0xbfb8aa3b, v14
	v_exp_f32_e32 v0, v0
	v_add_f32_e32 v1, 1.0, v1
	v_rcp_f32_e32 v12, v1
	v_mul_f32_e32 v1, 0xbfb8aa3b, v15
	v_exp_f32_e32 v1, v1
	v_add_f32_e32 v0, 1.0, v0
	v_rcp_f32_e32 v0, v0
	v_add_f32_e32 v1, 1.0, v1
	v_rcp_f32_e32 v1, v1
	s_nop 0
	v_pk_mul_f32 v[0:1], v[14:15], v[0:1]
	s_nop 0
	v_pk_mul_f32 v[10:11], v[0:1], v[10:11]
	v_mul_f32_e32 v0, 0xbfb8aa3b, v7
	v_exp_f32_e32 v0, v0
	s_nop 0
	v_add_f32_e32 v0, 1.0, v0
	v_rcp_f32_e32 v13, v0
	s_nop 0
	v_pk_mul_f32 v[0:1], v[6:7], v[12:13]
	v_add_u32_e32 v12, 0xb0, v143
	v_pk_mul_f32 v[6:7], v[0:1], v[2:3]
	v_cvt_pk_bf16_f32 v2, v4, v5
	v_mad_i64_i32 v[4:5], s[26:27], v12, s34, v[112:113]
	v_lshl_add_u64 v[4:5], v[4:5], 0, s[88:89]
	v_lshl_add_u64 v[4:5], v[4:5], 0, s[28:29]
	v_cvt_pk_bf16_f32 v0, v8, v9
	v_cvt_pk_bf16_f32 v1, v10, v11
	v_cvt_pk_bf16_f32 v3, v6, v7
	v_lshl_add_u64 v[4:5], v[4:5], 0, v[208:209]
	s_mov_b32 s88, s44
	s_mov_b64 s[28:29], s[64:65]
	s_mov_b64 s[26:27], s[48:49]
	global_store_dwordx4 v[4:5], v[0:3], off
	s_cbranch_vccz .LBB0_27
	s_waitcnt vmcnt(0)
	s_cmpk_gt_u32 s30, 0xff
	s_mov_b32 s89, 0xc000
	s_mov_b64 s[34:35], 0
	s_cbranch_scc1 .LBB0_34
	s_barrier

; #define PG8_STAGE(bufoff, gbase, voff) do { _Pragma("unroll") for (int _i = 0; _i < 2; ++_i) \
;         __builtin_amdgcn_global_load_lds((const unsigned*)((const char*)(gbase) + (voff)[_i]), (LAS unsigned*)(lds + (bufoff) + ldsw + _i * 8192), 16, 0, 0); } while (0)
; #define PG8_LDA(dst, b, h) do { _Pragma("unroll") for (int m = 0; m < 4; ++m) _Pragma("unroll") for (int k = 0; k < 2; ++k) dst[m][k] = *(const LAS bf16x8*)(lds + PG8_SA(b, h) + aoff + m * 2048 + k * 1024); } while (0)
; #define PG8_LDB(dst, b, h) do { _Pragma("unroll") for (int n = 0; n < 2; ++n) _Pragma("unroll") for (int k = 0; k < 2; ++k) dst[n][k] = *(const LAS bf16x8*)(lds + PG8_SB(b, h) + boff + n * 2048 + k * 1024); } while (0)
; #define PG8_MMA(ai, bj, At, Bt) do { __builtin_amdgcn_s_setprio(1); _Pragma("unroll") for (int m = 0; m < 4; ++m) _Pragma("unroll") for (int n = 0; n < 2; ++n) _Pragma("unroll") for (int k = 0; k < 2; ++k) \
;         acc[ai][bj][m][n] = __builtin_amdgcn_mfma_f32_16x16x32_bf16(Bt[n][k], At[m][k], acc[ai][bj][m][n], 0, 0, 0); __builtin_amdgcn_s_setprio(0); } while (0)
; #define PG8_WAIT_V(n) asm volatile("s_waitcnt vmcnt(" #n ")" ::: "memory")
; #define PG8_WAIT_L(n) asm volatile("s_waitcnt lgkmcnt(" #n ")" ::: "memory")
; #define PG8_BAR __builtin_amdgcn_s_barrier()
; #define PG8_SCHED __builtin_amdgcn_sched_barrier(0)
; template <class Epi>
; __device__ __forceinline__ void gemm_phase(LAS unsigned char* lds, const Gemm g, const Epi& E) {
;     ...
;             PG8_LDB(B0, 0, 0); PG8_SCHED; PG8_LDA(At, 0, 0); PG8_STAGE(PG8_SA(1, 1), a1 + hstep, voffA);
;             PG8_WAIT_L(8); PG8_BAR; PG8_WAIT_L(0); PG8_MMA(0, 0, At, B0); PG8_BAR; PG8_SCHED;
;             PG8_LDB(B1, 0, 1); PG8_STAGE(PG8_SB(0, 0), b2, voffB);
;             PG8_BAR; PG8_WAIT_L(0); PG8_MMA(0, 1, At, B1); PG8_BAR;
;             PG8_LDA(At, 0, 1); PG8_STAGE(PG8_SA(0, 0), a2, voffA);
;             PG8_BAR; PG8_WAIT_L(0); PG8_MMA(1, 0, At, B0); PG8_BAR; PG8_SCHED;
;             PG8_STAGE(PG8_SB(0, 1), b2 + hstep, voffB);
;             PG8_WAIT_V(6); PG8_BAR; PG8_MMA(1, 1, At, B1); PG8_BAR;
.LBB0_120:
	s_add_u32 s28, s26, 0xfff80080
	s_addc_u32 s29, s27, -1
	s_add_i32 s34, 0, 0x10000
	v_add_u32_e32 v92, s34, v174
	ds_read_b128 v[72:75], v92
	ds_read_b128 v[76:79], v92 offset:1024
	ds_read_b128 v[84:87], v92 offset:2048
	ds_read_b128 v[92:95], v92 offset:3072
	s_cmp_eq_u32 vcc_lo, 28
	s_cselect_b32 s37, s38, s29
	s_cselect_b32 s36, s39, s28
	s_cselect_b32 s29, s43, s97
	s_cselect_b32 s28, s49, s65
	s_add_i32 m0, s68, 0xc000
	ds_read_b128 v[144:147], v175
	ds_read_b128 v[148:151], v175 offset:1024
	ds_read_b128 v[164:167], v175 offset:2048
	ds_read_b128 v[168:171], v175 offset:3072
	ds_read_b128 v[178:181], v175 offset:4096
	ds_read_b128 v[182:185], v175 offset:5120
	ds_read_b128 v[186:189], v175 offset:6144
	ds_read_b128 v[190:193], v175 offset:7168
	global_load_lds_dwordx4 v160, s[26:27]
	s_add_i32 m0, s68, 0xe000
	s_nop 0
	global_load_lds_dwordx4 v162, s[26:27]
	s_waitcnt lgkmcnt(8)
	s_barrier
	s_waitcnt lgkmcnt(0)
	v_mfma_f32_16x16x32_bf16 v[140:143], v[72:75], v[144:147], v[140:143]
	v_mfma_f32_16x16x32_bf16 v[136:139], v[84:87], v[144:147], v[136:139]
	v_mfma_f32_16x16x32_bf16 v[124:127], v[72:75], v[164:167], v[124:127]
	v_mfma_f32_16x16x32_bf16 v[120:123], v[84:87], v[164:167], v[120:123]
	v_mfma_f32_16x16x32_bf16 v[108:111], v[72:75], v[178:181], v[108:111]
	v_mfma_f32_16x16x32_bf16 v[104:107], v[84:87], v[178:181], v[104:107]
	v_mfma_f32_16x16x32_bf16 v[88:91], v[72:75], v[186:189], v[88:91]
	v_mfma_f32_16x16x32_bf16 v[80:83], v[84:87], v[186:189], v[80:83]
	v_mfma_f32_16x16x32_bf16 v[140:143], v[76:79], v[148:151], v[140:143]
	v_mfma_f32_16x16x32_bf16 v[136:139], v[92:95], v[148:151], v[136:139]
	v_mfma_f32_16x16x32_bf16 v[124:127], v[76:79], v[168:171], v[124:127]
	v_mfma_f32_16x16x32_bf16 v[120:123], v[92:95], v[168:171], v[120:123]
	v_mfma_f32_16x16x32_bf16 v[108:111], v[76:79], v[182:185], v[108:111]
	v_mfma_f32_16x16x32_bf16 v[104:107], v[92:95], v[182:185], v[104:107]
	v_mfma_f32_16x16x32_bf16 v[88:91], v[76:79], v[190:193], v[88:91]
	v_mfma_f32_16x16x32_bf16 v[80:83], v[92:95], v[190:193], v[80:83]
	s_barrier
	s_add_i32 s46, 0, 0x14000
	v_add_u32_e32 v172, s46, v174
	s_add_i32 s34, s34, s31
	ds_read_b128 v[194:197], v172
	ds_read_b128 v[198:201], v172 offset:1024
	ds_read_b128 v[202:205], v172 offset:2048
	ds_read_b128 v[228:231], v172 offset:3072
	s_mov_b32 m0, s34
	s_nop 0
	global_load_lds_dwordx4 v208, s[28:29]
	s_add_i32 m0, s34, 0x2000
	s_nop 0
	global_load_lds_dwordx4 v156, s[28:29]
	s_barrier
	s_waitcnt lgkmcnt(0)
	v_mfma_f32_16x16x32_bf16 v[132:135], v[194:197], v[144:147], v[132:135]
	v_mfma_f32_16x16x32_bf16 v[128:131], v[202:205], v[144:147], v[128:131]
	v_mfma_f32_16x16x32_bf16 v[116:119], v[194:197], v[164:167], v[116:119]
	v_mfma_f32_16x16x32_bf16 v[112:115], v[202:205], v[164:167], v[112:115]
	v_mfma_f32_16x16x32_bf16 v[100:103], v[194:197], v[178:181], v[100:103]
	v_mfma_f32_16x16x32_bf16 v[96:99], v[202:205], v[178:181], v[96:99]
	v_mfma_f32_16x16x32_bf16 v[68:71], v[194:197], v[186:189], v[68:71]
	v_mfma_f32_16x16x32_bf16 v[64:67], v[202:205], v[186:189], v[64:67]
	v_mfma_f32_16x16x32_bf16 v[132:135], v[198:201], v[148:151], v[132:135]
	v_mfma_f32_16x16x32_bf16 v[128:131], v[228:231], v[148:151], v[128:131]
	v_mfma_f32_16x16x32_bf16 v[116:119], v[198:201], v[168:171], v[116:119]
	v_mfma_f32_16x16x32_bf16 v[112:115], v[228:231], v[168:171], v[112:115]
	v_mfma_f32_16x16x32_bf16 v[100:103], v[198:201], v[182:185], v[100:103]
	v_mfma_f32_16x16x32_bf16 v[96:99], v[228:231], v[182:185], v[96:99]
	v_mfma_f32_16x16x32_bf16 v[68:71], v[198:201], v[190:193], v[68:71]
	v_mfma_f32_16x16x32_bf16 v[64:67], v[228:231], v[190:193], v[64:67]
	s_barrier
	s_mov_b32 m0, s68
	ds_read_b128 v[144:147], v175 offset:16384
	ds_read_b128 v[148:151], v175 offset:17408
	ds_read_b128 v[164:167], v175 offset:18432
	ds_read_b128 v[168:171], v175 offset:19456
	ds_read_b128 v[178:181], v175 offset:20480
	ds_read_b128 v[182:185], v175 offset:21504
	ds_read_b128 v[186:189], v175 offset:22528
	ds_read_b128 v[190:193], v175 offset:23552
	global_load_lds_dwordx4 v152, s[36:37]
	s_mov_b32 m0, s69
	s_nop 0
	global_load_lds_dwordx4 v154, s[36:37]
	s_barrier
	s_waitcnt lgkmcnt(0)
	v_mfma_f32_16x16x32_bf16 v[60:63], v[72:75], v[144:147], v[60:63]
	v_mfma_f32_16x16x32_bf16 v[56:59], v[84:87], v[144:147], v[56:59]
	v_mfma_f32_16x16x32_bf16 v[44:47], v[72:75], v[164:167], v[44:47]
	v_mfma_f32_16x16x32_bf16 v[40:43], v[84:87], v[164:167], v[40:43]
	v_mfma_f32_16x16x32_bf16 v[28:31], v[72:75], v[178:181], v[28:31]
	v_mfma_f32_16x16x32_bf16 v[24:27], v[84:87], v[178:181], v[24:27]
	v_mfma_f32_16x16x32_bf16 v[12:15], v[72:75], v[186:189], v[12:15]
	v_mfma_f32_16x16x32_bf16 v[8:11], v[84:87], v[186:189], v[8:11]
	v_mfma_f32_16x16x32_bf16 v[60:63], v[76:79], v[148:151], v[60:63]
	v_mfma_f32_16x16x32_bf16 v[56:59], v[92:95], v[148:151], v[56:59]
	v_mfma_f32_16x16x32_bf16 v[44:47], v[76:79], v[168:171], v[44:47]
	v_mfma_f32_16x16x32_bf16 v[40:43], v[92:95], v[168:171], v[40:43]
	v_mfma_f32_16x16x32_bf16 v[28:31], v[76:79], v[182:185], v[28:31]
	v_mfma_f32_16x16x32_bf16 v[24:27], v[92:95], v[182:185], v[24:27]
	v_mfma_f32_16x16x32_bf16 v[12:15], v[76:79], v[190:193], v[12:15]
	v_mfma_f32_16x16x32_bf16 v[8:11], v[92:95], v[190:193], v[8:11]
	s_barrier
	s_add_u32 s34, s28, 0x80000
	s_addc_u32 s35, s29, 0
	s_add_i32 s46, s46, s31
	s_mov_b32 m0, s46
	s_nop 0
	global_load_lds_dwordx4 v208, s[34:35]
	s_add_i32 m0, s46, 0x2000
	s_nop 0
	global_load_lds_dwordx4 v156, s[34:35]
	s_waitcnt vmcnt(6)
	s_barrier
; #define PG8_STAGE(bufoff, gbase, voff) do { _Pragma("unroll") for (int _i = 0; _i < 2; ++_i) \
;         __builtin_amdgcn_global_load_lds((const unsigned*)((const char*)(gbase) + (voff)[_i]), (LAS unsigned*)(lds + (bufoff) + ldsw + _i * 8192), 16, 0, 0); } while (0)
; #define PG8_LDA(dst, b, h) do { _Pragma("unroll") for (int m = 0; m < 4; ++m) _Pragma("unroll") for (int k = 0; k < 2; ++k) dst[m][k] = *(const LAS bf16x8*)(lds + PG8_SA(b, h) + aoff + m * 2048 + k * 1024); } while (0)
; #define PG8_LDB(dst, b, h) do { _Pragma("unroll") for (int n = 0; n < 2; ++n) _Pragma("unroll") for (int k = 0; k < 2; ++k) dst[n][k] = *(const LAS bf16x8*)(lds + PG8_SB(b, h) + boff + n * 2048 + k * 1024); } while (0)
; #define PG8_MMA(ai, bj, At, Bt) do { __builtin_amdgcn_s_setprio(1); _Pragma("unroll") for (int m = 0; m < 4; ++m) _Pragma("unroll") for (int n = 0; n < 2; ++n) _Pragma("unroll") for (int k = 0; k < 2; ++k) \
;         acc[ai][bj][m][n] = __builtin_amdgcn_mfma_f32_16x16x32_bf16(Bt[n][k], At[m][k], acc[ai][bj][m][n], 0, 0, 0); __builtin_amdgcn_s_setprio(0); } while (0)
; #define PG8_WAIT_V(n) asm volatile("s_waitcnt vmcnt(" #n ")" ::: "memory")
; #define PG8_WAIT_L(n) asm volatile("s_waitcnt lgkmcnt(" #n ")" ::: "memory")
; #define PG8_BAR __builtin_amdgcn_s_barrier()
; #define PG8_SCHED __builtin_amdgcn_sched_barrier(0)
; template <class Epi>
; __device__ __forceinline__ void gemm_phase(LAS unsigned char* lds, const Gemm g, const Epi& E) {
;     ...
;             PG8_WAIT_V(6); PG8_BAR; PG8_MMA(1, 1, At, B1); PG8_BAR;
;             PG8_LDB(B0, 1, 0); PG8_SCHED; PG8_LDA(At, 1, 0); PG8_STAGE(PG8_SA(0, 1), a2 + hstep, voffA);
;             PG8_WAIT_L(8); PG8_BAR; PG8_WAIT_L(0); PG8_MMA(0, 0, At, B0); PG8_BAR; PG8_SCHED;
;             PG8_LDB(B1, 1, 1); PG8_STAGE(PG8_SB(1, 0), b3, voffB);
;             PG8_BAR; PG8_WAIT_L(0); PG8_MMA(0, 1, At, B1); PG8_BAR;
;             PG8_LDA(At, 1, 1); PG8_STAGE(PG8_SA(1, 0), a3, voffA);
;             PG8_BAR; PG8_WAIT_L(0); PG8_MMA(1, 0, At, B0); PG8_BAR; PG8_SCHED;
	v_mfma_f32_16x16x32_bf16 v[52:55], v[194:197], v[144:147], v[52:55]
	v_mfma_f32_16x16x32_bf16 v[48:51], v[202:205], v[144:147], v[48:51]
	v_mfma_f32_16x16x32_bf16 v[36:39], v[194:197], v[164:167], v[36:39]
	v_mfma_f32_16x16x32_bf16 v[32:35], v[202:205], v[164:167], v[32:35]
	v_mfma_f32_16x16x32_bf16 v[20:23], v[194:197], v[178:181], v[20:23]
	v_mfma_f32_16x16x32_bf16 v[16:19], v[202:205], v[178:181], v[16:19]
	v_mfma_f32_16x16x32_bf16 v[4:7], v[194:197], v[186:189], v[4:7]
	v_mfma_f32_16x16x32_bf16 v[0:3], v[202:205], v[186:189], v[0:3]
	v_mfma_f32_16x16x32_bf16 v[52:55], v[198:201], v[148:151], v[52:55]
	v_mfma_f32_16x16x32_bf16 v[48:51], v[228:231], v[148:151], v[48:51]
	v_mfma_f32_16x16x32_bf16 v[36:39], v[198:201], v[168:171], v[36:39]
	v_mfma_f32_16x16x32_bf16 v[32:35], v[228:231], v[168:171], v[32:35]
	v_mfma_f32_16x16x32_bf16 v[20:23], v[198:201], v[182:185], v[20:23]
	v_mfma_f32_16x16x32_bf16 v[16:19], v[228:231], v[182:185], v[16:19]
	v_mfma_f32_16x16x32_bf16 v[4:7], v[198:201], v[190:193], v[4:7]
	v_mfma_f32_16x16x32_bf16 v[0:3], v[228:231], v[190:193], v[0:3]
	s_barrier
	s_add_i32 s46, 0, 0x18000
	v_add_u32_e32 v92, s46, v174
	ds_read_b128 v[72:75], v92
	ds_read_b128 v[76:79], v92 offset:1024
	ds_read_b128 v[84:87], v92 offset:2048
	ds_read_b128 v[92:95], v92 offset:3072
	s_add_u32 s34, s36, 0x80000
	s_addc_u32 s35, s37, 0
	s_mov_b32 m0, s70
	ds_read_b128 v[144:147], v175 offset:32768
	ds_read_b128 v[148:151], v175 offset:33792
	ds_read_b128 v[164:167], v175 offset:34816
	ds_read_b128 v[168:171], v175 offset:35840
	ds_read_b128 v[178:181], v175 offset:36864
	ds_read_b128 v[182:185], v175 offset:37888
	ds_read_b128 v[186:189], v175 offset:38912
	ds_read_b128 v[190:193], v175 offset:39936
	global_load_lds_dwordx4 v152, s[34:35]
	s_mov_b32 m0, s71
	s_nop 0
	global_load_lds_dwordx4 v154, s[34:35]
	s_waitcnt lgkmcnt(8)
	s_barrier
	s_waitcnt lgkmcnt(0)
	v_mfma_f32_16x16x32_bf16 v[140:143], v[72:75], v[144:147], v[140:143]
	v_mfma_f32_16x16x32_bf16 v[136:139], v[84:87], v[144:147], v[136:139]
	v_mfma_f32_16x16x32_bf16 v[124:127], v[72:75], v[164:167], v[124:127]
	v_mfma_f32_16x16x32_bf16 v[120:123], v[84:87], v[164:167], v[120:123]
	v_mfma_f32_16x16x32_bf16 v[108:111], v[72:75], v[178:181], v[108:111]
	v_mfma_f32_16x16x32_bf16 v[104:107], v[84:87], v[178:181], v[104:107]
	v_mfma_f32_16x16x32_bf16 v[88:91], v[72:75], v[186:189], v[88:91]
	v_mfma_f32_16x16x32_bf16 v[80:83], v[84:87], v[186:189], v[80:83]
	v_mfma_f32_16x16x32_bf16 v[140:143], v[76:79], v[148:151], v[140:143]
	v_mfma_f32_16x16x32_bf16 v[136:139], v[92:95], v[148:151], v[136:139]
	v_mfma_f32_16x16x32_bf16 v[124:127], v[76:79], v[168:171], v[124:127]
	v_mfma_f32_16x16x32_bf16 v[120:123], v[92:95], v[168:171], v[120:123]
	v_mfma_f32_16x16x32_bf16 v[108:111], v[76:79], v[182:185], v[108:111]
	v_mfma_f32_16x16x32_bf16 v[104:107], v[92:95], v[182:185], v[104:107]
	v_mfma_f32_16x16x32_bf16 v[88:91], v[76:79], v[190:193], v[88:91]
	v_mfma_f32_16x16x32_bf16 v[80:83], v[92:95], v[190:193], v[80:83]
	s_barrier
	s_add_i32 s34, 0, 0x1c000
	s_add_i32 s35, s46, s31
	v_add_u32_e32 v177, s34, v174
	s_mov_b32 m0, s35
	ds_read_b128 v[194:197], v177
	ds_read_b128 v[198:201], v177 offset:1024
	ds_read_b128 v[202:205], v177 offset:2048
	ds_read_b128 v[228:231], v177 offset:3072
	s_add_u32 s98, s28, 0x80
	s_addc_u32 s99, s29, 0
	global_load_lds_dwordx4 v208, s[98:99]
	s_add_i32 m0, s35, 0x2000
	s_add_u32 s100, s28, 0x80
	s_addc_u32 s101, s29, 0
	global_load_lds_dwordx4 v156, s[100:101]
	s_barrier
	s_waitcnt lgkmcnt(0)
	v_mfma_f32_16x16x32_bf16 v[132:135], v[194:197], v[144:147], v[132:135]
	v_mfma_f32_16x16x32_bf16 v[128:131], v[202:205], v[144:147], v[128:131]
	v_mfma_f32_16x16x32_bf16 v[116:119], v[194:197], v[164:167], v[116:119]
	v_mfma_f32_16x16x32_bf16 v[112:115], v[202:205], v[164:167], v[112:115]
	v_mfma_f32_16x16x32_bf16 v[100:103], v[194:197], v[178:181], v[100:103]
	v_mfma_f32_16x16x32_bf16 v[96:99], v[202:205], v[178:181], v[96:99]
	v_mfma_f32_16x16x32_bf16 v[68:71], v[194:197], v[186:189], v[68:71]
	v_mfma_f32_16x16x32_bf16 v[64:67], v[202:205], v[186:189], v[64:67]
	v_mfma_f32_16x16x32_bf16 v[132:135], v[198:201], v[148:151], v[132:135]
	v_mfma_f32_16x16x32_bf16 v[128:131], v[228:231], v[148:151], v[128:131]
	v_mfma_f32_16x16x32_bf16 v[116:119], v[198:201], v[168:171], v[116:119]
	v_mfma_f32_16x16x32_bf16 v[112:115], v[228:231], v[168:171], v[112:115]
	v_mfma_f32_16x16x32_bf16 v[100:103], v[198:201], v[182:185], v[100:103]
	v_mfma_f32_16x16x32_bf16 v[96:99], v[228:231], v[182:185], v[96:99]
	v_mfma_f32_16x16x32_bf16 v[68:71], v[198:201], v[190:193], v[68:71]
	v_mfma_f32_16x16x32_bf16 v[64:67], v[228:231], v[190:193], v[64:67]
	s_barrier
	s_mov_b32 m0, s78
	ds_read_b128 v[144:147], v175 offset:49152
	ds_read_b128 v[148:151], v175 offset:50176
	ds_read_b128 v[164:167], v175 offset:51200
	ds_read_b128 v[168:171], v175 offset:52224
	ds_read_b128 v[178:181], v175 offset:53248
	ds_read_b128 v[182:185], v175 offset:54272
	ds_read_b128 v[186:189], v175 offset:55296
	ds_read_b128 v[190:193], v175 offset:56320
	s_add_u32 s98, s36, 0x80
	s_addc_u32 s99, s37, 0
	global_load_lds_dwordx4 v152, s[98:99]
	s_mov_b32 m0, s79
	s_add_u32 s100, s36, 0x80
	s_addc_u32 s101, s37, 0
	global_load_lds_dwordx4 v154, s[100:101]
	s_barrier
; __device__ __forceinline__ float bflo(unsigned w) { return __uint_as_float(w << 16); }
; __device__ __forceinline__ float bfhi(unsigned w) { return __uint_as_float(w & 0xffff0000u); }
; __device__ __forceinline__ u32x4 pack8u(f32x4 a, f32x4 b) { u32x4 w = {cvt_pk_bf16(a[0], a[1]), cvt_pk_bf16(a[2], a[3]), cvt_pk_bf16(b[0], b[1]), cvt_pk_bf16(b[2], b[3])}; return w; }
; #define PG8_STAGE(bufoff, gbase, voff) do { _Pragma("unroll") for (int _i = 0; _i < 2; ++_i) \
;         __builtin_amdgcn_global_load_lds((const unsigned*)((const char*)(gbase) + (voff)[_i]), (LAS unsigned*)(lds + (bufoff) + ldsw + _i * 8192), 16, 0, 0); } while (0)
; #define PG8_WAIT_V(n) asm volatile("s_waitcnt vmcnt(" #n ")" ::: "memory")
; #define PG8_WAIT_L(n) asm volatile("s_waitcnt lgkmcnt(" #n ")" ::: "memory")
; template <class Epi>
; __device__ __forceinline__ void gemm_phase(LAS unsigned char* lds, const Gemm g, const Epi& E) {
;     ...
;             PG8_BAR; PG8_WAIT_L(0); PG8_MMA(1, 0, At, B0); PG8_BAR; PG8_SCHED;
;             PG8_STAGE(PG8_SB(1, 1), b3 + hstep, voffB);
;             PG8_WAIT_V(6); PG8_BAR; PG8_MMA(1, 1, At, B1); PG8_BAR;
;         }
;     __device__ __forceinline__ void operator()(const AccT& acc, const Unit& u, int wr, int wc, int fr, int fq) const {
;         const int b = (u.pm * 256) / SEQ;
;         f32x4 gt[2][2];
; #pragma unroll
;         for (int bj = 0; bj < 2; ++bj)
; #pragma unroll
;             for (int n = 0; n < 2; ++n) gt[bj][n] = *(const f32x4*)(GT + (size_t)b * 6 * D + u.pn * 256 + bj * 128 + wc * 32 + fq * 8 + 4 * n);
; #pragma unroll
;         for (int ai = 0; ai < 2; ++ai)
; #pragma unroll
;             for (int m = 0; m < 4; ++m) {
;                 const int row = u.pm * 256 + ai * 128 + wr * 64 + m * 16 + fr;
; #pragma unroll
;                 for (int bj = 0; bj < 2; ++bj) {
;                     const size_t off = (size_t)row * D + u.pn * 256 + bj * 128 + wc * 32 + fq * 8;
;                     f32x4 x0, x1;
;                     if (XINF) { x0 = *(const f32x4*)(XINF + off); x1 = *(const f32x4*)(XINF + off + 4); }
;                     else { const u32x4 w = *(const u32x4*)(XIN16 + off); x0 = (f32x4){bflo(w[0]), bfhi(w[0]), bflo(w[1]), bfhi(w[1])}; x1 = (f32x4){bflo(w[2]), bfhi(w[2]), bflo(w[3]), bfhi(w[3])}; }
;                     *(u32x4*)(XOUT + off) = pack8u(x0 + gt[bj][0] * acc[ai][bj][m][0], x1 + gt[bj][1] * acc[ai][bj][m][1]);
	s_waitcnt lgkmcnt(0)
	v_mfma_f32_16x16x32_bf16 v[60:63], v[72:75], v[144:147], v[60:63]
	v_mfma_f32_16x16x32_bf16 v[56:59], v[84:87], v[144:147], v[56:59]
	v_mfma_f32_16x16x32_bf16 v[44:47], v[72:75], v[164:167], v[44:47]
	v_mfma_f32_16x16x32_bf16 v[40:43], v[84:87], v[164:167], v[40:43]
	v_mfma_f32_16x16x32_bf16 v[28:31], v[72:75], v[178:181], v[28:31]
	v_mfma_f32_16x16x32_bf16 v[24:27], v[84:87], v[178:181], v[24:27]
	v_mfma_f32_16x16x32_bf16 v[12:15], v[72:75], v[186:189], v[12:15]
	v_mfma_f32_16x16x32_bf16 v[8:11], v[84:87], v[186:189], v[8:11]
	v_mfma_f32_16x16x32_bf16 v[60:63], v[76:79], v[148:151], v[60:63]
	v_mfma_f32_16x16x32_bf16 v[56:59], v[92:95], v[148:151], v[56:59]
	v_mfma_f32_16x16x32_bf16 v[44:47], v[76:79], v[168:171], v[44:47]
	v_mfma_f32_16x16x32_bf16 v[40:43], v[92:95], v[168:171], v[40:43]
	v_mfma_f32_16x16x32_bf16 v[28:31], v[76:79], v[182:185], v[28:31]
	v_mfma_f32_16x16x32_bf16 v[24:27], v[92:95], v[182:185], v[24:27]
	v_mfma_f32_16x16x32_bf16 v[12:15], v[76:79], v[190:193], v[12:15]
	v_mfma_f32_16x16x32_bf16 v[8:11], v[92:95], v[190:193], v[8:11]
	s_barrier
	s_add_u32 s28, s28, 0x80080
	s_addc_u32 s29, s29, 0
	s_add_i32 s34, s34, s31
	s_mov_b32 m0, s34
	s_nop 0
	global_load_lds_dwordx4 v208, s[28:29]
	s_add_i32 m0, s34, 0x2000
	s_nop 0
	global_load_lds_dwordx4 v156, s[28:29]
	s_waitcnt vmcnt(6)
	s_barrier
	v_mfma_f32_16x16x32_bf16 v[52:55], v[194:197], v[144:147], v[52:55]
	v_mfma_f32_16x16x32_bf16 v[48:51], v[202:205], v[144:147], v[48:51]
	v_mfma_f32_16x16x32_bf16 v[36:39], v[194:197], v[164:167], v[36:39]
	v_mfma_f32_16x16x32_bf16 v[32:35], v[202:205], v[164:167], v[32:35]
	v_mfma_f32_16x16x32_bf16 v[20:23], v[194:197], v[178:181], v[20:23]
	v_mfma_f32_16x16x32_bf16 v[16:19], v[202:205], v[178:181], v[16:19]
	v_mfma_f32_16x16x32_bf16 v[4:7], v[194:197], v[186:189], v[4:7]
	v_mfma_f32_16x16x32_bf16 v[0:3], v[202:205], v[186:189], v[0:3]
	v_mfma_f32_16x16x32_bf16 v[52:55], v[198:201], v[148:151], v[52:55]
	v_mfma_f32_16x16x32_bf16 v[48:51], v[228:231], v[148:151], v[48:51]
	v_mfma_f32_16x16x32_bf16 v[36:39], v[198:201], v[168:171], v[36:39]
	v_mfma_f32_16x16x32_bf16 v[32:35], v[228:231], v[168:171], v[32:35]
	v_mfma_f32_16x16x32_bf16 v[20:23], v[198:201], v[182:185], v[20:23]
	v_mfma_f32_16x16x32_bf16 v[16:19], v[228:231], v[182:185], v[16:19]
	v_mfma_f32_16x16x32_bf16 v[4:7], v[198:201], v[190:193], v[4:7]
	v_mfma_f32_16x16x32_bf16 v[0:3], v[228:231], v[190:193], v[0:3]
	s_barrier
	s_add_i32 vcc_lo, vcc_lo, 2
	s_add_u32 s26, s26, 0x100
	s_addc_u32 s27, s27, 0
	s_add_u32 s65, s65, 0x100
	s_addc_u32 s97, s97, 0
	s_cmp_gt_u32 vcc_lo, 29
	s_cbranch_scc0 .LBB0_120
	s_ashr_i32 s26, s42, 31
	s_lshr_b32 s26, s26, 29
	s_add_i32 s26, s42, s26
	s_ashr_i32 s26, s26, 3
	s_mul_i32 s26, s26, 6
	s_ashr_i32 s27, s26, 31
	s_lshl_b64 s[26:27], s[26:27], 13
	s_add_u32 s34, s74, s26
	s_addc_u32 s35, s76, s27
	s_lshl_b32 s26, s96, 8
	s_ashr_i32 s27, s26, 31
	s_lshl_b64 s[28:29], s[26:27], 2
	s_add_u32 s28, s34, s28
	s_addc_u32 s29, s35, s29
	s_add_u32 s28, s28, s83
	s_addc_u32 s29, s29, 0
	global_load_dwordx4 v[84:87], v176, s[28:29] offset:16
	global_load_dwordx4 v[92:95], v176, s[28:29]
	global_load_dwordx4 v[72:75], v176, s[28:29] offset:528
	global_load_dwordx4 v[76:79], v176, s[28:29] offset:512
	v_readlane_b32 s34, v255, 22
	v_readlane_b32 s35, v255, 23
	v_lshl_add_u32 v166, s42, 8, v159
	v_or_b32_e32 v167, s26, v158
	v_lshlrev_b32_e32 v164, 2, v167
	v_lshl_add_u32 v164, v166, 13, v164
	v_lshlrev_b32_e32 v165, 1, v167
	v_lshl_add_u32 v165, v166, 12, v165
	s_and_b64 vcc, exec, s[44:45]
	s_cbranch_vccnz .Lepr1_f32
	v_add_u32_e32 v166, 0x0, v165
	global_load_dwordx4 v[168:171], v166, s[34:35] offset:0
	v_add_u32_e32 v166, 0x0, v165
	global_load_dwordx4 v[178:181], v166, s[34:35] offset:256
	v_add_u32_e32 v166, 0x10000, v165
	global_load_dwordx4 v[182:185], v166, s[34:35] offset:0
	v_add_u32_e32 v166, 0x10000, v165
	global_load_dwordx4 v[186:189], v166, s[34:35] offset:256
	v_add_u32_e32 v166, 0x20000, v165
	global_load_dwordx4 v[190:193], v166, s[34:35] offset:0
	v_add_u32_e32 v166, 0x20000, v165
	global_load_dwordx4 v[194:197], v166, s[34:35] offset:256
	v_add_u32_e32 v166, 0x30000, v165
	global_load_dwordx4 v[198:201], v166, s[34:35] offset:0
	v_add_u32_e32 v166, 0x30000, v165
	global_load_dwordx4 v[202:205], v166, s[34:35] offset:256
	v_add_u32_e32 v166, 0x80000, v165
	global_load_dwordx4 v[228:231], v166, s[34:35] offset:0
	s_waitcnt vmcnt(8)
	v_lshlrev_b32_e32 v144, 16, v168
	v_and_b32_e32 v145, 0xffff0000, v168
	v_lshlrev_b32_e32 v146, 16, v169
	v_and_b32_e32 v147, 0xffff0000, v169
	v_lshlrev_b32_e32 v148, 16, v170
	v_and_b32_e32 v149, 0xffff0000, v170
	v_lshlrev_b32_e32 v150, 16, v171
	v_and_b32_e32 v151, 0xffff0000, v171
	v_pk_fma_f32 v[140:141], v[140:141], v[92:93], v[144:145]
	v_pk_fma_f32 v[142:143], v[142:143], v[94:95], v[146:147]
	v_pk_fma_f32 v[136:137], v[136:137], v[84:85], v[148:149]
	v_pk_fma_f32 v[138:139], v[138:139], v[86:87], v[150:151]
	v_cvt_pk_bf16_f32 v140, v140, v141
	v_cvt_pk_bf16_f32 v141, v142, v143
	v_cvt_pk_bf16_f32 v142, v136, v137
	v_cvt_pk_bf16_f32 v143, v138, v139
	v_add_u32_e32 v167, 0x0, v165
	global_store_dwordx4 v167, v[140:143], s[34:35] offset:0
	v_add_u32_e32 v166, 0x80000, v165
	global_load_dwordx4 v[168:171], v166, s[34:35] offset:256
	v_add_u32_e32 v166, 0x90000, v165
	global_load_dwordx4 v[136:139], v166, s[34:35] offset:0
	s_waitcnt vmcnt(10)
; __device__ __forceinline__ float bflo(unsigned w) { return __uint_as_float(w << 16); }
; __device__ __forceinline__ float bfhi(unsigned w) { return __uint_as_float(w & 0xffff0000u); }
; __device__ __forceinline__ u32x4 pack8u(f32x4 a, f32x4 b) { u32x4 w = {cvt_pk_bf16(a[0], a[1]), cvt_pk_bf16(a[2], a[3]), cvt_pk_bf16(b[0], b[1]), cvt_pk_bf16(b[2], b[3])}; return w; }
;     __device__ __forceinline__ void operator()(const AccT& acc, const Unit& u, int wr, int wc, int fr, int fq) const {
;     ...
;                 for (int bj = 0; bj < 2; ++bj) {
;                     const size_t off = (size_t)row * D + u.pn * 256 + bj * 128 + wc * 32 + fq * 8;
;                     f32x4 x0, x1;
;                     if (XINF) { x0 = *(const f32x4*)(XINF + off); x1 = *(const f32x4*)(XINF + off + 4); }
;                     else { const u32x4 w = *(const u32x4*)(XIN16 + off); x0 = (f32x4){bflo(w[0]), bfhi(w[0]), bflo(w[1]), bfhi(w[1])}; x1 = (f32x4){bflo(w[2]), bfhi(w[2]), bflo(w[3]), bfhi(w[3])}; }
;                     *(u32x4*)(XOUT + off) = pack8u(x0 + gt[bj][0] * acc[ai][bj][m][0], x1 + gt[bj][1] * acc[ai][bj][m][1]);
	v_lshlrev_b32_e32 v144, 16, v178
	v_and_b32_e32 v145, 0xffff0000, v178
	v_lshlrev_b32_e32 v146, 16, v179
	v_and_b32_e32 v147, 0xffff0000, v179
	v_lshlrev_b32_e32 v148, 16, v180
	v_and_b32_e32 v149, 0xffff0000, v180
	v_lshlrev_b32_e32 v150, 16, v181
	v_and_b32_e32 v151, 0xffff0000, v181
	v_pk_fma_f32 v[132:133], v[132:133], v[76:77], v[144:145]
	v_pk_fma_f32 v[134:135], v[134:135], v[78:79], v[146:147]
	v_pk_fma_f32 v[128:129], v[128:129], v[72:73], v[148:149]
	v_pk_fma_f32 v[130:131], v[130:131], v[74:75], v[150:151]
	v_cvt_pk_bf16_f32 v132, v132, v133
	v_cvt_pk_bf16_f32 v133, v134, v135
	v_cvt_pk_bf16_f32 v134, v128, v129
	v_cvt_pk_bf16_f32 v135, v130, v131
	v_add_u32_e32 v167, 0x0, v165
	global_store_dwordx4 v167, v[132:135], s[34:35] offset:256
	v_add_u32_e32 v166, 0x90000, v165
	global_load_dwordx4 v[178:181], v166, s[34:35] offset:256
	v_add_u32_e32 v166, 0xa0000, v165
	global_load_dwordx4 v[128:131], v166, s[34:35] offset:0
	s_waitcnt vmcnt(12)
	v_lshlrev_b32_e32 v144, 16, v182
	v_and_b32_e32 v145, 0xffff0000, v182
	v_lshlrev_b32_e32 v146, 16, v183
	v_and_b32_e32 v147, 0xffff0000, v183
	v_lshlrev_b32_e32 v148, 16, v184
	v_and_b32_e32 v149, 0xffff0000, v184
	v_lshlrev_b32_e32 v150, 16, v185
	v_and_b32_e32 v151, 0xffff0000, v185
	v_pk_fma_f32 v[124:125], v[124:125], v[92:93], v[144:145]
	v_pk_fma_f32 v[126:127], v[126:127], v[94:95], v[146:147]
	v_pk_fma_f32 v[120:121], v[120:121], v[84:85], v[148:149]
	v_pk_fma_f32 v[122:123], v[122:123], v[86:87], v[150:151]
	v_cvt_pk_bf16_f32 v124, v124, v125
	v_cvt_pk_bf16_f32 v125, v126, v127
	v_cvt_pk_bf16_f32 v126, v120, v121
	v_cvt_pk_bf16_f32 v127, v122, v123
	v_add_u32_e32 v167, 0x10000, v165
	global_store_dwordx4 v167, v[124:127], s[34:35] offset:0
	v_add_u32_e32 v166, 0xa0000, v165
	global_load_dwordx4 v[182:185], v166, s[34:35] offset:256
	v_add_u32_e32 v166, 0xb0000, v165
	global_load_dwordx4 v[120:123], v166, s[34:35] offset:0
	s_waitcnt vmcnt(14)
	v_lshlrev_b32_e32 v144, 16, v186
	v_and_b32_e32 v145, 0xffff0000, v186
	v_lshlrev_b32_e32 v146, 16, v187
	v_and_b32_e32 v147, 0xffff0000, v187
	v_lshlrev_b32_e32 v148, 16, v188
	v_and_b32_e32 v149, 0xffff0000, v188
	v_lshlrev_b32_e32 v150, 16, v189
	v_and_b32_e32 v151, 0xffff0000, v189
	v_pk_fma_f32 v[116:117], v[116:117], v[76:77], v[144:145]
	v_pk_fma_f32 v[118:119], v[118:119], v[78:79], v[146:147]
	v_pk_fma_f32 v[112:113], v[112:113], v[72:73], v[148:149]
	v_pk_fma_f32 v[114:115], v[114:115], v[74:75], v[150:151]
	v_cvt_pk_bf16_f32 v116, v116, v117
	v_cvt_pk_bf16_f32 v117, v118, v119
	v_cvt_pk_bf16_f32 v118, v112, v113
	v_cvt_pk_bf16_f32 v119, v114, v115
	v_add_u32_e32 v167, 0x10000, v165
	global_store_dwordx4 v167, v[116:119], s[34:35] offset:256
	v_add_u32_e32 v166, 0xb0000, v165
	global_load_dwordx4 v[186:189], v166, s[34:35] offset:256
	s_waitcnt vmcnt(15)
	v_lshlrev_b32_e32 v144, 16, v190
	v_and_b32_e32 v145, 0xffff0000, v190
	v_lshlrev_b32_e32 v146, 16, v191
	v_and_b32_e32 v147, 0xffff0000, v191
	v_lshlrev_b32_e32 v148, 16, v192
	v_and_b32_e32 v149, 0xffff0000, v192
	v_lshlrev_b32_e32 v150, 16, v193
	v_and_b32_e32 v151, 0xffff0000, v193
	v_pk_fma_f32 v[108:109], v[108:109], v[92:93], v[144:145]
	v_pk_fma_f32 v[110:111], v[110:111], v[94:95], v[146:147]
	v_pk_fma_f32 v[104:105], v[104:105], v[84:85], v[148:149]
	v_pk_fma_f32 v[106:107], v[106:107], v[86:87], v[150:151]
	v_cvt_pk_bf16_f32 v108, v108, v109
	v_cvt_pk_bf16_f32 v109, v110, v111
	v_cvt_pk_bf16_f32 v110, v104, v105
	v_cvt_pk_bf16_f32 v111, v106, v107
	v_add_u32_e32 v167, 0x20000, v165
	global_store_dwordx4 v167, v[108:111], s[34:35] offset:0
	s_waitcnt vmcnt(15)
	v_lshlrev_b32_e32 v144, 16, v194
	v_and_b32_e32 v145, 0xffff0000, v194
	v_lshlrev_b32_e32 v146, 16, v195
	v_and_b32_e32 v147, 0xffff0000, v195
	v_lshlrev_b32_e32 v148, 16, v196
	v_and_b32_e32 v149, 0xffff0000, v196
	v_lshlrev_b32_e32 v150, 16, v197
	v_and_b32_e32 v151, 0xffff0000, v197
	v_pk_fma_f32 v[100:101], v[100:101], v[76:77], v[144:145]
	v_pk_fma_f32 v[102:103], v[102:103], v[78:79], v[146:147]
	v_pk_fma_f32 v[96:97], v[96:97], v[72:73], v[148:149]
	v_pk_fma_f32 v[98:99], v[98:99], v[74:75], v[150:151]
	v_cvt_pk_bf16_f32 v100, v100, v101
	v_cvt_pk_bf16_f32 v101, v102, v103
	v_cvt_pk_bf16_f32 v102, v96, v97
	v_cvt_pk_bf16_f32 v103, v98, v99
	v_add_u32_e32 v167, 0x20000, v165
	global_store_dwordx4 v167, v[100:103], s[34:35] offset:256
	s_waitcnt vmcnt(15)
	v_lshlrev_b32_e32 v144, 16, v198
	v_and_b32_e32 v145, 0xffff0000, v198
	v_lshlrev_b32_e32 v146, 16, v199
	v_and_b32_e32 v147, 0xffff0000, v199
	v_lshlrev_b32_e32 v148, 16, v200
	v_and_b32_e32 v149, 0xffff0000, v200
	v_lshlrev_b32_e32 v150, 16, v201
	v_and_b32_e32 v151, 0xffff0000, v201
	v_pk_fma_f32 v[88:89], v[88:89], v[92:93], v[144:145]
	v_pk_fma_f32 v[90:91], v[90:91], v[94:95], v[146:147]
	v_pk_fma_f32 v[80:81], v[80:81], v[84:85], v[148:149]
	v_pk_fma_f32 v[82:83], v[82:83], v[86:87], v[150:151]
	v_cvt_pk_bf16_f32 v88, v88, v89
	v_cvt_pk_bf16_f32 v89, v90, v91
	v_cvt_pk_bf16_f32 v90, v80, v81
	v_cvt_pk_bf16_f32 v91, v82, v83
	v_add_u32_e32 v167, 0x30000, v165
	global_store_dwordx4 v167, v[88:91], s[34:35] offset:0
	s_waitcnt vmcnt(15)
	v_lshlrev_b32_e32 v144, 16, v202
	v_and_b32_e32 v145, 0xffff0000, v202
	v_lshlrev_b32_e32 v146, 16, v203
	v_and_b32_e32 v147, 0xffff0000, v203
	v_lshlrev_b32_e32 v148, 16, v204
	v_and_b32_e32 v149, 0xffff0000, v204
	v_lshlrev_b32_e32 v150, 16, v205
	v_and_b32_e32 v151, 0xffff0000, v205
	v_pk_fma_f32 v[68:69], v[68:69], v[76:77], v[144:145]
	v_pk_fma_f32 v[70:71], v[70:71], v[78:79], v[146:147]
	v_pk_fma_f32 v[64:65], v[64:65], v[72:73], v[148:149]
	v_pk_fma_f32 v[66:67], v[66:67], v[74:75], v[150:151]
	v_cvt_pk_bf16_f32 v68, v68, v69
	v_cvt_pk_bf16_f32 v69, v70, v71
	v_cvt_pk_bf16_f32 v70, v64, v65
	v_cvt_pk_bf16_f32 v71, v66, v67
	v_add_u32_e32 v167, 0x30000, v165
	global_store_dwordx4 v167, v[68:71], s[34:35] offset:256
	s_waitcnt vmcnt(15)
; __device__ __forceinline__ float bflo(unsigned w) { return __uint_as_float(w << 16); }
; __device__ __forceinline__ float bfhi(unsigned w) { return __uint_as_float(w & 0xffff0000u); }
; __device__ __forceinline__ u32x4 pack8u(f32x4 a, f32x4 b) { u32x4 w = {cvt_pk_bf16(a[0], a[1]), cvt_pk_bf16(a[2], a[3]), cvt_pk_bf16(b[0], b[1]), cvt_pk_bf16(b[2], b[3])}; return w; }
;     __device__ __forceinline__ void operator()(const AccT& acc, const Unit& u, int wr, int wc, int fr, int fq) const {
;     ...
;                 for (int bj = 0; bj < 2; ++bj) {
;                     const size_t off = (size_t)row * D + u.pn * 256 + bj * 128 + wc * 32 + fq * 8;
;                     f32x4 x0, x1;
;                     if (XINF) { x0 = *(const f32x4*)(XINF + off); x1 = *(const f32x4*)(XINF + off + 4); }
;                     else { const u32x4 w = *(const u32x4*)(XIN16 + off); x0 = (f32x4){bflo(w[0]), bfhi(w[0]), bflo(w[1]), bfhi(w[1])}; x1 = (f32x4){bflo(w[2]), bfhi(w[2]), bflo(w[3]), bfhi(w[3])}; }
;                     *(u32x4*)(XOUT + off) = pack8u(x0 + gt[bj][0] * acc[ai][bj][m][0], x1 + gt[bj][1] * acc[ai][bj][m][1]);
	v_lshlrev_b32_e32 v144, 16, v228
	v_and_b32_e32 v145, 0xffff0000, v228
	v_lshlrev_b32_e32 v146, 16, v229
	v_and_b32_e32 v147, 0xffff0000, v229
	v_lshlrev_b32_e32 v148, 16, v230
	v_and_b32_e32 v149, 0xffff0000, v230
	v_lshlrev_b32_e32 v150, 16, v231
	v_and_b32_e32 v151, 0xffff0000, v231
	v_pk_fma_f32 v[60:61], v[60:61], v[92:93], v[144:145]
	v_pk_fma_f32 v[62:63], v[62:63], v[94:95], v[146:147]
	v_pk_fma_f32 v[56:57], v[56:57], v[84:85], v[148:149]
	v_pk_fma_f32 v[58:59], v[58:59], v[86:87], v[150:151]
	v_cvt_pk_bf16_f32 v60, v60, v61
	v_cvt_pk_bf16_f32 v61, v62, v63
	v_cvt_pk_bf16_f32 v62, v56, v57
	v_cvt_pk_bf16_f32 v63, v58, v59
	v_add_u32_e32 v167, 0x80000, v165
	global_store_dwordx4 v167, v[60:63], s[34:35] offset:0
	s_waitcnt vmcnt(14)
	v_lshlrev_b32_e32 v144, 16, v168
	v_and_b32_e32 v145, 0xffff0000, v168
	v_lshlrev_b32_e32 v146, 16, v169
	v_and_b32_e32 v147, 0xffff0000, v169
	v_lshlrev_b32_e32 v148, 16, v170
	v_and_b32_e32 v149, 0xffff0000, v170
	v_lshlrev_b32_e32 v150, 16, v171
	v_and_b32_e32 v151, 0xffff0000, v171
	v_pk_fma_f32 v[52:53], v[52:53], v[76:77], v[144:145]
	v_pk_fma_f32 v[54:55], v[54:55], v[78:79], v[146:147]
	v_pk_fma_f32 v[48:49], v[48:49], v[72:73], v[148:149]
	v_pk_fma_f32 v[50:51], v[50:51], v[74:75], v[150:151]
	v_cvt_pk_bf16_f32 v52, v52, v53
	v_cvt_pk_bf16_f32 v53, v54, v55
	v_cvt_pk_bf16_f32 v54, v48, v49
	v_cvt_pk_bf16_f32 v55, v50, v51
	v_add_u32_e32 v167, 0x80000, v165
	global_store_dwordx4 v167, v[52:55], s[34:35] offset:256
	s_waitcnt vmcnt(14)
	v_lshlrev_b32_e32 v144, 16, v136
	v_and_b32_e32 v145, 0xffff0000, v136
	v_lshlrev_b32_e32 v146, 16, v137
	v_and_b32_e32 v147, 0xffff0000, v137
	v_lshlrev_b32_e32 v148, 16, v138
	v_and_b32_e32 v149, 0xffff0000, v138
	v_lshlrev_b32_e32 v150, 16, v139
	v_and_b32_e32 v151, 0xffff0000, v139
	v_pk_fma_f32 v[44:45], v[44:45], v[92:93], v[144:145]
	v_pk_fma_f32 v[46:47], v[46:47], v[94:95], v[146:147]
	v_pk_fma_f32 v[40:41], v[40:41], v[84:85], v[148:149]
	v_pk_fma_f32 v[42:43], v[42:43], v[86:87], v[150:151]
	v_cvt_pk_bf16_f32 v44, v44, v45
	v_cvt_pk_bf16_f32 v45, v46, v47
	v_cvt_pk_bf16_f32 v46, v40, v41
	v_cvt_pk_bf16_f32 v47, v42, v43
	v_add_u32_e32 v167, 0x90000, v165
	global_store_dwordx4 v167, v[44:47], s[34:35] offset:0
	s_waitcnt vmcnt(13)
	v_lshlrev_b32_e32 v144, 16, v178
	v_and_b32_e32 v145, 0xffff0000, v178
	v_lshlrev_b32_e32 v146, 16, v179
	v_and_b32_e32 v147, 0xffff0000, v179
	v_lshlrev_b32_e32 v148, 16, v180
	v_and_b32_e32 v149, 0xffff0000, v180
	v_lshlrev_b32_e32 v150, 16, v181
	v_and_b32_e32 v151, 0xffff0000, v181
	v_pk_fma_f32 v[36:37], v[36:37], v[76:77], v[144:145]
	v_pk_fma_f32 v[38:39], v[38:39], v[78:79], v[146:147]
	v_pk_fma_f32 v[32:33], v[32:33], v[72:73], v[148:149]
	v_pk_fma_f32 v[34:35], v[34:35], v[74:75], v[150:151]
	v_cvt_pk_bf16_f32 v36, v36, v37
	v_cvt_pk_bf16_f32 v37, v38, v39
	v_cvt_pk_bf16_f32 v38, v32, v33
	v_cvt_pk_bf16_f32 v39, v34, v35
	v_add_u32_e32 v167, 0x90000, v165
	global_store_dwordx4 v167, v[36:39], s[34:35] offset:256
	s_waitcnt vmcnt(13)
	v_lshlrev_b32_e32 v144, 16, v128
	v_and_b32_e32 v145, 0xffff0000, v128
	v_lshlrev_b32_e32 v146, 16, v129
	v_and_b32_e32 v147, 0xffff0000, v129
	v_lshlrev_b32_e32 v148, 16, v130
	v_and_b32_e32 v149, 0xffff0000, v130
	v_lshlrev_b32_e32 v150, 16, v131
	v_and_b32_e32 v151, 0xffff0000, v131
	v_pk_fma_f32 v[28:29], v[28:29], v[92:93], v[144:145]
	v_pk_fma_f32 v[30:31], v[30:31], v[94:95], v[146:147]
	v_pk_fma_f32 v[24:25], v[24:25], v[84:85], v[148:149]
	v_pk_fma_f32 v[26:27], v[26:27], v[86:87], v[150:151]
	v_cvt_pk_bf16_f32 v28, v28, v29
	v_cvt_pk_bf16_f32 v29, v30, v31
	v_cvt_pk_bf16_f32 v30, v24, v25
	v_cvt_pk_bf16_f32 v31, v26, v27
	v_add_u32_e32 v167, 0xa0000, v165
	global_store_dwordx4 v167, v[28:31], s[34:35] offset:0
	s_waitcnt vmcnt(12)
	v_lshlrev_b32_e32 v144, 16, v182
	v_and_b32_e32 v145, 0xffff0000, v182
	v_lshlrev_b32_e32 v146, 16, v183
	v_and_b32_e32 v147, 0xffff0000, v183
	v_lshlrev_b32_e32 v148, 16, v184
	v_and_b32_e32 v149, 0xffff0000, v184
	v_lshlrev_b32_e32 v150, 16, v185
	v_and_b32_e32 v151, 0xffff0000, v185
	v_pk_fma_f32 v[20:21], v[20:21], v[76:77], v[144:145]
	v_pk_fma_f32 v[22:23], v[22:23], v[78:79], v[146:147]
	v_pk_fma_f32 v[16:17], v[16:17], v[72:73], v[148:149]
	v_pk_fma_f32 v[18:19], v[18:19], v[74:75], v[150:151]
	v_cvt_pk_bf16_f32 v20, v20, v21
	v_cvt_pk_bf16_f32 v21, v22, v23
	v_cvt_pk_bf16_f32 v22, v16, v17
	v_cvt_pk_bf16_f32 v23, v18, v19
	v_add_u32_e32 v167, 0xa0000, v165
	global_store_dwordx4 v167, v[20:23], s[34:35] offset:256
	s_waitcnt vmcnt(12)
	v_lshlrev_b32_e32 v144, 16, v120
	v_and_b32_e32 v145, 0xffff0000, v120
	v_lshlrev_b32_e32 v146, 16, v121
	v_and_b32_e32 v147, 0xffff0000, v121
	v_lshlrev_b32_e32 v148, 16, v122
	v_and_b32_e32 v149, 0xffff0000, v122
	v_lshlrev_b32_e32 v150, 16, v123
	v_and_b32_e32 v151, 0xffff0000, v123
	v_pk_fma_f32 v[12:13], v[12:13], v[92:93], v[144:145]
	v_pk_fma_f32 v[14:15], v[14:15], v[94:95], v[146:147]
	v_pk_fma_f32 v[8:9], v[8:9], v[84:85], v[148:149]
	v_pk_fma_f32 v[10:11], v[10:11], v[86:87], v[150:151]
	v_cvt_pk_bf16_f32 v12, v12, v13
	v_cvt_pk_bf16_f32 v13, v14, v15
	v_cvt_pk_bf16_f32 v14, v8, v9
	v_cvt_pk_bf16_f32 v15, v10, v11
	v_add_u32_e32 v167, 0xb0000, v165
	global_store_dwordx4 v167, v[12:15], s[34:35] offset:0
	s_waitcnt vmcnt(11)
	v_lshlrev_b32_e32 v144, 16, v186
	v_and_b32_e32 v145, 0xffff0000, v186
	v_lshlrev_b32_e32 v146, 16, v187
	v_and_b32_e32 v147, 0xffff0000, v187
	v_lshlrev_b32_e32 v148, 16, v188
	v_and_b32_e32 v149, 0xffff0000, v188
	v_lshlrev_b32_e32 v150, 16, v189
	v_and_b32_e32 v151, 0xffff0000, v189
	v_pk_fma_f32 v[4:5], v[4:5], v[76:77], v[144:145]
	v_pk_fma_f32 v[6:7], v[6:7], v[78:79], v[146:147]
	v_pk_fma_f32 v[0:1], v[0:1], v[72:73], v[148:149]
	v_pk_fma_f32 v[2:3], v[2:3], v[74:75], v[150:151]
	v_cvt_pk_bf16_f32 v4, v4, v5
	v_cvt_pk_bf16_f32 v5, v6, v7
	v_cvt_pk_bf16_f32 v6, v0, v1
	v_cvt_pk_bf16_f32 v7, v2, v3
	v_add_u32_e32 v167, 0xb0000, v165
	global_store_dwordx4 v167, v[4:7], s[34:35] offset:256
	s_mov_b64 s[42:43], exec
	s_branch .Lepr1_latch

; #define PG8_STAGE(bufoff, gbase, voff) do { _Pragma("unroll") for (int _i = 0; _i < 2; ++_i) \
;         __builtin_amdgcn_global_load_lds((const unsigned*)((const char*)(gbase) + (voff)[_i]), (LAS unsigned*)(lds + (bufoff) + ldsw + _i * 8192), 16, 0, 0); } while (0)
; #define PG8_LDA(dst, b, h) do { _Pragma("unroll") for (int m = 0; m < 4; ++m) _Pragma("unroll") for (int k = 0; k < 2; ++k) dst[m][k] = *(const LAS bf16x8*)(lds + PG8_SA(b, h) + aoff + m * 2048 + k * 1024); } while (0)
; #define PG8_LDB(dst, b, h) do { _Pragma("unroll") for (int n = 0; n < 2; ++n) _Pragma("unroll") for (int k = 0; k < 2; ++k) dst[n][k] = *(const LAS bf16x8*)(lds + PG8_SB(b, h) + boff + n * 2048 + k * 1024); } while (0)
; #define PG8_MMA(ai, bj, At, Bt) do { __builtin_amdgcn_s_setprio(1); _Pragma("unroll") for (int m = 0; m < 4; ++m) _Pragma("unroll") for (int n = 0; n < 2; ++n) _Pragma("unroll") for (int k = 0; k < 2; ++k) \
;         acc[ai][bj][m][n] = __builtin_amdgcn_mfma_f32_16x16x32_bf16(Bt[n][k], At[m][k], acc[ai][bj][m][n], 0, 0, 0); __builtin_amdgcn_s_setprio(0); } while (0)
; #define PG8_WAIT_V(n) asm volatile("s_waitcnt vmcnt(" #n ")" ::: "memory")
; #define PG8_WAIT_L(n) asm volatile("s_waitcnt lgkmcnt(" #n ")" ::: "memory")
; #define PG8_BAR __builtin_amdgcn_s_barrier()
; #define PG8_SCHED __builtin_amdgcn_sched_barrier(0)
; template <class Epi>
; __device__ __forceinline__ void gemm_phase(LAS unsigned char* lds, const Gemm g, const Epi& E) {
;     ...
;             PG8_LDB(B0, 0, 0); PG8_SCHED; PG8_LDA(At, 0, 0); PG8_STAGE(PG8_SA(1, 1), a1 + hstep, voffA);
;             PG8_WAIT_L(8); PG8_BAR; PG8_WAIT_L(0); PG8_MMA(0, 0, At, B0); PG8_BAR; PG8_SCHED;
;             PG8_LDB(B1, 0, 1); PG8_STAGE(PG8_SB(0, 0), b2, voffB);
;             PG8_BAR; PG8_WAIT_L(0); PG8_MMA(0, 1, At, B1); PG8_BAR;
;             PG8_LDA(At, 0, 1); PG8_STAGE(PG8_SA(0, 0), a2, voffA);
;             PG8_BAR; PG8_WAIT_L(0); PG8_MMA(1, 0, At, B0); PG8_BAR; PG8_SCHED;
;             PG8_STAGE(PG8_SB(0, 1), b2 + hstep, voffB);
;             PG8_WAIT_V(6); PG8_BAR; PG8_MMA(1, 1, At, B1); PG8_BAR;
.LBB0_211:
	s_add_u32 s28, s26, 0xfffc0080
	s_addc_u32 s29, s27, -1
	s_add_i32 s34, 0, 0x10000
	v_add_u32_e32 v150, s34, v159
	ds_read_b128 v[138:141], v150
	ds_read_b128 v[142:145], v150 offset:1024
	ds_read_b128 v[146:149], v150 offset:2048
	ds_read_b128 v[150:153], v150 offset:3072
	s_cmp_eq_u32 vcc_hi, 12
	s_cselect_b32 s37, s38, s29
	s_cselect_b32 s36, s39, s28
	s_cselect_b32 s29, s43, vcc_lo
	s_cselect_b32 s28, s49, s65
	s_add_i32 m0, s74, 0xc000
	ds_read_b128 v[154:157], v161
	ds_read_b128 v[162:165], v161 offset:1024
	ds_read_b128 v[166:169], v161 offset:2048
	ds_read_b128 v[170:173], v161 offset:3072
	ds_read_b128 v[174:177], v161 offset:4096
	ds_read_b128 v[178:181], v161 offset:5120
	ds_read_b128 v[182:185], v161 offset:6144
	ds_read_b128 v[186:189], v161 offset:7168
	global_load_lds_dwordx4 v134, s[26:27]
	s_add_i32 m0, s74, 0xe000
	s_nop 0
	global_load_lds_dwordx4 v136, s[26:27]
	s_waitcnt lgkmcnt(8)
	s_barrier
	s_waitcnt lgkmcnt(0)
	v_mfma_f32_16x16x32_bf16 v[124:127], v[138:141], v[154:157], v[124:127]
	v_mfma_f32_16x16x32_bf16 v[120:123], v[146:149], v[154:157], v[120:123]
	v_mfma_f32_16x16x32_bf16 v[108:111], v[138:141], v[166:169], v[108:111]
	v_mfma_f32_16x16x32_bf16 v[104:107], v[146:149], v[166:169], v[104:107]
	v_mfma_f32_16x16x32_bf16 v[92:95], v[138:141], v[174:177], v[92:95]
	v_mfma_f32_16x16x32_bf16 v[88:91], v[146:149], v[174:177], v[88:91]
	v_mfma_f32_16x16x32_bf16 v[76:79], v[138:141], v[182:185], v[76:79]
	v_mfma_f32_16x16x32_bf16 v[72:75], v[146:149], v[182:185], v[72:75]
	v_mfma_f32_16x16x32_bf16 v[124:127], v[142:145], v[162:165], v[124:127]
	v_mfma_f32_16x16x32_bf16 v[120:123], v[150:153], v[162:165], v[120:123]
	v_mfma_f32_16x16x32_bf16 v[108:111], v[142:145], v[170:173], v[108:111]
	v_mfma_f32_16x16x32_bf16 v[104:107], v[150:153], v[170:173], v[104:107]
	v_mfma_f32_16x16x32_bf16 v[92:95], v[142:145], v[178:181], v[92:95]
	v_mfma_f32_16x16x32_bf16 v[88:91], v[150:153], v[178:181], v[88:91]
	v_mfma_f32_16x16x32_bf16 v[76:79], v[142:145], v[186:189], v[76:79]
	v_mfma_f32_16x16x32_bf16 v[72:75], v[150:153], v[186:189], v[72:75]
	s_barrier
	s_add_i32 s46, 0, 0x14000
	s_add_i32 s34, s34, s71
	v_add_u32_e32 v202, s46, v159
	s_mov_b32 m0, s34
	ds_read_b128 v[190:193], v202
	ds_read_b128 v[194:197], v202 offset:1024
	ds_read_b128 v[198:201], v202 offset:2048
	ds_read_b128 v[202:205], v202 offset:3072
	global_load_lds_dwordx4 v208, s[28:29]
	s_add_i32 m0, s34, 0x2000
	s_nop 0
	global_load_lds_dwordx4 v132, s[28:29]
	s_barrier
	s_waitcnt lgkmcnt(0)
	v_mfma_f32_16x16x32_bf16 v[116:119], v[190:193], v[154:157], v[116:119]
	v_mfma_f32_16x16x32_bf16 v[112:115], v[198:201], v[154:157], v[112:115]
	v_mfma_f32_16x16x32_bf16 v[100:103], v[190:193], v[166:169], v[100:103]
	v_mfma_f32_16x16x32_bf16 v[96:99], v[198:201], v[166:169], v[96:99]
	v_mfma_f32_16x16x32_bf16 v[84:87], v[190:193], v[174:177], v[84:87]
	v_mfma_f32_16x16x32_bf16 v[80:83], v[198:201], v[174:177], v[80:83]
	v_mfma_f32_16x16x32_bf16 v[68:71], v[190:193], v[182:185], v[68:71]
	v_mfma_f32_16x16x32_bf16 v[64:67], v[198:201], v[182:185], v[64:67]
	v_mfma_f32_16x16x32_bf16 v[116:119], v[194:197], v[162:165], v[116:119]
	v_mfma_f32_16x16x32_bf16 v[112:115], v[202:205], v[162:165], v[112:115]
	v_mfma_f32_16x16x32_bf16 v[100:103], v[194:197], v[170:173], v[100:103]
	v_mfma_f32_16x16x32_bf16 v[96:99], v[202:205], v[170:173], v[96:99]
	v_mfma_f32_16x16x32_bf16 v[84:87], v[194:197], v[178:181], v[84:87]
	v_mfma_f32_16x16x32_bf16 v[80:83], v[202:205], v[178:181], v[80:83]
	v_mfma_f32_16x16x32_bf16 v[68:71], v[194:197], v[186:189], v[68:71]
	v_mfma_f32_16x16x32_bf16 v[64:67], v[202:205], v[186:189], v[64:67]
	s_barrier
	s_mov_b32 m0, s74
	ds_read_b128 v[154:157], v161 offset:16384
	ds_read_b128 v[162:165], v161 offset:17408
	ds_read_b128 v[166:169], v161 offset:18432
	ds_read_b128 v[170:173], v161 offset:19456
	ds_read_b128 v[174:177], v161 offset:20480
	ds_read_b128 v[178:181], v161 offset:21504
	ds_read_b128 v[182:185], v161 offset:22528
	ds_read_b128 v[186:189], v161 offset:23552
	global_load_lds_dwordx4 v128, s[36:37]
	s_mov_b32 m0, s76
	s_nop 0
	global_load_lds_dwordx4 v130, s[36:37]
	s_barrier
	s_waitcnt lgkmcnt(0)
	v_mfma_f32_16x16x32_bf16 v[60:63], v[138:141], v[154:157], v[60:63]
	v_mfma_f32_16x16x32_bf16 v[56:59], v[146:149], v[154:157], v[56:59]
	v_mfma_f32_16x16x32_bf16 v[44:47], v[138:141], v[166:169], v[44:47]
	v_mfma_f32_16x16x32_bf16 v[40:43], v[146:149], v[166:169], v[40:43]
	v_mfma_f32_16x16x32_bf16 v[28:31], v[138:141], v[174:177], v[28:31]
	v_mfma_f32_16x16x32_bf16 v[24:27], v[146:149], v[174:177], v[24:27]
	v_mfma_f32_16x16x32_bf16 v[12:15], v[138:141], v[182:185], v[12:15]
	v_mfma_f32_16x16x32_bf16 v[8:11], v[146:149], v[182:185], v[8:11]
	v_mfma_f32_16x16x32_bf16 v[60:63], v[142:145], v[162:165], v[60:63]
	v_mfma_f32_16x16x32_bf16 v[56:59], v[150:153], v[162:165], v[56:59]
	v_mfma_f32_16x16x32_bf16 v[44:47], v[142:145], v[170:173], v[44:47]
	v_mfma_f32_16x16x32_bf16 v[40:43], v[150:153], v[170:173], v[40:43]
	v_mfma_f32_16x16x32_bf16 v[28:31], v[142:145], v[178:181], v[28:31]
	v_mfma_f32_16x16x32_bf16 v[24:27], v[150:153], v[178:181], v[24:27]
	v_mfma_f32_16x16x32_bf16 v[12:15], v[142:145], v[186:189], v[12:15]
	v_mfma_f32_16x16x32_bf16 v[8:11], v[150:153], v[186:189], v[8:11]
	s_barrier
	s_add_u32 s34, s28, 0x40000
	s_addc_u32 s35, s29, 0
	s_add_i32 s46, s46, s71
	s_mov_b32 m0, s46
	s_nop 0
	global_load_lds_dwordx4 v208, s[34:35]
	s_add_i32 m0, s46, 0x2000
	s_nop 0
	global_load_lds_dwordx4 v132, s[34:35]
	s_waitcnt vmcnt(6)
	s_barrier
; #define PG8_STAGE(bufoff, gbase, voff) do { _Pragma("unroll") for (int _i = 0; _i < 2; ++_i) \
;         __builtin_amdgcn_global_load_lds((const unsigned*)((const char*)(gbase) + (voff)[_i]), (LAS unsigned*)(lds + (bufoff) + ldsw + _i * 8192), 16, 0, 0); } while (0)
; #define PG8_LDA(dst, b, h) do { _Pragma("unroll") for (int m = 0; m < 4; ++m) _Pragma("unroll") for (int k = 0; k < 2; ++k) dst[m][k] = *(const LAS bf16x8*)(lds + PG8_SA(b, h) + aoff + m * 2048 + k * 1024); } while (0)
; #define PG8_LDB(dst, b, h) do { _Pragma("unroll") for (int n = 0; n < 2; ++n) _Pragma("unroll") for (int k = 0; k < 2; ++k) dst[n][k] = *(const LAS bf16x8*)(lds + PG8_SB(b, h) + boff + n * 2048 + k * 1024); } while (0)
; #define PG8_MMA(ai, bj, At, Bt) do { __builtin_amdgcn_s_setprio(1); _Pragma("unroll") for (int m = 0; m < 4; ++m) _Pragma("unroll") for (int n = 0; n < 2; ++n) _Pragma("unroll") for (int k = 0; k < 2; ++k) \
;         acc[ai][bj][m][n] = __builtin_amdgcn_mfma_f32_16x16x32_bf16(Bt[n][k], At[m][k], acc[ai][bj][m][n], 0, 0, 0); __builtin_amdgcn_s_setprio(0); } while (0)
; #define PG8_WAIT_V(n) asm volatile("s_waitcnt vmcnt(" #n ")" ::: "memory")
; #define PG8_WAIT_L(n) asm volatile("s_waitcnt lgkmcnt(" #n ")" ::: "memory")
; #define PG8_BAR __builtin_amdgcn_s_barrier()
; #define PG8_SCHED __builtin_amdgcn_sched_barrier(0)
; template <class Epi>
; __device__ __forceinline__ void gemm_phase(LAS unsigned char* lds, const Gemm g, const Epi& E) {
;     ...
;             PG8_WAIT_V(6); PG8_BAR; PG8_MMA(1, 1, At, B1); PG8_BAR;
;             PG8_LDB(B0, 1, 0); PG8_SCHED; PG8_LDA(At, 1, 0); PG8_STAGE(PG8_SA(0, 1), a2 + hstep, voffA);
;             PG8_WAIT_L(8); PG8_BAR; PG8_WAIT_L(0); PG8_MMA(0, 0, At, B0); PG8_BAR; PG8_SCHED;
;             PG8_LDB(B1, 1, 1); PG8_STAGE(PG8_SB(1, 0), b3, voffB);
;             PG8_BAR; PG8_WAIT_L(0); PG8_MMA(0, 1, At, B1); PG8_BAR;
;             PG8_LDA(At, 1, 1); PG8_STAGE(PG8_SA(1, 0), a3, voffA);
;             PG8_BAR; PG8_WAIT_L(0); PG8_MMA(1, 0, At, B0); PG8_BAR; PG8_SCHED;
	v_mfma_f32_16x16x32_bf16 v[52:55], v[190:193], v[154:157], v[52:55]
	v_mfma_f32_16x16x32_bf16 v[48:51], v[198:201], v[154:157], v[48:51]
	v_mfma_f32_16x16x32_bf16 v[36:39], v[190:193], v[166:169], v[36:39]
	v_mfma_f32_16x16x32_bf16 v[32:35], v[198:201], v[166:169], v[32:35]
	v_mfma_f32_16x16x32_bf16 v[20:23], v[190:193], v[174:177], v[20:23]
	v_mfma_f32_16x16x32_bf16 v[16:19], v[198:201], v[174:177], v[16:19]
	v_mfma_f32_16x16x32_bf16 v[4:7], v[190:193], v[182:185], v[4:7]
	v_mfma_f32_16x16x32_bf16 v[0:3], v[198:201], v[182:185], v[0:3]
	v_mfma_f32_16x16x32_bf16 v[52:55], v[194:197], v[162:165], v[52:55]
	v_mfma_f32_16x16x32_bf16 v[48:51], v[202:205], v[162:165], v[48:51]
	v_mfma_f32_16x16x32_bf16 v[36:39], v[194:197], v[170:173], v[36:39]
	v_mfma_f32_16x16x32_bf16 v[32:35], v[202:205], v[170:173], v[32:35]
	v_mfma_f32_16x16x32_bf16 v[20:23], v[194:197], v[178:181], v[20:23]
	v_mfma_f32_16x16x32_bf16 v[16:19], v[202:205], v[178:181], v[16:19]
	v_mfma_f32_16x16x32_bf16 v[4:7], v[194:197], v[186:189], v[4:7]
	v_mfma_f32_16x16x32_bf16 v[0:3], v[202:205], v[186:189], v[0:3]
	s_barrier
	s_add_i32 s46, 0, 0x18000
	v_add_u32_e32 v150, s46, v159
	ds_read_b128 v[138:141], v150
	ds_read_b128 v[142:145], v150 offset:1024
	ds_read_b128 v[146:149], v150 offset:2048
	ds_read_b128 v[150:153], v150 offset:3072
	s_add_u32 s34, s36, 0x40000
	s_addc_u32 s35, s37, 0
	s_mov_b32 m0, s78
	ds_read_b128 v[154:157], v161 offset:32768
	ds_read_b128 v[162:165], v161 offset:33792
	ds_read_b128 v[166:169], v161 offset:34816
	ds_read_b128 v[170:173], v161 offset:35840
	ds_read_b128 v[174:177], v161 offset:36864
	ds_read_b128 v[178:181], v161 offset:37888
	ds_read_b128 v[182:185], v161 offset:38912
	ds_read_b128 v[186:189], v161 offset:39936
	global_load_lds_dwordx4 v128, s[34:35]
	s_mov_b32 m0, s79
	s_nop 0
	global_load_lds_dwordx4 v130, s[34:35]
	s_waitcnt lgkmcnt(8)
	s_barrier
	s_waitcnt lgkmcnt(0)
	v_mfma_f32_16x16x32_bf16 v[124:127], v[138:141], v[154:157], v[124:127]
	v_mfma_f32_16x16x32_bf16 v[120:123], v[146:149], v[154:157], v[120:123]
	v_mfma_f32_16x16x32_bf16 v[108:111], v[138:141], v[166:169], v[108:111]
	v_mfma_f32_16x16x32_bf16 v[104:107], v[146:149], v[166:169], v[104:107]
	v_mfma_f32_16x16x32_bf16 v[92:95], v[138:141], v[174:177], v[92:95]
	v_mfma_f32_16x16x32_bf16 v[88:91], v[146:149], v[174:177], v[88:91]
	v_mfma_f32_16x16x32_bf16 v[76:79], v[138:141], v[182:185], v[76:79]
	v_mfma_f32_16x16x32_bf16 v[72:75], v[146:149], v[182:185], v[72:75]
	v_mfma_f32_16x16x32_bf16 v[124:127], v[142:145], v[162:165], v[124:127]
	v_mfma_f32_16x16x32_bf16 v[120:123], v[150:153], v[162:165], v[120:123]
	v_mfma_f32_16x16x32_bf16 v[108:111], v[142:145], v[170:173], v[108:111]
	v_mfma_f32_16x16x32_bf16 v[104:107], v[150:153], v[170:173], v[104:107]
	v_mfma_f32_16x16x32_bf16 v[92:95], v[142:145], v[178:181], v[92:95]
	v_mfma_f32_16x16x32_bf16 v[88:91], v[150:153], v[178:181], v[88:91]
	v_mfma_f32_16x16x32_bf16 v[76:79], v[142:145], v[186:189], v[76:79]
	v_mfma_f32_16x16x32_bf16 v[72:75], v[150:153], v[186:189], v[72:75]
	s_barrier
	s_add_i32 s34, 0, 0x1c000
	s_add_i32 s35, s46, s71
	v_add_u32_e32 v202, s34, v159
	s_mov_b32 m0, s35
	ds_read_b128 v[190:193], v202
	ds_read_b128 v[194:197], v202 offset:1024
	ds_read_b128 v[198:201], v202 offset:2048
	ds_read_b128 v[202:205], v202 offset:3072
	s_add_u32 s98, s28, 0x80
	s_addc_u32 s99, s29, 0
	global_load_lds_dwordx4 v208, s[98:99]
	s_add_i32 m0, s35, 0x2000
	s_add_u32 s100, s28, 0x80
	s_addc_u32 s101, s29, 0
	global_load_lds_dwordx4 v132, s[100:101]
	s_barrier
	s_waitcnt lgkmcnt(0)
	v_mfma_f32_16x16x32_bf16 v[116:119], v[190:193], v[154:157], v[116:119]
	v_mfma_f32_16x16x32_bf16 v[112:115], v[198:201], v[154:157], v[112:115]
	v_mfma_f32_16x16x32_bf16 v[100:103], v[190:193], v[166:169], v[100:103]
	v_mfma_f32_16x16x32_bf16 v[96:99], v[198:201], v[166:169], v[96:99]
	v_mfma_f32_16x16x32_bf16 v[84:87], v[190:193], v[174:177], v[84:87]
	v_mfma_f32_16x16x32_bf16 v[80:83], v[198:201], v[174:177], v[80:83]
	v_mfma_f32_16x16x32_bf16 v[68:71], v[190:193], v[182:185], v[68:71]
	v_mfma_f32_16x16x32_bf16 v[64:67], v[198:201], v[182:185], v[64:67]
	v_mfma_f32_16x16x32_bf16 v[116:119], v[194:197], v[162:165], v[116:119]
	v_mfma_f32_16x16x32_bf16 v[112:115], v[202:205], v[162:165], v[112:115]
	v_mfma_f32_16x16x32_bf16 v[100:103], v[194:197], v[170:173], v[100:103]
	v_mfma_f32_16x16x32_bf16 v[96:99], v[202:205], v[170:173], v[96:99]
	v_mfma_f32_16x16x32_bf16 v[84:87], v[194:197], v[178:181], v[84:87]
	v_mfma_f32_16x16x32_bf16 v[80:83], v[202:205], v[178:181], v[80:83]
	v_mfma_f32_16x16x32_bf16 v[68:71], v[194:197], v[186:189], v[68:71]
	v_mfma_f32_16x16x32_bf16 v[64:67], v[202:205], v[186:189], v[64:67]
	s_barrier
	s_mov_b32 m0, s82
	ds_read_b128 v[154:157], v161 offset:49152
	ds_read_b128 v[162:165], v161 offset:50176
	ds_read_b128 v[166:169], v161 offset:51200
	ds_read_b128 v[170:173], v161 offset:52224
	ds_read_b128 v[174:177], v161 offset:53248
	ds_read_b128 v[178:181], v161 offset:54272
	ds_read_b128 v[182:185], v161 offset:55296
	ds_read_b128 v[186:189], v161 offset:56320
	s_add_u32 s98, s36, 0x80
	s_addc_u32 s99, s37, 0
	global_load_lds_dwordx4 v128, s[98:99]
	s_mov_b32 m0, s83
	s_add_u32 s100, s36, 0x80
	s_addc_u32 s101, s37, 0
	global_load_lds_dwordx4 v130, s[100:101]
	s_barrier
; __device__ __forceinline__ float bflo(unsigned w) { return __uint_as_float(w << 16); }
; __device__ __forceinline__ float bfhi(unsigned w) { return __uint_as_float(w & 0xffff0000u); }
; __device__ __forceinline__ u32x4 pack8u(f32x4 a, f32x4 b) { u32x4 w = {cvt_pk_bf16(a[0], a[1]), cvt_pk_bf16(a[2], a[3]), cvt_pk_bf16(b[0], b[1]), cvt_pk_bf16(b[2], b[3])}; return w; }
; #define PG8_STAGE(bufoff, gbase, voff) do { _Pragma("unroll") for (int _i = 0; _i < 2; ++_i) \
;         __builtin_amdgcn_global_load_lds((const unsigned*)((const char*)(gbase) + (voff)[_i]), (LAS unsigned*)(lds + (bufoff) + ldsw + _i * 8192), 16, 0, 0); } while (0)
; #define PG8_MMA(ai, bj, At, Bt) do { __builtin_amdgcn_s_setprio(1); _Pragma("unroll") for (int m = 0; m < 4; ++m) _Pragma("unroll") for (int n = 0; n < 2; ++n) _Pragma("unroll") for (int k = 0; k < 2; ++k) \
;         acc[ai][bj][m][n] = __builtin_amdgcn_mfma_f32_16x16x32_bf16(Bt[n][k], At[m][k], acc[ai][bj][m][n], 0, 0, 0); __builtin_amdgcn_s_setprio(0); } while (0)
; #define PG8_WAIT_V(n) asm volatile("s_waitcnt vmcnt(" #n ")" ::: "memory")
; #define PG8_BAR __builtin_amdgcn_s_barrier()
; template <class Epi>
; __device__ __forceinline__ void gemm_phase(LAS unsigned char* lds, const Gemm g, const Epi& E) {
;     ...
;             PG8_BAR; PG8_WAIT_L(0); PG8_MMA(1, 0, At, B0); PG8_BAR; PG8_SCHED;
;             PG8_STAGE(PG8_SB(1, 1), b3 + hstep, voffB);
;             PG8_WAIT_V(6); PG8_BAR; PG8_MMA(1, 1, At, B1); PG8_BAR;
;         }
;     __device__ __forceinline__ void operator()(const AccT& acc, const Unit& u, int wr, int wc, int fr, int fq) const {
; #pragma unroll
;         for (int ai = 0; ai < 2; ++ai)
; #pragma unroll
;             for (int m = 0; m < 4; ++m) {
;                 const int row = u.pm * 256 + ai * 128 + wr * 64 + m * 16 + fr;
; #pragma unroll
;                 for (int bj = 0; bj < 2; ++bj) {
;                     const int c8 = u.pn * 256 + bj * 128 + wc * 32 + fq * 8;
;                     const u32x4 gw = *(const u32x4*)(GATE + (size_t)row * 4096 + SECOND * 2048 + c8);
;                     const f32x4 g0 = {bflo(gw[0]), bfhi(gw[0]), bflo(gw[1]), bfhi(gw[1])}, g1 = {bflo(gw[2]), bfhi(gw[2]), bflo(gw[3]), bfhi(gw[3])};
;                     bf16_t* tp = (bf16_t*)TMP + (size_t)row * 2048 + c8;
;                     if (SECOND == 0) { *(u32x4*)tp = pack8u(g0 * acc[ai][bj][m][0], g1 * acc[ai][bj][m][1]); }
	s_waitcnt lgkmcnt(0)
	v_mfma_f32_16x16x32_bf16 v[60:63], v[138:141], v[154:157], v[60:63]
	v_mfma_f32_16x16x32_bf16 v[56:59], v[146:149], v[154:157], v[56:59]
	v_mfma_f32_16x16x32_bf16 v[44:47], v[138:141], v[166:169], v[44:47]
	v_mfma_f32_16x16x32_bf16 v[40:43], v[146:149], v[166:169], v[40:43]
	v_mfma_f32_16x16x32_bf16 v[28:31], v[138:141], v[174:177], v[28:31]
	v_mfma_f32_16x16x32_bf16 v[24:27], v[146:149], v[174:177], v[24:27]
	v_mfma_f32_16x16x32_bf16 v[12:15], v[138:141], v[182:185], v[12:15]
	v_mfma_f32_16x16x32_bf16 v[8:11], v[146:149], v[182:185], v[8:11]
	v_mfma_f32_16x16x32_bf16 v[60:63], v[142:145], v[162:165], v[60:63]
	v_mfma_f32_16x16x32_bf16 v[56:59], v[150:153], v[162:165], v[56:59]
	v_mfma_f32_16x16x32_bf16 v[44:47], v[142:145], v[170:173], v[44:47]
	v_mfma_f32_16x16x32_bf16 v[40:43], v[150:153], v[170:173], v[40:43]
	v_mfma_f32_16x16x32_bf16 v[28:31], v[142:145], v[178:181], v[28:31]
	v_mfma_f32_16x16x32_bf16 v[24:27], v[150:153], v[178:181], v[24:27]
	v_mfma_f32_16x16x32_bf16 v[12:15], v[142:145], v[186:189], v[12:15]
	v_mfma_f32_16x16x32_bf16 v[8:11], v[150:153], v[186:189], v[8:11]
	s_barrier
	s_add_u32 s28, s28, 0x40080
	s_addc_u32 s29, s29, 0
	s_add_i32 s34, s34, s71
	s_mov_b32 m0, s34
	s_nop 0
	global_load_lds_dwordx4 v208, s[28:29]
	s_add_i32 m0, s34, 0x2000
	s_nop 0
	global_load_lds_dwordx4 v132, s[28:29]
	s_waitcnt vmcnt(6)
	s_barrier
	v_mfma_f32_16x16x32_bf16 v[52:55], v[190:193], v[154:157], v[52:55]
	v_mfma_f32_16x16x32_bf16 v[48:51], v[198:201], v[154:157], v[48:51]
	v_mfma_f32_16x16x32_bf16 v[36:39], v[190:193], v[166:169], v[36:39]
	v_mfma_f32_16x16x32_bf16 v[32:35], v[198:201], v[166:169], v[32:35]
	v_mfma_f32_16x16x32_bf16 v[20:23], v[190:193], v[174:177], v[20:23]
	v_mfma_f32_16x16x32_bf16 v[16:19], v[198:201], v[174:177], v[16:19]
	v_mfma_f32_16x16x32_bf16 v[4:7], v[190:193], v[182:185], v[4:7]
	v_mfma_f32_16x16x32_bf16 v[0:3], v[198:201], v[182:185], v[0:3]
	v_mfma_f32_16x16x32_bf16 v[52:55], v[194:197], v[162:165], v[52:55]
	v_mfma_f32_16x16x32_bf16 v[48:51], v[202:205], v[162:165], v[48:51]
	v_mfma_f32_16x16x32_bf16 v[36:39], v[194:197], v[170:173], v[36:39]
	v_mfma_f32_16x16x32_bf16 v[32:35], v[202:205], v[170:173], v[32:35]
	v_mfma_f32_16x16x32_bf16 v[20:23], v[194:197], v[178:181], v[20:23]
	v_mfma_f32_16x16x32_bf16 v[16:19], v[202:205], v[178:181], v[16:19]
	v_mfma_f32_16x16x32_bf16 v[4:7], v[194:197], v[186:189], v[4:7]
	v_mfma_f32_16x16x32_bf16 v[0:3], v[202:205], v[186:189], v[0:3]
	s_barrier
	s_add_i32 vcc_hi, vcc_hi, 2
	s_add_u32 s26, s26, 0x100
	s_addc_u32 s27, s27, 0
	s_add_u32 s65, s65, 0x100
	s_addc_u32 vcc_lo, vcc_lo, 0
	s_cmp_gt_u32 vcc_hi, 13
	s_cbranch_scc0 .LBB0_211
	v_lshl_add_u32 v140, s42, 8, v158
	v_lshl_or_b32 v141, s96, 8, v160
	v_lshlrev_b32_e32 v141, 1, v141
	v_lshl_add_u32 v138, v140, 13, v141
	v_lshl_add_u32 v139, v140, 12, v141
	s_and_b64 vcc, exec, s[0:1]
	s_cbranch_vccnz .Lepo_second
	v_add_u32_e32 v140, 0x0, v138
	global_load_dwordx4 v[162:165], v140, s[44:45]
	v_add_u32_e32 v140, 0x0, v138
	global_load_dwordx4 v[166:169], v140, s[44:45] offset:256
	v_add_u32_e32 v140, 0x20000, v138
	global_load_dwordx4 v[170:173], v140, s[44:45]
	v_add_u32_e32 v140, 0x20000, v138
	global_load_dwordx4 v[174:177], v140, s[44:45] offset:256
	v_add_u32_e32 v140, 0x40000, v138
	global_load_dwordx4 v[178:181], v140, s[44:45]
	v_add_u32_e32 v140, 0x40000, v138
	global_load_dwordx4 v[182:185], v140, s[44:45] offset:256
	v_add_u32_e32 v140, 0x60000, v138
	global_load_dwordx4 v[186:189], v140, s[44:45]
	v_add_u32_e32 v140, 0x60000, v138
	global_load_dwordx4 v[190:193], v140, s[44:45] offset:256
	v_add_u32_e32 v140, 0x100000, v138
	global_load_dwordx4 v[194:197], v140, s[44:45]
	v_add_u32_e32 v140, 0x100000, v138
	global_load_dwordx4 v[198:201], v140, s[44:45] offset:256
	v_add_u32_e32 v140, 0x120000, v138
	global_load_dwordx4 v[202:205], v140, s[44:45]
	v_add_u32_e32 v140, 0x120000, v138
	global_load_dwordx4 v[228:231], v140, s[44:45] offset:256
	s_waitcnt vmcnt(11)
	v_lshlrev_b32_e32 v142, 16, v162
	v_and_b32_e32 v143, 0xffff0000, v162
	v_lshlrev_b32_e32 v144, 16, v163
	v_and_b32_e32 v145, 0xffff0000, v163
	v_lshlrev_b32_e32 v146, 16, v164
	v_and_b32_e32 v147, 0xffff0000, v164
	v_lshlrev_b32_e32 v148, 16, v165
	v_and_b32_e32 v149, 0xffff0000, v165
	v_pk_mul_f32 v[124:125], v[124:125], v[142:143]
	v_pk_mul_f32 v[126:127], v[126:127], v[144:145]
	v_pk_mul_f32 v[120:121], v[120:121], v[146:147]
	v_pk_mul_f32 v[122:123], v[122:123], v[148:149]
	v_cvt_pk_bf16_f32 v124, v124, v125
	v_cvt_pk_bf16_f32 v125, v126, v127
	v_cvt_pk_bf16_f32 v126, v120, v121
	v_cvt_pk_bf16_f32 v127, v122, v123
	v_add_u32_e32 v141, 0x0, v139
	global_store_dwordx4 v141, v[124:127], s[92:93]
	v_add_u32_e32 v140, 0x140000, v138
	global_load_dwordx4 v[162:165], v140, s[44:45]
	v_add_u32_e32 v140, 0x140000, v138
	global_load_dwordx4 v[120:123], v140, s[44:45] offset:256
	s_waitcnt vmcnt(13)
	v_lshlrev_b32_e32 v142, 16, v166
	v_and_b32_e32 v143, 0xffff0000, v166
	v_lshlrev_b32_e32 v144, 16, v167
	v_and_b32_e32 v145, 0xffff0000, v167
	v_lshlrev_b32_e32 v146, 16, v168
	v_and_b32_e32 v147, 0xffff0000, v168
	v_lshlrev_b32_e32 v148, 16, v169
	v_and_b32_e32 v149, 0xffff0000, v169
	v_pk_mul_f32 v[116:117], v[116:117], v[142:143]
	v_pk_mul_f32 v[118:119], v[118:119], v[144:145]
	v_pk_mul_f32 v[112:113], v[112:113], v[146:147]
	v_pk_mul_f32 v[114:115], v[114:115], v[148:149]
	v_cvt_pk_bf16_f32 v116, v116, v117
	v_cvt_pk_bf16_f32 v117, v118, v119
	v_cvt_pk_bf16_f32 v118, v112, v113
	v_cvt_pk_bf16_f32 v119, v114, v115
	v_add_u32_e32 v141, 0x0, v139
	global_store_dwordx4 v141, v[116:119], s[92:93] offset:256
	v_add_u32_e32 v140, 0x160000, v138
	global_load_dwordx4 v[166:169], v140, s[44:45]
	v_add_u32_e32 v140, 0x160000, v138
	global_load_dwordx4 v[112:115], v140, s[44:45] offset:256
	s_waitcnt vmcnt(15)
; __device__ __forceinline__ float bflo(unsigned w) { return __uint_as_float(w << 16); }
; __device__ __forceinline__ float bfhi(unsigned w) { return __uint_as_float(w & 0xffff0000u); }
; __device__ __forceinline__ u32x4 pack8u(f32x4 a, f32x4 b) { u32x4 w = {cvt_pk_bf16(a[0], a[1]), cvt_pk_bf16(a[2], a[3]), cvt_pk_bf16(b[0], b[1]), cvt_pk_bf16(b[2], b[3])}; return w; }
;     __device__ __forceinline__ void operator()(const AccT& acc, const Unit& u, int wr, int wc, int fr, int fq) const {
;     ...
;         for (int ai = 0; ai < 2; ++ai)
; #pragma unroll
;             for (int m = 0; m < 4; ++m) {
;                 const int row = u.pm * 256 + ai * 128 + wr * 64 + m * 16 + fr;
; #pragma unroll
;                 for (int bj = 0; bj < 2; ++bj) {
;                     const int c8 = u.pn * 256 + bj * 128 + wc * 32 + fq * 8;
;                     const u32x4 gw = *(const u32x4*)(GATE + (size_t)row * 4096 + SECOND * 2048 + c8);
;                     const f32x4 g0 = {bflo(gw[0]), bfhi(gw[0]), bflo(gw[1]), bfhi(gw[1])}, g1 = {bflo(gw[2]), bfhi(gw[2]), bflo(gw[3]), bfhi(gw[3])};
;                     bf16_t* tp = (bf16_t*)TMP + (size_t)row * 2048 + c8;
;                     if (SECOND == 0) { *(u32x4*)tp = pack8u(g0 * acc[ai][bj][m][0], g1 * acc[ai][bj][m][1]); }
	v_lshlrev_b32_e32 v142, 16, v170
	v_and_b32_e32 v143, 0xffff0000, v170
	v_lshlrev_b32_e32 v144, 16, v171
	v_and_b32_e32 v145, 0xffff0000, v171
	v_lshlrev_b32_e32 v146, 16, v172
	v_and_b32_e32 v147, 0xffff0000, v172
	v_lshlrev_b32_e32 v148, 16, v173
	v_and_b32_e32 v149, 0xffff0000, v173
	v_pk_mul_f32 v[108:109], v[108:109], v[142:143]
	v_pk_mul_f32 v[110:111], v[110:111], v[144:145]
	v_pk_mul_f32 v[104:105], v[104:105], v[146:147]
	v_pk_mul_f32 v[106:107], v[106:107], v[148:149]
	v_cvt_pk_bf16_f32 v108, v108, v109
	v_cvt_pk_bf16_f32 v109, v110, v111
	v_cvt_pk_bf16_f32 v110, v104, v105
	v_cvt_pk_bf16_f32 v111, v106, v107
	v_add_u32_e32 v141, 0x10000, v139
	global_store_dwordx4 v141, v[108:111], s[92:93]
	s_waitcnt vmcnt(15)
	v_lshlrev_b32_e32 v142, 16, v174
	v_and_b32_e32 v143, 0xffff0000, v174
	v_lshlrev_b32_e32 v144, 16, v175
	v_and_b32_e32 v145, 0xffff0000, v175
	v_lshlrev_b32_e32 v146, 16, v176
	v_and_b32_e32 v147, 0xffff0000, v176
	v_lshlrev_b32_e32 v148, 16, v177
	v_and_b32_e32 v149, 0xffff0000, v177
	v_pk_mul_f32 v[100:101], v[100:101], v[142:143]
	v_pk_mul_f32 v[102:103], v[102:103], v[144:145]
	v_pk_mul_f32 v[96:97], v[96:97], v[146:147]
	v_pk_mul_f32 v[98:99], v[98:99], v[148:149]
	v_cvt_pk_bf16_f32 v100, v100, v101
	v_cvt_pk_bf16_f32 v101, v102, v103
	v_cvt_pk_bf16_f32 v102, v96, v97
	v_cvt_pk_bf16_f32 v103, v98, v99
	v_add_u32_e32 v141, 0x10000, v139
	global_store_dwordx4 v141, v[100:103], s[92:93] offset:256
	s_waitcnt vmcnt(15)
	v_lshlrev_b32_e32 v142, 16, v178
	v_and_b32_e32 v143, 0xffff0000, v178
	v_lshlrev_b32_e32 v144, 16, v179
	v_and_b32_e32 v145, 0xffff0000, v179
	v_lshlrev_b32_e32 v146, 16, v180
	v_and_b32_e32 v147, 0xffff0000, v180
	v_lshlrev_b32_e32 v148, 16, v181
	v_and_b32_e32 v149, 0xffff0000, v181
	v_pk_mul_f32 v[92:93], v[92:93], v[142:143]
	v_pk_mul_f32 v[94:95], v[94:95], v[144:145]
	v_pk_mul_f32 v[88:89], v[88:89], v[146:147]
	v_pk_mul_f32 v[90:91], v[90:91], v[148:149]
	v_cvt_pk_bf16_f32 v92, v92, v93
	v_cvt_pk_bf16_f32 v93, v94, v95
	v_cvt_pk_bf16_f32 v94, v88, v89
	v_cvt_pk_bf16_f32 v95, v90, v91
	v_add_u32_e32 v141, 0x20000, v139
	global_store_dwordx4 v141, v[92:95], s[92:93]
	s_waitcnt vmcnt(15)
	v_lshlrev_b32_e32 v142, 16, v182
	v_and_b32_e32 v143, 0xffff0000, v182
	v_lshlrev_b32_e32 v144, 16, v183
	v_and_b32_e32 v145, 0xffff0000, v183
	v_lshlrev_b32_e32 v146, 16, v184
	v_and_b32_e32 v147, 0xffff0000, v184
	v_lshlrev_b32_e32 v148, 16, v185
	v_and_b32_e32 v149, 0xffff0000, v185
	v_pk_mul_f32 v[84:85], v[84:85], v[142:143]
	v_pk_mul_f32 v[86:87], v[86:87], v[144:145]
	v_pk_mul_f32 v[80:81], v[80:81], v[146:147]
	v_pk_mul_f32 v[82:83], v[82:83], v[148:149]
	v_cvt_pk_bf16_f32 v84, v84, v85
	v_cvt_pk_bf16_f32 v85, v86, v87
	v_cvt_pk_bf16_f32 v86, v80, v81
	v_cvt_pk_bf16_f32 v87, v82, v83
	v_add_u32_e32 v141, 0x20000, v139
	global_store_dwordx4 v141, v[84:87], s[92:93] offset:256
	s_waitcnt vmcnt(15)
	v_lshlrev_b32_e32 v142, 16, v186
	v_and_b32_e32 v143, 0xffff0000, v186
	v_lshlrev_b32_e32 v144, 16, v187
	v_and_b32_e32 v145, 0xffff0000, v187
	v_lshlrev_b32_e32 v146, 16, v188
	v_and_b32_e32 v147, 0xffff0000, v188
	v_lshlrev_b32_e32 v148, 16, v189
	v_and_b32_e32 v149, 0xffff0000, v189
	v_pk_mul_f32 v[76:77], v[76:77], v[142:143]
	v_pk_mul_f32 v[78:79], v[78:79], v[144:145]
	v_pk_mul_f32 v[72:73], v[72:73], v[146:147]
	v_pk_mul_f32 v[74:75], v[74:75], v[148:149]
	v_cvt_pk_bf16_f32 v76, v76, v77
	v_cvt_pk_bf16_f32 v77, v78, v79
	v_cvt_pk_bf16_f32 v78, v72, v73
	v_cvt_pk_bf16_f32 v79, v74, v75
	v_add_u32_e32 v141, 0x30000, v139
	global_store_dwordx4 v141, v[76:79], s[92:93]
	s_waitcnt vmcnt(15)
	v_lshlrev_b32_e32 v142, 16, v190
	v_and_b32_e32 v143, 0xffff0000, v190
	v_lshlrev_b32_e32 v144, 16, v191
	v_and_b32_e32 v145, 0xffff0000, v191
	v_lshlrev_b32_e32 v146, 16, v192
	v_and_b32_e32 v147, 0xffff0000, v192
	v_lshlrev_b32_e32 v148, 16, v193
	v_and_b32_e32 v149, 0xffff0000, v193
	v_pk_mul_f32 v[68:69], v[68:69], v[142:143]
	v_pk_mul_f32 v[70:71], v[70:71], v[144:145]
	v_pk_mul_f32 v[64:65], v[64:65], v[146:147]
	v_pk_mul_f32 v[66:67], v[66:67], v[148:149]
	v_cvt_pk_bf16_f32 v68, v68, v69
	v_cvt_pk_bf16_f32 v69, v70, v71
	v_cvt_pk_bf16_f32 v70, v64, v65
	v_cvt_pk_bf16_f32 v71, v66, v67
	v_add_u32_e32 v141, 0x30000, v139
	global_store_dwordx4 v141, v[68:71], s[92:93] offset:256
	s_waitcnt vmcnt(15)
	v_lshlrev_b32_e32 v142, 16, v194
	v_and_b32_e32 v143, 0xffff0000, v194
	v_lshlrev_b32_e32 v144, 16, v195
	v_and_b32_e32 v145, 0xffff0000, v195
	v_lshlrev_b32_e32 v146, 16, v196
	v_and_b32_e32 v147, 0xffff0000, v196
	v_lshlrev_b32_e32 v148, 16, v197
	v_and_b32_e32 v149, 0xffff0000, v197
	v_pk_mul_f32 v[60:61], v[60:61], v[142:143]
	v_pk_mul_f32 v[62:63], v[62:63], v[144:145]
	v_pk_mul_f32 v[56:57], v[56:57], v[146:147]
	v_pk_mul_f32 v[58:59], v[58:59], v[148:149]
	v_cvt_pk_bf16_f32 v60, v60, v61
	v_cvt_pk_bf16_f32 v61, v62, v63
	v_cvt_pk_bf16_f32 v62, v56, v57
	v_cvt_pk_bf16_f32 v63, v58, v59
	v_add_u32_e32 v141, 0x80000, v139
	global_store_dwordx4 v141, v[60:63], s[92:93]
	s_waitcnt vmcnt(15)
; __device__ __forceinline__ float bflo(unsigned w) { return __uint_as_float(w << 16); }
; __device__ __forceinline__ float bfhi(unsigned w) { return __uint_as_float(w & 0xffff0000u); }
; __device__ __forceinline__ u32x4 pack8u(f32x4 a, f32x4 b) { u32x4 w = {cvt_pk_bf16(a[0], a[1]), cvt_pk_bf16(a[2], a[3]), cvt_pk_bf16(b[0], b[1]), cvt_pk_bf16(b[2], b[3])}; return w; }
;     __device__ __forceinline__ void operator()(const AccT& acc, const Unit& u, int wr, int wc, int fr, int fq) const {
;     ...
;         for (int ai = 0; ai < 2; ++ai)
; #pragma unroll
;             for (int m = 0; m < 4; ++m) {
;                 const int row = u.pm * 256 + ai * 128 + wr * 64 + m * 16 + fr;
; #pragma unroll
;                 for (int bj = 0; bj < 2; ++bj) {
;                     const int c8 = u.pn * 256 + bj * 128 + wc * 32 + fq * 8;
;                     const u32x4 gw = *(const u32x4*)(GATE + (size_t)row * 4096 + SECOND * 2048 + c8);
;                     const f32x4 g0 = {bflo(gw[0]), bfhi(gw[0]), bflo(gw[1]), bfhi(gw[1])}, g1 = {bflo(gw[2]), bfhi(gw[2]), bflo(gw[3]), bfhi(gw[3])};
;                     bf16_t* tp = (bf16_t*)TMP + (size_t)row * 2048 + c8;
;                     if (SECOND == 0) { *(u32x4*)tp = pack8u(g0 * acc[ai][bj][m][0], g1 * acc[ai][bj][m][1]); }
	v_lshlrev_b32_e32 v142, 16, v198
	v_and_b32_e32 v143, 0xffff0000, v198
	v_lshlrev_b32_e32 v144, 16, v199
	v_and_b32_e32 v145, 0xffff0000, v199
	v_lshlrev_b32_e32 v146, 16, v200
	v_and_b32_e32 v147, 0xffff0000, v200
	v_lshlrev_b32_e32 v148, 16, v201
	v_and_b32_e32 v149, 0xffff0000, v201
	v_pk_mul_f32 v[52:53], v[52:53], v[142:143]
	v_pk_mul_f32 v[54:55], v[54:55], v[144:145]
	v_pk_mul_f32 v[48:49], v[48:49], v[146:147]
	v_pk_mul_f32 v[50:51], v[50:51], v[148:149]
	v_cvt_pk_bf16_f32 v52, v52, v53
	v_cvt_pk_bf16_f32 v53, v54, v55
	v_cvt_pk_bf16_f32 v54, v48, v49
	v_cvt_pk_bf16_f32 v55, v50, v51
	v_add_u32_e32 v141, 0x80000, v139
	global_store_dwordx4 v141, v[52:55], s[92:93] offset:256
	s_waitcnt vmcnt(15)
	v_lshlrev_b32_e32 v142, 16, v202
	v_and_b32_e32 v143, 0xffff0000, v202
	v_lshlrev_b32_e32 v144, 16, v203
	v_and_b32_e32 v145, 0xffff0000, v203
	v_lshlrev_b32_e32 v146, 16, v204
	v_and_b32_e32 v147, 0xffff0000, v204
	v_lshlrev_b32_e32 v148, 16, v205
	v_and_b32_e32 v149, 0xffff0000, v205
	v_pk_mul_f32 v[44:45], v[44:45], v[142:143]
	v_pk_mul_f32 v[46:47], v[46:47], v[144:145]
	v_pk_mul_f32 v[40:41], v[40:41], v[146:147]
	v_pk_mul_f32 v[42:43], v[42:43], v[148:149]
	v_cvt_pk_bf16_f32 v44, v44, v45
	v_cvt_pk_bf16_f32 v45, v46, v47
	v_cvt_pk_bf16_f32 v46, v40, v41
	v_cvt_pk_bf16_f32 v47, v42, v43
	v_add_u32_e32 v141, 0x90000, v139
	global_store_dwordx4 v141, v[44:47], s[92:93]
	s_waitcnt vmcnt(15)
	v_lshlrev_b32_e32 v142, 16, v228
	v_and_b32_e32 v143, 0xffff0000, v228
	v_lshlrev_b32_e32 v144, 16, v229
	v_and_b32_e32 v145, 0xffff0000, v229
	v_lshlrev_b32_e32 v146, 16, v230
	v_and_b32_e32 v147, 0xffff0000, v230
	v_lshlrev_b32_e32 v148, 16, v231
	v_and_b32_e32 v149, 0xffff0000, v231
	v_pk_mul_f32 v[36:37], v[36:37], v[142:143]
	v_pk_mul_f32 v[38:39], v[38:39], v[144:145]
	v_pk_mul_f32 v[32:33], v[32:33], v[146:147]
	v_pk_mul_f32 v[34:35], v[34:35], v[148:149]
	v_cvt_pk_bf16_f32 v36, v36, v37
	v_cvt_pk_bf16_f32 v37, v38, v39
	v_cvt_pk_bf16_f32 v38, v32, v33
	v_cvt_pk_bf16_f32 v39, v34, v35
	v_add_u32_e32 v141, 0x90000, v139
	global_store_dwordx4 v141, v[36:39], s[92:93] offset:256
	s_waitcnt vmcnt(14)
	v_lshlrev_b32_e32 v142, 16, v162
	v_and_b32_e32 v143, 0xffff0000, v162
	v_lshlrev_b32_e32 v144, 16, v163
	v_and_b32_e32 v145, 0xffff0000, v163
	v_lshlrev_b32_e32 v146, 16, v164
	v_and_b32_e32 v147, 0xffff0000, v164
	v_lshlrev_b32_e32 v148, 16, v165
	v_and_b32_e32 v149, 0xffff0000, v165
	v_pk_mul_f32 v[28:29], v[28:29], v[142:143]
	v_pk_mul_f32 v[30:31], v[30:31], v[144:145]
	v_pk_mul_f32 v[24:25], v[24:25], v[146:147]
	v_pk_mul_f32 v[26:27], v[26:27], v[148:149]
	v_cvt_pk_bf16_f32 v28, v28, v29
	v_cvt_pk_bf16_f32 v29, v30, v31
	v_cvt_pk_bf16_f32 v30, v24, v25
	v_cvt_pk_bf16_f32 v31, v26, v27
	v_add_u32_e32 v141, 0xa0000, v139
	global_store_dwordx4 v141, v[28:31], s[92:93]
	s_waitcnt vmcnt(14)
	v_lshlrev_b32_e32 v142, 16, v120
	v_and_b32_e32 v143, 0xffff0000, v120
	v_lshlrev_b32_e32 v144, 16, v121
	v_and_b32_e32 v145, 0xffff0000, v121
	v_lshlrev_b32_e32 v146, 16, v122
	v_and_b32_e32 v147, 0xffff0000, v122
	v_lshlrev_b32_e32 v148, 16, v123
	v_and_b32_e32 v149, 0xffff0000, v123
	v_pk_mul_f32 v[20:21], v[20:21], v[142:143]
	v_pk_mul_f32 v[22:23], v[22:23], v[144:145]
	v_pk_mul_f32 v[16:17], v[16:17], v[146:147]
	v_pk_mul_f32 v[18:19], v[18:19], v[148:149]
	v_cvt_pk_bf16_f32 v20, v20, v21
	v_cvt_pk_bf16_f32 v21, v22, v23
	v_cvt_pk_bf16_f32 v22, v16, v17
	v_cvt_pk_bf16_f32 v23, v18, v19
	v_add_u32_e32 v141, 0xa0000, v139
	global_store_dwordx4 v141, v[20:23], s[92:93] offset:256
	s_waitcnt vmcnt(13)
	v_lshlrev_b32_e32 v142, 16, v166
	v_and_b32_e32 v143, 0xffff0000, v166
	v_lshlrev_b32_e32 v144, 16, v167
	v_and_b32_e32 v145, 0xffff0000, v167
	v_lshlrev_b32_e32 v146, 16, v168
	v_and_b32_e32 v147, 0xffff0000, v168
	v_lshlrev_b32_e32 v148, 16, v169
	v_and_b32_e32 v149, 0xffff0000, v169
	v_pk_mul_f32 v[12:13], v[12:13], v[142:143]
	v_pk_mul_f32 v[14:15], v[14:15], v[144:145]
	v_pk_mul_f32 v[8:9], v[8:9], v[146:147]
	v_pk_mul_f32 v[10:11], v[10:11], v[148:149]
	v_cvt_pk_bf16_f32 v12, v12, v13
	v_cvt_pk_bf16_f32 v13, v14, v15
	v_cvt_pk_bf16_f32 v14, v8, v9
	v_cvt_pk_bf16_f32 v15, v10, v11
	v_add_u32_e32 v141, 0xb0000, v139
	global_store_dwordx4 v141, v[12:15], s[92:93]
	s_waitcnt vmcnt(13)
	v_lshlrev_b32_e32 v142, 16, v112
	v_and_b32_e32 v143, 0xffff0000, v112
	v_lshlrev_b32_e32 v144, 16, v113
	v_and_b32_e32 v145, 0xffff0000, v113
	v_lshlrev_b32_e32 v146, 16, v114
	v_and_b32_e32 v147, 0xffff0000, v114
	v_lshlrev_b32_e32 v148, 16, v115
	v_and_b32_e32 v149, 0xffff0000, v115
	v_pk_mul_f32 v[4:5], v[4:5], v[142:143]
	v_pk_mul_f32 v[6:7], v[6:7], v[144:145]
	v_pk_mul_f32 v[0:1], v[0:1], v[146:147]
	v_pk_mul_f32 v[2:3], v[2:3], v[148:149]
	v_cvt_pk_bf16_f32 v4, v4, v5
	v_cvt_pk_bf16_f32 v5, v6, v7
	v_cvt_pk_bf16_f32 v6, v0, v1
	v_cvt_pk_bf16_f32 v7, v2, v3
	v_add_u32_e32 v141, 0xb0000, v139
	global_store_dwordx4 v141, v[4:7], s[92:93] offset:256
	s_mov_b64 s[26:27], -1
	s_mov_b64 s[42:43], exec
	s_mov_b64 vcc, 0
	s_branch .LBB0_203

; #define PG8_STAGE(bufoff, gbase, voff) do { _Pragma("unroll") for (int _i = 0; _i < 2; ++_i) \
;         __builtin_amdgcn_global_load_lds((const unsigned*)((const char*)(gbase) + (voff)[_i]), (LAS unsigned*)(lds + (bufoff) + ldsw + _i * 8192), 16, 0, 0); } while (0)
; #define PG8_LDA(dst, b, h) do { _Pragma("unroll") for (int m = 0; m < 4; ++m) _Pragma("unroll") for (int k = 0; k < 2; ++k) dst[m][k] = *(const LAS bf16x8*)(lds + PG8_SA(b, h) + aoff + m * 2048 + k * 1024); } while (0)
; #define PG8_LDB(dst, b, h) do { _Pragma("unroll") for (int n = 0; n < 2; ++n) _Pragma("unroll") for (int k = 0; k < 2; ++k) dst[n][k] = *(const LAS bf16x8*)(lds + PG8_SB(b, h) + boff + n * 2048 + k * 1024); } while (0)
; #define PG8_MMA(ai, bj, At, Bt) do { __builtin_amdgcn_s_setprio(1); _Pragma("unroll") for (int m = 0; m < 4; ++m) _Pragma("unroll") for (int n = 0; n < 2; ++n) _Pragma("unroll") for (int k = 0; k < 2; ++k) \
;         acc[ai][bj][m][n] = __builtin_amdgcn_mfma_f32_16x16x32_bf16(Bt[n][k], At[m][k], acc[ai][bj][m][n], 0, 0, 0); __builtin_amdgcn_s_setprio(0); } while (0)
; #define PG8_WAIT_V(n) asm volatile("s_waitcnt vmcnt(" #n ")" ::: "memory")
; #define PG8_WAIT_L(n) asm volatile("s_waitcnt lgkmcnt(" #n ")" ::: "memory")
; #define PG8_BAR __builtin_amdgcn_s_barrier()
; #define PG8_SCHED __builtin_amdgcn_sched_barrier(0)
; template <class Epi>
; __device__ __forceinline__ void gemm_phase(LAS unsigned char* lds, const Gemm g, const Epi& E) {
;     ...
;             PG8_LDB(B0, 0, 0); PG8_SCHED; PG8_LDA(At, 0, 0); PG8_STAGE(PG8_SA(1, 1), a1 + hstep, voffA);
;             PG8_WAIT_L(8); PG8_BAR; PG8_WAIT_L(0); PG8_MMA(0, 0, At, B0); PG8_BAR; PG8_SCHED;
;             PG8_LDB(B1, 0, 1); PG8_STAGE(PG8_SB(0, 0), b2, voffB);
;             PG8_BAR; PG8_WAIT_L(0); PG8_MMA(0, 1, At, B1); PG8_BAR;
;             PG8_LDA(At, 0, 1); PG8_STAGE(PG8_SA(0, 0), a2, voffA);
;             PG8_BAR; PG8_WAIT_L(0); PG8_MMA(1, 0, At, B0); PG8_BAR; PG8_SCHED;
;             PG8_STAGE(PG8_SB(0, 1), b2 + hstep, voffB);
;             PG8_WAIT_V(6); PG8_BAR; PG8_MMA(1, 1, At, B1); PG8_BAR;
.LBB0_499:
	s_add_u32 s28, s26, 0xfffe0080
	s_addc_u32 s29, s27, -1
	s_add_i32 s34, 0, 0x10000
	v_add_u32_e32 v156, s34, v159
	ds_read_b128 v[144:147], v156
	ds_read_b128 v[148:151], v156 offset:1024
	ds_read_b128 v[152:155], v156 offset:2048
	ds_read_b128 v[162:165], v156 offset:3072
	s_cmp_eq_u32 vcc_lo, 4
	s_cselect_b32 s37, s1, s29
	s_cselect_b32 s36, s31, s28
	s_cselect_b32 s29, s42, s65
	s_cselect_b32 s28, s43, s45
	s_add_i32 m0, s95, 0xc000
	ds_read_b128 v[166:169], v161
	ds_read_b128 v[170:173], v161 offset:1024
	ds_read_b128 v[174:177], v161 offset:2048
	ds_read_b128 v[178:181], v161 offset:3072
	ds_read_b128 v[182:185], v161 offset:4096
	ds_read_b128 v[186:189], v161 offset:5120
	ds_read_b128 v[190:193], v161 offset:6144
	ds_read_b128 v[194:197], v161 offset:7168
	global_load_lds_dwordx4 v140, s[26:27]
	s_add_i32 m0, s95, 0xe000
	s_nop 0
	global_load_lds_dwordx4 v142, s[26:27]
	s_waitcnt lgkmcnt(8)
	s_barrier
	s_waitcnt lgkmcnt(0)
	v_mfma_f32_16x16x32_bf16 v[124:127], v[144:147], v[166:169], v[124:127]
	v_mfma_f32_16x16x32_bf16 v[120:123], v[152:155], v[166:169], v[120:123]
	v_mfma_f32_16x16x32_bf16 v[108:111], v[144:147], v[174:177], v[108:111]
	v_mfma_f32_16x16x32_bf16 v[104:107], v[152:155], v[174:177], v[104:107]
	v_mfma_f32_16x16x32_bf16 v[92:95], v[144:147], v[182:185], v[92:95]
	v_mfma_f32_16x16x32_bf16 v[88:91], v[152:155], v[182:185], v[88:91]
	v_mfma_f32_16x16x32_bf16 v[76:79], v[144:147], v[190:193], v[76:79]
	v_mfma_f32_16x16x32_bf16 v[72:75], v[152:155], v[190:193], v[72:75]
	v_mfma_f32_16x16x32_bf16 v[124:127], v[148:151], v[170:173], v[124:127]
	v_mfma_f32_16x16x32_bf16 v[120:123], v[162:165], v[170:173], v[120:123]
	v_mfma_f32_16x16x32_bf16 v[108:111], v[148:151], v[178:181], v[108:111]
	v_mfma_f32_16x16x32_bf16 v[104:107], v[162:165], v[178:181], v[104:107]
	v_mfma_f32_16x16x32_bf16 v[92:95], v[148:151], v[186:189], v[92:95]
	v_mfma_f32_16x16x32_bf16 v[88:91], v[162:165], v[186:189], v[88:91]
	v_mfma_f32_16x16x32_bf16 v[76:79], v[148:151], v[194:197], v[76:79]
	v_mfma_f32_16x16x32_bf16 v[72:75], v[162:165], v[194:197], v[72:75]
	s_barrier
	s_add_i32 vcc_hi, 0, 0x14000
	v_add_u32_e32 v156, vcc_hi, v159
	s_add_i32 s34, s34, s83
	ds_read_b128 v[198:201], v156
	ds_read_b128 v[202:205], v156 offset:1024
	ds_read_b128 v[238:241], v156 offset:2048
	ds_read_b128 v[242:245], v156 offset:3072
	s_mov_b32 m0, s34
	s_nop 0
	global_load_lds_dwordx4 v130, s[28:29]
	s_add_i32 m0, s34, 0x2000
	s_nop 0
	global_load_lds_dwordx4 v134, s[28:29]
	s_barrier
	s_waitcnt lgkmcnt(0)
	v_mfma_f32_16x16x32_bf16 v[116:119], v[198:201], v[166:169], v[116:119]
	v_mfma_f32_16x16x32_bf16 v[112:115], v[238:241], v[166:169], v[112:115]
	v_mfma_f32_16x16x32_bf16 v[100:103], v[198:201], v[174:177], v[100:103]
	v_mfma_f32_16x16x32_bf16 v[96:99], v[238:241], v[174:177], v[96:99]
	v_mfma_f32_16x16x32_bf16 v[84:87], v[198:201], v[182:185], v[84:87]
	v_mfma_f32_16x16x32_bf16 v[80:83], v[238:241], v[182:185], v[80:83]
	v_mfma_f32_16x16x32_bf16 v[68:71], v[198:201], v[190:193], v[68:71]
	v_mfma_f32_16x16x32_bf16 v[64:67], v[238:241], v[190:193], v[64:67]
	v_mfma_f32_16x16x32_bf16 v[116:119], v[202:205], v[170:173], v[116:119]
	v_mfma_f32_16x16x32_bf16 v[112:115], v[242:245], v[170:173], v[112:115]
	v_mfma_f32_16x16x32_bf16 v[100:103], v[202:205], v[178:181], v[100:103]
	v_mfma_f32_16x16x32_bf16 v[96:99], v[242:245], v[178:181], v[96:99]
	v_mfma_f32_16x16x32_bf16 v[84:87], v[202:205], v[186:189], v[84:87]
	v_mfma_f32_16x16x32_bf16 v[80:83], v[242:245], v[186:189], v[80:83]
	v_mfma_f32_16x16x32_bf16 v[68:71], v[202:205], v[194:197], v[68:71]
	v_mfma_f32_16x16x32_bf16 v[64:67], v[242:245], v[194:197], v[64:67]
	s_barrier
	s_mov_b32 m0, s95
	ds_read_b128 v[166:169], v161 offset:16384
	ds_read_b128 v[170:173], v161 offset:17408
	ds_read_b128 v[174:177], v161 offset:18432
	ds_read_b128 v[178:181], v161 offset:19456
	ds_read_b128 v[182:185], v161 offset:20480
	ds_read_b128 v[186:189], v161 offset:21504
	ds_read_b128 v[190:193], v161 offset:22528
	ds_read_b128 v[194:197], v161 offset:23552
	global_load_lds_dwordx4 v128, s[36:37]
	s_mov_b32 m0, s82
	s_nop 0
	global_load_lds_dwordx4 v132, s[36:37]
	s_barrier
	s_waitcnt lgkmcnt(0)
	v_mfma_f32_16x16x32_bf16 v[60:63], v[144:147], v[166:169], v[60:63]
	v_mfma_f32_16x16x32_bf16 v[56:59], v[152:155], v[166:169], v[56:59]
	v_mfma_f32_16x16x32_bf16 v[44:47], v[144:147], v[174:177], v[44:47]
	v_mfma_f32_16x16x32_bf16 v[40:43], v[152:155], v[174:177], v[40:43]
	v_mfma_f32_16x16x32_bf16 v[28:31], v[144:147], v[182:185], v[28:31]
	v_mfma_f32_16x16x32_bf16 v[24:27], v[152:155], v[182:185], v[24:27]
	v_mfma_f32_16x16x32_bf16 v[12:15], v[144:147], v[190:193], v[12:15]
	v_mfma_f32_16x16x32_bf16 v[8:11], v[152:155], v[190:193], v[8:11]
	v_mfma_f32_16x16x32_bf16 v[60:63], v[148:151], v[170:173], v[60:63]
	v_mfma_f32_16x16x32_bf16 v[56:59], v[162:165], v[170:173], v[56:59]
	v_mfma_f32_16x16x32_bf16 v[44:47], v[148:151], v[178:181], v[44:47]
	v_mfma_f32_16x16x32_bf16 v[40:43], v[162:165], v[178:181], v[40:43]
	v_mfma_f32_16x16x32_bf16 v[28:31], v[148:151], v[186:189], v[28:31]
	v_mfma_f32_16x16x32_bf16 v[24:27], v[162:165], v[186:189], v[24:27]
	v_mfma_f32_16x16x32_bf16 v[12:15], v[148:151], v[194:197], v[12:15]
	v_mfma_f32_16x16x32_bf16 v[8:11], v[162:165], v[194:197], v[8:11]
	s_barrier
	s_add_u32 s34, s28, 0x20000
	s_addc_u32 s35, s29, 0
	s_add_i32 vcc_hi, vcc_hi, s83
	s_mov_b32 m0, vcc_hi
	s_nop 0
	global_load_lds_dwordx4 v130, s[34:35]
	s_add_i32 m0, vcc_hi, 0x2000
	s_nop 0
	global_load_lds_dwordx4 v134, s[34:35]
	s_waitcnt vmcnt(6)
	s_barrier
; #define PG8_STAGE(bufoff, gbase, voff) do { _Pragma("unroll") for (int _i = 0; _i < 2; ++_i) \
;         __builtin_amdgcn_global_load_lds((const unsigned*)((const char*)(gbase) + (voff)[_i]), (LAS unsigned*)(lds + (bufoff) + ldsw + _i * 8192), 16, 0, 0); } while (0)
; #define PG8_LDA(dst, b, h) do { _Pragma("unroll") for (int m = 0; m < 4; ++m) _Pragma("unroll") for (int k = 0; k < 2; ++k) dst[m][k] = *(const LAS bf16x8*)(lds + PG8_SA(b, h) + aoff + m * 2048 + k * 1024); } while (0)
; #define PG8_LDB(dst, b, h) do { _Pragma("unroll") for (int n = 0; n < 2; ++n) _Pragma("unroll") for (int k = 0; k < 2; ++k) dst[n][k] = *(const LAS bf16x8*)(lds + PG8_SB(b, h) + boff + n * 2048 + k * 1024); } while (0)
; #define PG8_MMA(ai, bj, At, Bt) do { __builtin_amdgcn_s_setprio(1); _Pragma("unroll") for (int m = 0; m < 4; ++m) _Pragma("unroll") for (int n = 0; n < 2; ++n) _Pragma("unroll") for (int k = 0; k < 2; ++k) \
;         acc[ai][bj][m][n] = __builtin_amdgcn_mfma_f32_16x16x32_bf16(Bt[n][k], At[m][k], acc[ai][bj][m][n], 0, 0, 0); __builtin_amdgcn_s_setprio(0); } while (0)
; #define PG8_WAIT_V(n) asm volatile("s_waitcnt vmcnt(" #n ")" ::: "memory")
; #define PG8_WAIT_L(n) asm volatile("s_waitcnt lgkmcnt(" #n ")" ::: "memory")
; #define PG8_BAR __builtin_amdgcn_s_barrier()
; #define PG8_SCHED __builtin_amdgcn_sched_barrier(0)
; template <class Epi>
; __device__ __forceinline__ void gemm_phase(LAS unsigned char* lds, const Gemm g, const Epi& E) {
;     ...
;             PG8_WAIT_V(6); PG8_BAR; PG8_MMA(1, 1, At, B1); PG8_BAR;
;             PG8_LDB(B0, 1, 0); PG8_SCHED; PG8_LDA(At, 1, 0); PG8_STAGE(PG8_SA(0, 1), a2 + hstep, voffA);
;             PG8_WAIT_L(8); PG8_BAR; PG8_WAIT_L(0); PG8_MMA(0, 0, At, B0); PG8_BAR; PG8_SCHED;
;             PG8_LDB(B1, 1, 1); PG8_STAGE(PG8_SB(1, 0), b3, voffB);
;             PG8_BAR; PG8_WAIT_L(0); PG8_MMA(0, 1, At, B1); PG8_BAR;
;             PG8_LDA(At, 1, 1); PG8_STAGE(PG8_SA(1, 0), a3, voffA);
;             PG8_BAR; PG8_WAIT_L(0); PG8_MMA(1, 0, At, B0); PG8_BAR; PG8_SCHED;
	v_mfma_f32_16x16x32_bf16 v[52:55], v[198:201], v[166:169], v[52:55]
	v_mfma_f32_16x16x32_bf16 v[48:51], v[238:241], v[166:169], v[48:51]
	v_mfma_f32_16x16x32_bf16 v[36:39], v[198:201], v[174:177], v[36:39]
	v_mfma_f32_16x16x32_bf16 v[32:35], v[238:241], v[174:177], v[32:35]
	v_mfma_f32_16x16x32_bf16 v[20:23], v[198:201], v[182:185], v[20:23]
	v_mfma_f32_16x16x32_bf16 v[16:19], v[238:241], v[182:185], v[16:19]
	v_mfma_f32_16x16x32_bf16 v[4:7], v[198:201], v[190:193], v[4:7]
	v_mfma_f32_16x16x32_bf16 v[0:3], v[238:241], v[190:193], v[0:3]
	v_mfma_f32_16x16x32_bf16 v[52:55], v[202:205], v[170:173], v[52:55]
	v_mfma_f32_16x16x32_bf16 v[48:51], v[242:245], v[170:173], v[48:51]
	v_mfma_f32_16x16x32_bf16 v[36:39], v[202:205], v[178:181], v[36:39]
	v_mfma_f32_16x16x32_bf16 v[32:35], v[242:245], v[178:181], v[32:35]
	v_mfma_f32_16x16x32_bf16 v[20:23], v[202:205], v[186:189], v[20:23]
	v_mfma_f32_16x16x32_bf16 v[16:19], v[242:245], v[186:189], v[16:19]
	v_mfma_f32_16x16x32_bf16 v[4:7], v[202:205], v[194:197], v[4:7]
	v_mfma_f32_16x16x32_bf16 v[0:3], v[242:245], v[194:197], v[0:3]
	s_barrier
	s_add_i32 vcc_hi, 0, 0x18000
	v_add_u32_e32 v162, vcc_hi, v159
	ds_read_b128 v[144:147], v162
	ds_read_b128 v[148:151], v162 offset:1024
	ds_read_b128 v[152:155], v162 offset:2048
	ds_read_b128 v[162:165], v162 offset:3072
	s_add_u32 s34, s36, 0x20000
	s_addc_u32 s35, s37, 0
	s_mov_b32 m0, s78
	ds_read_b128 v[166:169], v161 offset:32768
	ds_read_b128 v[170:173], v161 offset:33792
	ds_read_b128 v[174:177], v161 offset:34816
	ds_read_b128 v[178:181], v161 offset:35840
	ds_read_b128 v[182:185], v161 offset:36864
	ds_read_b128 v[186:189], v161 offset:37888
	ds_read_b128 v[190:193], v161 offset:38912
	ds_read_b128 v[194:197], v161 offset:39936
	global_load_lds_dwordx4 v128, s[34:35]
	s_mov_b32 m0, s76
	s_nop 0
	global_load_lds_dwordx4 v132, s[34:35]
	s_waitcnt lgkmcnt(8)
	s_barrier
	s_waitcnt lgkmcnt(0)
	v_mfma_f32_16x16x32_bf16 v[124:127], v[144:147], v[166:169], v[124:127]
	v_mfma_f32_16x16x32_bf16 v[120:123], v[152:155], v[166:169], v[120:123]
	v_mfma_f32_16x16x32_bf16 v[108:111], v[144:147], v[174:177], v[108:111]
	v_mfma_f32_16x16x32_bf16 v[104:107], v[152:155], v[174:177], v[104:107]
	v_mfma_f32_16x16x32_bf16 v[92:95], v[144:147], v[182:185], v[92:95]
	v_mfma_f32_16x16x32_bf16 v[88:91], v[152:155], v[182:185], v[88:91]
	v_mfma_f32_16x16x32_bf16 v[76:79], v[144:147], v[190:193], v[76:79]
	v_mfma_f32_16x16x32_bf16 v[72:75], v[152:155], v[190:193], v[72:75]
	v_mfma_f32_16x16x32_bf16 v[124:127], v[148:151], v[170:173], v[124:127]
	v_mfma_f32_16x16x32_bf16 v[120:123], v[162:165], v[170:173], v[120:123]
	v_mfma_f32_16x16x32_bf16 v[108:111], v[148:151], v[178:181], v[108:111]
	v_mfma_f32_16x16x32_bf16 v[104:107], v[162:165], v[178:181], v[104:107]
	v_mfma_f32_16x16x32_bf16 v[92:95], v[148:151], v[186:189], v[92:95]
	v_mfma_f32_16x16x32_bf16 v[88:91], v[162:165], v[186:189], v[88:91]
	v_mfma_f32_16x16x32_bf16 v[76:79], v[148:151], v[194:197], v[76:79]
	v_mfma_f32_16x16x32_bf16 v[72:75], v[162:165], v[194:197], v[72:75]
	s_barrier
	s_add_i32 s34, 0, 0x1c000
	s_add_i32 s35, vcc_hi, s83
	v_add_u32_e32 v208, s34, v159
	s_mov_b32 m0, s35
	ds_read_b128 v[198:201], v208
	ds_read_b128 v[202:205], v208 offset:1024
	ds_read_b128 v[238:241], v208 offset:2048
	ds_read_b128 v[242:245], v208 offset:3072
	s_add_u32 s98, s28, 0x80
	s_addc_u32 s99, s29, 0
	global_load_lds_dwordx4 v130, s[98:99]
	s_add_i32 m0, s35, 0x2000
	s_add_u32 s100, s28, 0x80
	s_addc_u32 s101, s29, 0
	global_load_lds_dwordx4 v134, s[100:101]
	s_barrier
	s_waitcnt lgkmcnt(0)
	v_mfma_f32_16x16x32_bf16 v[116:119], v[198:201], v[166:169], v[116:119]
	v_mfma_f32_16x16x32_bf16 v[112:115], v[238:241], v[166:169], v[112:115]
	v_mfma_f32_16x16x32_bf16 v[100:103], v[198:201], v[174:177], v[100:103]
	v_mfma_f32_16x16x32_bf16 v[96:99], v[238:241], v[174:177], v[96:99]
	v_mfma_f32_16x16x32_bf16 v[84:87], v[198:201], v[182:185], v[84:87]
	v_mfma_f32_16x16x32_bf16 v[80:83], v[238:241], v[182:185], v[80:83]
	v_mfma_f32_16x16x32_bf16 v[68:71], v[198:201], v[190:193], v[68:71]
	v_mfma_f32_16x16x32_bf16 v[64:67], v[238:241], v[190:193], v[64:67]
	v_mfma_f32_16x16x32_bf16 v[116:119], v[202:205], v[170:173], v[116:119]
	v_mfma_f32_16x16x32_bf16 v[112:115], v[242:245], v[170:173], v[112:115]
	v_mfma_f32_16x16x32_bf16 v[100:103], v[202:205], v[178:181], v[100:103]
	v_mfma_f32_16x16x32_bf16 v[96:99], v[242:245], v[178:181], v[96:99]
	v_mfma_f32_16x16x32_bf16 v[84:87], v[202:205], v[186:189], v[84:87]
	v_mfma_f32_16x16x32_bf16 v[80:83], v[242:245], v[186:189], v[80:83]
	v_mfma_f32_16x16x32_bf16 v[68:71], v[202:205], v[194:197], v[68:71]
	v_mfma_f32_16x16x32_bf16 v[64:67], v[242:245], v[194:197], v[64:67]
	s_barrier
	s_mov_b32 m0, s68
	ds_read_b128 v[166:169], v161 offset:49152
	ds_read_b128 v[170:173], v161 offset:50176
	ds_read_b128 v[174:177], v161 offset:51200
	ds_read_b128 v[178:181], v161 offset:52224
	ds_read_b128 v[182:185], v161 offset:53248
	ds_read_b128 v[186:189], v161 offset:54272
	ds_read_b128 v[190:193], v161 offset:55296
	ds_read_b128 v[194:197], v161 offset:56320
	s_add_u32 s98, s36, 0x80
	s_addc_u32 s99, s37, 0
	global_load_lds_dwordx4 v128, s[98:99]
	s_mov_b32 m0, s74
	s_add_u32 s100, s36, 0x80
	s_addc_u32 s101, s37, 0
	global_load_lds_dwordx4 v132, s[100:101]
	s_barrier
; template <class Epi>
; __device__ __forceinline__ void gemm_phase(LAS unsigned char* lds, const Gemm g, const Epi& E) {
;     ...
;             PG8_BAR; PG8_WAIT_L(0); PG8_MMA(1, 0, At, B0); PG8_BAR; PG8_SCHED;
;             PG8_STAGE(PG8_SB(1, 1), b3 + hstep, voffB);
;             PG8_WAIT_V(6); PG8_BAR; PG8_MMA(1, 1, At, B1); PG8_BAR;
;         }
;     __device__ __forceinline__ void operator()(const AccT& acc, const Unit& u, int wr, int wc, int fr, int fq) const {
; #pragma unroll
;         for (int ai = 0; ai < 2; ++ai)
; #pragma unroll
;             for (int m = 0; m < 4; ++m) {
;                 const int row = u.pm * 256 + ai * 128 + wr * 64 + m * 16 + fr; const int b = row / SEQ, t = row % SEQ;
;                 const f32x4 s0 = *(const f32x4*)(SSQ + (size_t)row * 16 + mode * 8), s1 = *(const f32x4*)(SSQ + (size_t)row * 16 + mode * 8 + 4);
;                 const float ssq = (s0[0] + s0[1]) + (s0[2] + s0[3]) + (s1[0] + s1[1]) + (s1[2] + s1[3]);
;                 float rs = rsqrtf(ssq * (1.0f / 512.0f) + EPS);
;                 if (mode == 0) {
;                     rs *= (0.07216878364870322f * 1.4426950408889634f);
; #pragma unroll
;                     for (int bj = 0; bj < 2; ++bj) {
;                         const int c8 = u.pn * 256 + bj * 128 + wc * 32 + fq * 8; const int head = c8 / DQK, d0 = c8 % DQK;
;                         bf16_t* qp = Q + ((size_t)(b * NH + head) * SEQ + t) * DQK;
;                         const f32x4 v0 = acc[ai][bj][m][0] * rs, v1 = acc[ai][bj][m][1] * rs;
;                         if (d0 < 128) { *(u32x4*)(qp + d0) = pack8u(v0, v1); }
;                         else { const int i0 = 4 * ((d0 - 128) >> 3);
;                             const f32x4 cs = *(const f32x4*)(COS + (size_t)row * 32 + i0), sn = *(const f32x4*)(SIN + (size_t)row * 32 + i0);
;                             const f32x4 o1 = v0 * cs - v1 * sn, o2 = v1 * cs + v0 * sn;
;                             *(u32x2*)(qp + 128 + i0) = pack4u(o1); *(u32x2*)(qp + 160 + i0) = pack4u(o2); }
;                     }
;                 } else {
;                     const size_t bh = (size_t)(b * NH + u.pn) * SEQ + t; const int d = wc * 32 + fq * 8;
;                     *(u32x4*)(Kb + bh * DQK + d) = pack8u(acc[ai][0][m][0] * rs, acc[ai][0][m][1] * rs);
;                     *(u32x4*)(Vb + bh * 128 + d) = pack8u(acc[ai][1][m][0] * rs, acc[ai][1][m][1] * rs);
	s_waitcnt lgkmcnt(0)
	v_mfma_f32_16x16x32_bf16 v[60:63], v[144:147], v[166:169], v[60:63]
	v_mfma_f32_16x16x32_bf16 v[56:59], v[152:155], v[166:169], v[56:59]
	v_mfma_f32_16x16x32_bf16 v[44:47], v[144:147], v[174:177], v[44:47]
	v_mfma_f32_16x16x32_bf16 v[40:43], v[152:155], v[174:177], v[40:43]
	v_mfma_f32_16x16x32_bf16 v[28:31], v[144:147], v[182:185], v[28:31]
	v_mfma_f32_16x16x32_bf16 v[24:27], v[152:155], v[182:185], v[24:27]
	v_mfma_f32_16x16x32_bf16 v[12:15], v[144:147], v[190:193], v[12:15]
	v_mfma_f32_16x16x32_bf16 v[8:11], v[152:155], v[190:193], v[8:11]
	v_mfma_f32_16x16x32_bf16 v[60:63], v[148:151], v[170:173], v[60:63]
	v_mfma_f32_16x16x32_bf16 v[56:59], v[162:165], v[170:173], v[56:59]
	v_mfma_f32_16x16x32_bf16 v[44:47], v[148:151], v[178:181], v[44:47]
	v_mfma_f32_16x16x32_bf16 v[40:43], v[162:165], v[178:181], v[40:43]
	v_mfma_f32_16x16x32_bf16 v[28:31], v[148:151], v[186:189], v[28:31]
	v_mfma_f32_16x16x32_bf16 v[24:27], v[162:165], v[186:189], v[24:27]
	v_mfma_f32_16x16x32_bf16 v[12:15], v[148:151], v[194:197], v[12:15]
	v_mfma_f32_16x16x32_bf16 v[8:11], v[162:165], v[194:197], v[8:11]
	s_barrier
	s_add_u32 s28, s28, 0x20080
	s_addc_u32 s29, s29, 0
	s_add_i32 s34, s34, s83
	s_mov_b32 m0, s34
	s_nop 0
	global_load_lds_dwordx4 v130, s[28:29]
	s_add_i32 m0, s34, 0x2000
	s_nop 0
	global_load_lds_dwordx4 v134, s[28:29]
	s_waitcnt vmcnt(6)
	s_barrier
	v_mfma_f32_16x16x32_bf16 v[52:55], v[198:201], v[166:169], v[52:55]
	v_mfma_f32_16x16x32_bf16 v[48:51], v[238:241], v[166:169], v[48:51]
	v_mfma_f32_16x16x32_bf16 v[36:39], v[198:201], v[174:177], v[36:39]
	v_mfma_f32_16x16x32_bf16 v[32:35], v[238:241], v[174:177], v[32:35]
	v_mfma_f32_16x16x32_bf16 v[20:23], v[198:201], v[182:185], v[20:23]
	v_mfma_f32_16x16x32_bf16 v[16:19], v[238:241], v[182:185], v[16:19]
	v_mfma_f32_16x16x32_bf16 v[4:7], v[198:201], v[190:193], v[4:7]
	v_mfma_f32_16x16x32_bf16 v[0:3], v[238:241], v[190:193], v[0:3]
	v_mfma_f32_16x16x32_bf16 v[52:55], v[202:205], v[170:173], v[52:55]
	v_mfma_f32_16x16x32_bf16 v[48:51], v[242:245], v[170:173], v[48:51]
	v_mfma_f32_16x16x32_bf16 v[36:39], v[202:205], v[178:181], v[36:39]
	v_mfma_f32_16x16x32_bf16 v[32:35], v[242:245], v[178:181], v[32:35]
	v_mfma_f32_16x16x32_bf16 v[20:23], v[202:205], v[186:189], v[20:23]
	v_mfma_f32_16x16x32_bf16 v[16:19], v[242:245], v[186:189], v[16:19]
	v_mfma_f32_16x16x32_bf16 v[4:7], v[202:205], v[194:197], v[4:7]
	v_mfma_f32_16x16x32_bf16 v[0:3], v[242:245], v[194:197], v[0:3]
	s_barrier
	s_add_i32 vcc_lo, vcc_lo, 2
	s_add_u32 s26, s26, 0x100
	s_addc_u32 s27, s27, 0
	s_add_u32 s45, s45, 0x100
	s_addc_u32 s65, s65, 0
	s_cmp_gt_u32 vcc_lo, 5
	s_cbranch_scc0 .LBB0_499
	v_lshl_add_u32 v144, s0, 8, v158
	v_lshlrev_b32_e32 v220, 6, v144
	v_add_u32_e32 v221, 0x2000, v220
	global_load_dwordx4 v[176:179], v220, s[48:49] offset:16
	global_load_dwordx4 v[180:183], v220, s[48:49]
	global_load_dwordx4 v[184:187], v220, s[48:49] offset:1040
	global_load_dwordx4 v[188:191], v220, s[48:49] offset:1024
	global_load_dwordx4 v[192:195], v220, s[48:49] offset:2064
	global_load_dwordx4 v[196:199], v220, s[48:49] offset:2048
	global_load_dwordx4 v[200:203], v220, s[48:49] offset:3088
	global_load_dwordx4 v[204:207], v220, s[48:49] offset:3072
	v_ashrrev_i32_e32 v145, 31, v144
	v_lshlrev_b64 v[150:151], 6, v[144:145]
	v_lshl_add_u64 v[154:155], s[48:49], 0, v[150:151]
	s_waitcnt vmcnt(6)
	v_mov_b32_e32 v150, v176
	v_mov_b32_e32 v151, v177
	v_mov_b32_e32 v152, v178
	v_mov_b32_e32 v153, v179
	s_nop 0
	v_mov_b32_e32 v154, v180
	v_mov_b32_e32 v155, v181
	v_mov_b32_e32 v156, v182
	v_mov_b32_e32 v157, v183
	global_load_dwordx4 v[176:179], v221, s[48:49] offset:16
	global_load_dwordx4 v[180:183], v221, s[48:49]
	v_lshrrev_b32_e32 v146, 21, v145
	v_add_u32_e32 v146, v144, v146
	v_ashrrev_i32_e32 v149, 11, v146
	v_mul_i32_i24_e32 v146, 0x800, v149
	v_sub_u32_e32 v146, v144, v146
	s_mov_b64 s[0:1], -1
	s_nop 0
	v_mov_b32_e32 v162, v155
	v_mov_b32_e32 v163, v156
	v_mov_b32_e32 v155, v157
	v_pk_add_f32 v[154:155], v[162:163], v[154:155]
	v_mov_b32_e32 v156, v152
	v_mov_b32_e32 v157, v150
	v_mov_b32_e32 v150, v153
	v_pk_add_f32 v[150:151], v[156:157], v[150:151]
	v_add_f32_e32 v147, v154, v155
	v_add_f32_e32 v147, v147, v151
	v_add_f32_e32 v147, v150, v147
	v_fmamk_f32 v147, v147, 0x3b000000, v223
	v_cmp_gt_f32_e32 vcc, s60, v147
	v_mul_f32_e32 v148, 0x4b800000, v147
	s_nop 0
	v_cndmask_b32_e32 v147, v147, v148, vcc
	v_rsq_f32_e32 v147, v147
	s_nop 0
	v_mul_f32_e32 v148, 0x45800000, v147
	v_cndmask_b32_e32 v148, v147, v148, vcc
	s_and_b64 vcc, exec, s[46:47]
	v_ashrrev_i32_e32 v147, 31, v146
	s_cbranch_vccz .LBB0_502
	v_lshl_add_u32 v150, v149, 3, s94
	v_ashrrev_i32_e32 v151, 31, v150
	v_lshlrev_b64 v[150:151], 11, v[150:151]
	v_lshl_add_u64 v[154:155], v[150:151], 0, v[146:147]
	v_pk_mul_f32 v[152:153], v[126:127], v[148:149] op_sel_hi:[1,0]
	v_pk_mul_f32 v[150:151], v[124:125], v[148:149] op_sel_hi:[1,0]
	v_pk_mul_f32 v[156:157], v[122:123], v[148:149] op_sel_hi:[1,0]
	v_pk_mul_f32 v[162:163], v[120:121], v[148:149] op_sel_hi:[1,0]
	v_cvt_pk_bf16_f32 v150, v150, v151
	v_cvt_pk_bf16_f32 v151, v152, v153
	v_cvt_pk_bf16_f32 v153, v156, v157
	v_mad_u64_u32 v[156:157], s[0:1], v154, s33, v[136:137]
	v_cvt_pk_bf16_f32 v152, v162, v163
	v_mad_i32_i24 v157, v155, s33, v157
	global_store_dwordx4 v[156:157], v[150:153], off
	v_pk_mul_f32 v[156:157], v[114:115], v[148:149] op_sel_hi:[1,0]
	v_pk_mul_f32 v[162:163], v[112:113], v[148:149] op_sel_hi:[1,0]
	v_pk_mul_f32 v[152:153], v[118:119], v[148:149] op_sel_hi:[1,0]
	v_pk_mul_f32 v[150:151], v[116:117], v[148:149] op_sel_hi:[1,0]
	v_lshlrev_b64 v[154:155], 8, v[154:155]
	v_cvt_pk_bf16_f32 v150, v150, v151
	v_cvt_pk_bf16_f32 v151, v152, v153
	v_cvt_pk_bf16_f32 v152, v162, v163
	v_cvt_pk_bf16_f32 v153, v156, v157
	v_lshl_add_u64 v[154:155], v[138:139], 0, v[154:155]
	global_store_dwordx4 v[154:155], v[150:153], off
	s_mov_b64 s[0:1], 0

; #define PG8_STAGE(bufoff, gbase, voff) do { _Pragma("unroll") for (int _i = 0; _i < 2; ++_i) \
;         __builtin_amdgcn_global_load_lds((const unsigned*)((const char*)(gbase) + (voff)[_i]), (LAS unsigned*)(lds + (bufoff) + ldsw + _i * 8192), 16, 0, 0); } while (0)
; #define PG8_LDA(dst, b, h) do { _Pragma("unroll") for (int m = 0; m < 4; ++m) _Pragma("unroll") for (int k = 0; k < 2; ++k) dst[m][k] = *(const LAS bf16x8*)(lds + PG8_SA(b, h) + aoff + m * 2048 + k * 1024); } while (0)
; #define PG8_LDB(dst, b, h) do { _Pragma("unroll") for (int n = 0; n < 2; ++n) _Pragma("unroll") for (int k = 0; k < 2; ++k) dst[n][k] = *(const LAS bf16x8*)(lds + PG8_SB(b, h) + boff + n * 2048 + k * 1024); } while (0)
; #define PG8_MMA(ai, bj, At, Bt) do { __builtin_amdgcn_s_setprio(1); _Pragma("unroll") for (int m = 0; m < 4; ++m) _Pragma("unroll") for (int n = 0; n < 2; ++n) _Pragma("unroll") for (int k = 0; k < 2; ++k) \
;         acc[ai][bj][m][n] = __builtin_amdgcn_mfma_f32_16x16x32_bf16(Bt[n][k], At[m][k], acc[ai][bj][m][n], 0, 0, 0); __builtin_amdgcn_s_setprio(0); } while (0)
; #define PG8_WAIT_V(n) asm volatile("s_waitcnt vmcnt(" #n ")" ::: "memory")
; #define PG8_WAIT_L(n) asm volatile("s_waitcnt lgkmcnt(" #n ")" ::: "memory")
; #define PG8_BAR __builtin_amdgcn_s_barrier()
; #define PG8_SCHED __builtin_amdgcn_sched_barrier(0)
; template <class Epi>
; __device__ __forceinline__ void gemm_phase(LAS unsigned char* lds, const Gemm g, const Epi& E) {
;     ...
;             PG8_LDB(B0, 0, 0); PG8_SCHED; PG8_LDA(At, 0, 0); PG8_STAGE(PG8_SA(1, 1), a1 + hstep, voffA);
;             PG8_WAIT_L(8); PG8_BAR; PG8_WAIT_L(0); PG8_MMA(0, 0, At, B0); PG8_BAR; PG8_SCHED;
;             PG8_LDB(B1, 0, 1); PG8_STAGE(PG8_SB(0, 0), b2, voffB);
;             PG8_BAR; PG8_WAIT_L(0); PG8_MMA(0, 1, At, B1); PG8_BAR;
;             PG8_LDA(At, 0, 1); PG8_STAGE(PG8_SA(0, 0), a2, voffA);
;             PG8_BAR; PG8_WAIT_L(0); PG8_MMA(1, 0, At, B0); PG8_BAR; PG8_SCHED;
;             PG8_STAGE(PG8_SB(0, 1), b2 + hstep, voffB);
;             PG8_WAIT_V(6); PG8_BAR; PG8_MMA(1, 1, At, B1); PG8_BAR;
.LBB0_672:
	s_add_u32 s28, s26, 0xfff80080
	s_addc_u32 s29, s27, -1
	s_add_i32 s34, 0, 0x10000
	v_add_u32_e32 v160, s34, v163
	ds_read_b128 v[128:131], v160
	ds_read_b128 v[132:135], v160 offset:1024
	ds_read_b128 v[156:159], v160 offset:2048
	ds_read_b128 v[166:169], v160 offset:3072
	s_cmp_eq_u32 s39, 28
	s_cselect_b32 s37, s1, s29
	s_cselect_b32 s36, s2, s28
	s_cselect_b32 s29, s3, s38
	s_cselect_b32 s28, s30, s31
	s_add_i32 m0, s96, 0xc000
	ds_read_b128 v[170:173], v164
	ds_read_b128 v[174:177], v164 offset:1024
	ds_read_b128 v[178:181], v164 offset:2048
	ds_read_b128 v[182:185], v164 offset:3072
	ds_read_b128 v[186:189], v164 offset:4096
	ds_read_b128 v[190:193], v164 offset:5120
	ds_read_b128 v[194:197], v164 offset:6144
	ds_read_b128 v[198:201], v164 offset:7168
	global_load_lds_dwordx4 v152, s[26:27]
	s_add_i32 m0, s96, 0xe000
	s_nop 0
	global_load_lds_dwordx4 v154, s[26:27]
	s_waitcnt lgkmcnt(8)
	s_barrier
	s_waitcnt lgkmcnt(0)
	v_mfma_f32_16x16x32_bf16 v[124:127], v[128:131], v[170:173], v[124:127]
	v_mfma_f32_16x16x32_bf16 v[120:123], v[156:159], v[170:173], v[120:123]
	v_mfma_f32_16x16x32_bf16 v[108:111], v[128:131], v[178:181], v[108:111]
	v_mfma_f32_16x16x32_bf16 v[104:107], v[156:159], v[178:181], v[104:107]
	v_mfma_f32_16x16x32_bf16 v[92:95], v[128:131], v[186:189], v[92:95]
	v_mfma_f32_16x16x32_bf16 v[88:91], v[156:159], v[186:189], v[88:91]
	v_mfma_f32_16x16x32_bf16 v[76:79], v[128:131], v[194:197], v[76:79]
	v_mfma_f32_16x16x32_bf16 v[72:75], v[156:159], v[194:197], v[72:75]
	v_mfma_f32_16x16x32_bf16 v[124:127], v[132:135], v[174:177], v[124:127]
	v_mfma_f32_16x16x32_bf16 v[120:123], v[166:169], v[174:177], v[120:123]
	v_mfma_f32_16x16x32_bf16 v[108:111], v[132:135], v[182:185], v[108:111]
	v_mfma_f32_16x16x32_bf16 v[104:107], v[166:169], v[182:185], v[104:107]
	v_mfma_f32_16x16x32_bf16 v[92:95], v[132:135], v[190:193], v[92:95]
	v_mfma_f32_16x16x32_bf16 v[88:91], v[166:169], v[190:193], v[88:91]
	v_mfma_f32_16x16x32_bf16 v[76:79], v[132:135], v[198:201], v[76:79]
	v_mfma_f32_16x16x32_bf16 v[72:75], v[166:169], v[198:201], v[72:75]
	s_barrier
	s_add_i32 s35, 0, 0x14000
	v_add_u32_e32 v160, s35, v163
	s_add_i32 s34, s34, s71
	ds_read_b128 v[202:205], v160
	ds_read_b128 v[238:241], v160 offset:1024
	ds_read_b128 v[242:245], v160 offset:2048
	ds_read_b128 v[246:249], v160 offset:3072
	s_mov_b32 m0, s34
	s_nop 0
	global_load_lds_dwordx4 v138, s[28:29]
	s_add_i32 m0, s34, 0x2000
	s_nop 0
	global_load_lds_dwordx4 v142, s[28:29]
	s_barrier
	s_waitcnt lgkmcnt(0)
	v_mfma_f32_16x16x32_bf16 v[116:119], v[202:205], v[170:173], v[116:119]
	v_mfma_f32_16x16x32_bf16 v[112:115], v[242:245], v[170:173], v[112:115]
	v_mfma_f32_16x16x32_bf16 v[100:103], v[202:205], v[178:181], v[100:103]
	v_mfma_f32_16x16x32_bf16 v[96:99], v[242:245], v[178:181], v[96:99]
	v_mfma_f32_16x16x32_bf16 v[84:87], v[202:205], v[186:189], v[84:87]
	v_mfma_f32_16x16x32_bf16 v[80:83], v[242:245], v[186:189], v[80:83]
	v_mfma_f32_16x16x32_bf16 v[68:71], v[202:205], v[194:197], v[68:71]
	v_mfma_f32_16x16x32_bf16 v[64:67], v[242:245], v[194:197], v[64:67]
	v_mfma_f32_16x16x32_bf16 v[116:119], v[238:241], v[174:177], v[116:119]
	v_mfma_f32_16x16x32_bf16 v[112:115], v[246:249], v[174:177], v[112:115]
	v_mfma_f32_16x16x32_bf16 v[100:103], v[238:241], v[182:185], v[100:103]
	v_mfma_f32_16x16x32_bf16 v[96:99], v[246:249], v[182:185], v[96:99]
	v_mfma_f32_16x16x32_bf16 v[84:87], v[238:241], v[190:193], v[84:87]
	v_mfma_f32_16x16x32_bf16 v[80:83], v[246:249], v[190:193], v[80:83]
	v_mfma_f32_16x16x32_bf16 v[68:71], v[238:241], v[198:201], v[68:71]
	v_mfma_f32_16x16x32_bf16 v[64:67], v[246:249], v[198:201], v[64:67]
	s_barrier
	s_mov_b32 m0, s96
	ds_read_b128 v[170:173], v164 offset:16384
	ds_read_b128 v[174:177], v164 offset:17408
	ds_read_b128 v[178:181], v164 offset:18432
	ds_read_b128 v[182:185], v164 offset:19456
	ds_read_b128 v[186:189], v164 offset:20480
	ds_read_b128 v[190:193], v164 offset:21504
	ds_read_b128 v[194:197], v164 offset:22528
	ds_read_b128 v[198:201], v164 offset:23552
	global_load_lds_dwordx4 v136, s[36:37]
	s_mov_b32 m0, s97
	s_nop 0
	global_load_lds_dwordx4 v140, s[36:37]
	s_barrier
	s_waitcnt lgkmcnt(0)
	v_mfma_f32_16x16x32_bf16 v[60:63], v[128:131], v[170:173], v[60:63]
	v_mfma_f32_16x16x32_bf16 v[56:59], v[156:159], v[170:173], v[56:59]
	v_mfma_f32_16x16x32_bf16 v[44:47], v[128:131], v[178:181], v[44:47]
	v_mfma_f32_16x16x32_bf16 v[40:43], v[156:159], v[178:181], v[40:43]
	v_mfma_f32_16x16x32_bf16 v[28:31], v[128:131], v[186:189], v[28:31]
	v_mfma_f32_16x16x32_bf16 v[24:27], v[156:159], v[186:189], v[24:27]
	v_mfma_f32_16x16x32_bf16 v[12:15], v[128:131], v[194:197], v[12:15]
	v_mfma_f32_16x16x32_bf16 v[8:11], v[156:159], v[194:197], v[8:11]
	v_mfma_f32_16x16x32_bf16 v[60:63], v[132:135], v[174:177], v[60:63]
	v_mfma_f32_16x16x32_bf16 v[56:59], v[166:169], v[174:177], v[56:59]
	v_mfma_f32_16x16x32_bf16 v[44:47], v[132:135], v[182:185], v[44:47]
	v_mfma_f32_16x16x32_bf16 v[40:43], v[166:169], v[182:185], v[40:43]
	v_mfma_f32_16x16x32_bf16 v[28:31], v[132:135], v[190:193], v[28:31]
	v_mfma_f32_16x16x32_bf16 v[24:27], v[166:169], v[190:193], v[24:27]
	v_mfma_f32_16x16x32_bf16 v[12:15], v[132:135], v[198:201], v[12:15]
	v_mfma_f32_16x16x32_bf16 v[8:11], v[166:169], v[198:201], v[8:11]
	s_barrier
	s_add_u32 s48, s28, 0x80000
	s_addc_u32 s49, s29, 0
	s_add_i32 s34, s35, s71
	s_mov_b32 m0, s34
	s_nop 0
	global_load_lds_dwordx4 v138, s[48:49]
	s_add_i32 m0, s34, 0x2000
	s_nop 0
	global_load_lds_dwordx4 v142, s[48:49]
	s_waitcnt vmcnt(6)
	s_barrier
; #define PG8_STAGE(bufoff, gbase, voff) do { _Pragma("unroll") for (int _i = 0; _i < 2; ++_i) \
;         __builtin_amdgcn_global_load_lds((const unsigned*)((const char*)(gbase) + (voff)[_i]), (LAS unsigned*)(lds + (bufoff) + ldsw + _i * 8192), 16, 0, 0); } while (0)
; #define PG8_LDA(dst, b, h) do { _Pragma("unroll") for (int m = 0; m < 4; ++m) _Pragma("unroll") for (int k = 0; k < 2; ++k) dst[m][k] = *(const LAS bf16x8*)(lds + PG8_SA(b, h) + aoff + m * 2048 + k * 1024); } while (0)
; #define PG8_LDB(dst, b, h) do { _Pragma("unroll") for (int n = 0; n < 2; ++n) _Pragma("unroll") for (int k = 0; k < 2; ++k) dst[n][k] = *(const LAS bf16x8*)(lds + PG8_SB(b, h) + boff + n * 2048 + k * 1024); } while (0)
; #define PG8_MMA(ai, bj, At, Bt) do { __builtin_amdgcn_s_setprio(1); _Pragma("unroll") for (int m = 0; m < 4; ++m) _Pragma("unroll") for (int n = 0; n < 2; ++n) _Pragma("unroll") for (int k = 0; k < 2; ++k) \
;         acc[ai][bj][m][n] = __builtin_amdgcn_mfma_f32_16x16x32_bf16(Bt[n][k], At[m][k], acc[ai][bj][m][n], 0, 0, 0); __builtin_amdgcn_s_setprio(0); } while (0)
; #define PG8_WAIT_V(n) asm volatile("s_waitcnt vmcnt(" #n ")" ::: "memory")
; #define PG8_WAIT_L(n) asm volatile("s_waitcnt lgkmcnt(" #n ")" ::: "memory")
; #define PG8_BAR __builtin_amdgcn_s_barrier()
; #define PG8_SCHED __builtin_amdgcn_sched_barrier(0)
; template <class Epi>
; __device__ __forceinline__ void gemm_phase(LAS unsigned char* lds, const Gemm g, const Epi& E) {
;     ...
;             PG8_WAIT_V(6); PG8_BAR; PG8_MMA(1, 1, At, B1); PG8_BAR;
;             PG8_LDB(B0, 1, 0); PG8_SCHED; PG8_LDA(At, 1, 0); PG8_STAGE(PG8_SA(0, 1), a2 + hstep, voffA);
;             PG8_WAIT_L(8); PG8_BAR; PG8_WAIT_L(0); PG8_MMA(0, 0, At, B0); PG8_BAR; PG8_SCHED;
;             PG8_LDB(B1, 1, 1); PG8_STAGE(PG8_SB(1, 0), b3, voffB);
;             PG8_BAR; PG8_WAIT_L(0); PG8_MMA(0, 1, At, B1); PG8_BAR;
;             PG8_LDA(At, 1, 1); PG8_STAGE(PG8_SA(1, 0), a3, voffA);
;             PG8_BAR; PG8_WAIT_L(0); PG8_MMA(1, 0, At, B0); PG8_BAR; PG8_SCHED;
	v_mfma_f32_16x16x32_bf16 v[52:55], v[202:205], v[170:173], v[52:55]
	v_mfma_f32_16x16x32_bf16 v[48:51], v[242:245], v[170:173], v[48:51]
	v_mfma_f32_16x16x32_bf16 v[36:39], v[202:205], v[178:181], v[36:39]
	v_mfma_f32_16x16x32_bf16 v[32:35], v[242:245], v[178:181], v[32:35]
	v_mfma_f32_16x16x32_bf16 v[20:23], v[202:205], v[186:189], v[20:23]
	v_mfma_f32_16x16x32_bf16 v[16:19], v[242:245], v[186:189], v[16:19]
	v_mfma_f32_16x16x32_bf16 v[4:7], v[202:205], v[194:197], v[4:7]
	v_mfma_f32_16x16x32_bf16 v[0:3], v[242:245], v[194:197], v[0:3]
	v_mfma_f32_16x16x32_bf16 v[52:55], v[238:241], v[174:177], v[52:55]
	v_mfma_f32_16x16x32_bf16 v[48:51], v[246:249], v[174:177], v[48:51]
	v_mfma_f32_16x16x32_bf16 v[36:39], v[238:241], v[182:185], v[36:39]
	v_mfma_f32_16x16x32_bf16 v[32:35], v[246:249], v[182:185], v[32:35]
	v_mfma_f32_16x16x32_bf16 v[20:23], v[238:241], v[190:193], v[20:23]
	v_mfma_f32_16x16x32_bf16 v[16:19], v[246:249], v[190:193], v[16:19]
	v_mfma_f32_16x16x32_bf16 v[4:7], v[238:241], v[198:201], v[4:7]
	v_mfma_f32_16x16x32_bf16 v[0:3], v[246:249], v[198:201], v[0:3]
	s_barrier
	s_add_i32 s34, 0, 0x18000
	v_add_u32_e32 v165, s34, v163
	ds_read_b128 v[128:131], v165
	ds_read_b128 v[132:135], v165 offset:1024
	ds_read_b128 v[156:159], v165 offset:2048
	ds_read_b128 v[166:169], v165 offset:3072
	s_add_u32 s36, s36, 0x80000
	s_addc_u32 s37, s37, 0
	s_mov_b32 m0, s70
	ds_read_b128 v[170:173], v164 offset:32768
	ds_read_b128 v[174:177], v164 offset:33792
	ds_read_b128 v[178:181], v164 offset:34816
	ds_read_b128 v[182:185], v164 offset:35840
	ds_read_b128 v[186:189], v164 offset:36864
	ds_read_b128 v[190:193], v164 offset:37888
	ds_read_b128 v[194:197], v164 offset:38912
	ds_read_b128 v[198:201], v164 offset:39936
	global_load_lds_dwordx4 v136, s[36:37]
	s_mov_b32 m0, s69
	s_nop 0
	global_load_lds_dwordx4 v140, s[36:37]
	s_waitcnt lgkmcnt(8)
	s_barrier
	s_waitcnt lgkmcnt(0)
	v_mfma_f32_16x16x32_bf16 v[124:127], v[128:131], v[170:173], v[124:127]
	v_mfma_f32_16x16x32_bf16 v[120:123], v[156:159], v[170:173], v[120:123]
	v_mfma_f32_16x16x32_bf16 v[108:111], v[128:131], v[178:181], v[108:111]
	v_mfma_f32_16x16x32_bf16 v[104:107], v[156:159], v[178:181], v[104:107]
	v_mfma_f32_16x16x32_bf16 v[92:95], v[128:131], v[186:189], v[92:95]
	v_mfma_f32_16x16x32_bf16 v[88:91], v[156:159], v[186:189], v[88:91]
	v_mfma_f32_16x16x32_bf16 v[76:79], v[128:131], v[194:197], v[76:79]
	v_mfma_f32_16x16x32_bf16 v[72:75], v[156:159], v[194:197], v[72:75]
	v_mfma_f32_16x16x32_bf16 v[124:127], v[132:135], v[174:177], v[124:127]
	v_mfma_f32_16x16x32_bf16 v[120:123], v[166:169], v[174:177], v[120:123]
	v_mfma_f32_16x16x32_bf16 v[108:111], v[132:135], v[182:185], v[108:111]
	v_mfma_f32_16x16x32_bf16 v[104:107], v[166:169], v[182:185], v[104:107]
	v_mfma_f32_16x16x32_bf16 v[92:95], v[132:135], v[190:193], v[92:95]
	v_mfma_f32_16x16x32_bf16 v[88:91], v[166:169], v[190:193], v[88:91]
	v_mfma_f32_16x16x32_bf16 v[76:79], v[132:135], v[198:201], v[76:79]
	v_mfma_f32_16x16x32_bf16 v[72:75], v[166:169], v[198:201], v[72:75]
	s_barrier
	s_add_i32 s35, 0, 0x1c000
	s_add_i32 s34, s34, s71
	v_add_u32_e32 v165, s35, v163
	s_mov_b32 m0, s34
	ds_read_b128 v[202:205], v165
	ds_read_b128 v[238:241], v165 offset:1024
	ds_read_b128 v[242:245], v165 offset:2048
	ds_read_b128 v[246:249], v165 offset:3072
	s_add_u32 s98, s28, 0x80
	s_addc_u32 s99, s29, 0
	global_load_lds_dwordx4 v138, s[98:99]
	s_add_i32 m0, s34, 0x2000
	s_add_u32 s100, s28, 0x80
	s_addc_u32 s101, s29, 0
	global_load_lds_dwordx4 v142, s[100:101]
	s_barrier
	s_waitcnt lgkmcnt(0)
	v_mfma_f32_16x16x32_bf16 v[116:119], v[202:205], v[170:173], v[116:119]
	v_mfma_f32_16x16x32_bf16 v[112:115], v[242:245], v[170:173], v[112:115]
	v_mfma_f32_16x16x32_bf16 v[100:103], v[202:205], v[178:181], v[100:103]
	v_mfma_f32_16x16x32_bf16 v[96:99], v[242:245], v[178:181], v[96:99]
	v_mfma_f32_16x16x32_bf16 v[84:87], v[202:205], v[186:189], v[84:87]
	v_mfma_f32_16x16x32_bf16 v[80:83], v[242:245], v[186:189], v[80:83]
	v_mfma_f32_16x16x32_bf16 v[68:71], v[202:205], v[194:197], v[68:71]
	v_mfma_f32_16x16x32_bf16 v[64:67], v[242:245], v[194:197], v[64:67]
	v_mfma_f32_16x16x32_bf16 v[116:119], v[238:241], v[174:177], v[116:119]
	v_mfma_f32_16x16x32_bf16 v[112:115], v[246:249], v[174:177], v[112:115]
	v_mfma_f32_16x16x32_bf16 v[100:103], v[238:241], v[182:185], v[100:103]
	v_mfma_f32_16x16x32_bf16 v[96:99], v[246:249], v[182:185], v[96:99]
	v_mfma_f32_16x16x32_bf16 v[84:87], v[238:241], v[190:193], v[84:87]
	v_mfma_f32_16x16x32_bf16 v[80:83], v[246:249], v[190:193], v[80:83]
	v_mfma_f32_16x16x32_bf16 v[68:71], v[238:241], v[198:201], v[68:71]
	v_mfma_f32_16x16x32_bf16 v[64:67], v[246:249], v[198:201], v[64:67]
	s_barrier
; __device__ __forceinline__ u32x2 pack4u(f32x4 a) { u32x2 w = {cvt_pk_bf16(a[0], a[1]), cvt_pk_bf16(a[2], a[3])}; return w; }
; #define PG8_WAIT_V(n) asm volatile("s_waitcnt vmcnt(" #n ")" ::: "memory")
; #define PG8_WAIT_L(n) asm volatile("s_waitcnt lgkmcnt(" #n ")" ::: "memory")
; template <class Epi>
; __device__ __forceinline__ void gemm_phase(LAS unsigned char* lds, const Gemm g, const Epi& E) {
;     ...
;             PG8_WAIT_V(6); PG8_BAR; PG8_MMA(1, 1, At, B1); PG8_BAR;
;             PG8_LDB(B0, 1, 0); PG8_SCHED; PG8_LDA(At, 1, 0); PG8_STAGE(PG8_SA(0, 1), a2 + hstep, voffA);
;             PG8_WAIT_L(8); PG8_BAR; PG8_WAIT_L(0); PG8_MMA(0, 0, At, B0); PG8_BAR; PG8_SCHED;
;             PG8_LDB(B1, 1, 1); PG8_STAGE(PG8_SB(1, 0), b3, voffB);
;             PG8_BAR; PG8_WAIT_L(0); PG8_MMA(0, 1, At, B1); PG8_BAR;
;             PG8_LDA(At, 1, 1); PG8_STAGE(PG8_SA(1, 0), a3, voffA);
;             PG8_BAR; PG8_WAIT_L(0); PG8_MMA(1, 0, At, B0); PG8_BAR; PG8_SCHED;
;             PG8_STAGE(PG8_SB(1, 1), b3 + hstep, voffB);
;             PG8_WAIT_V(6); PG8_BAR; PG8_MMA(1, 1, At, B1); PG8_BAR;
;     __device__ __forceinline__ void operator()(const AccT& acc, const Unit& u, int wr, int wc, int fr, int fq) const {
;     ...
;             const int g8 = wc * 4 + fq;
; #pragma unroll
;             for (int ai = 0; ai < 2; ++ai)
; #pragma unroll
;                 for (int m = 0; m < 4; ++m) {
;                     const int row = u.pm * 256 + ai * 128 + wr * 64 + m * 16 + fr;
;                     const f32x4 v0 = acc[ai][0][m][0], v1 = acc[ai][0][m][1];
;                     if (g8 < 8) {
;                         const int i0 = 4 * g8;
;                         const f32x4 cs = *(const f32x4*)(COS + (size_t)row * 32 + i0), sn = *(const f32x4*)(SIN + (size_t)row * 32 + i0);
;                         const f32x4 o1 = v0 * cs - v1 * sn, o2 = v1 * cs + v0 * sn;
;                         const u32x2 w1 = pack4u(o1), w2 = pack4u(o2);
;                         const int b = row / SEQ, t = row % SEQ;
;                         bf16_t* kp = Kb + ((size_t)(b * NH) * SEQ + t) * DQK + 128 + i0;
; #pragma unroll
;                         for (int h = 0; h < NH; ++h) { *(u32x2*)(kp + (size_t)h * SEQ * DQK) = w1; *(u32x2*)(kp + (size_t)h * SEQ * DQK + 32) = w2; }
;                     } else if (g8 < 10) { float* bp = BA + (size_t)row * 16 + (g8 - 8) * 8; *(f32x4*)bp = v0; *(f32x4*)(bp + 4) = v1; }
	s_mov_b32 m0, s68
	ds_read_b128 v[170:173], v164 offset:49152
	ds_read_b128 v[174:177], v164 offset:50176
	ds_read_b128 v[178:181], v164 offset:51200
	ds_read_b128 v[182:185], v164 offset:52224
	ds_read_b128 v[186:189], v164 offset:53248
	ds_read_b128 v[190:193], v164 offset:54272
	ds_read_b128 v[194:197], v164 offset:55296
	ds_read_b128 v[198:201], v164 offset:56320
	s_add_u32 s98, s36, 0xfff80080
	s_addc_u32 s99, s37, -1
	global_load_lds_dwordx4 v136, s[98:99]
	s_mov_b32 m0, s83
	s_add_u32 s100, s36, 0xfff80080
	s_addc_u32 s101, s37, -1
	global_load_lds_dwordx4 v140, s[100:101]
	s_barrier
	s_waitcnt lgkmcnt(0)
	v_mfma_f32_16x16x32_bf16 v[60:63], v[128:131], v[170:173], v[60:63]
	v_mfma_f32_16x16x32_bf16 v[56:59], v[156:159], v[170:173], v[56:59]
	v_mfma_f32_16x16x32_bf16 v[44:47], v[128:131], v[178:181], v[44:47]
	v_mfma_f32_16x16x32_bf16 v[40:43], v[156:159], v[178:181], v[40:43]
	v_mfma_f32_16x16x32_bf16 v[28:31], v[128:131], v[186:189], v[28:31]
	v_mfma_f32_16x16x32_bf16 v[24:27], v[156:159], v[186:189], v[24:27]
	v_mfma_f32_16x16x32_bf16 v[12:15], v[128:131], v[194:197], v[12:15]
	v_mfma_f32_16x16x32_bf16 v[8:11], v[156:159], v[194:197], v[8:11]
	v_mfma_f32_16x16x32_bf16 v[60:63], v[132:135], v[174:177], v[60:63]
	v_mfma_f32_16x16x32_bf16 v[56:59], v[166:169], v[174:177], v[56:59]
	v_mfma_f32_16x16x32_bf16 v[44:47], v[132:135], v[182:185], v[44:47]
	v_mfma_f32_16x16x32_bf16 v[40:43], v[166:169], v[182:185], v[40:43]
	v_mfma_f32_16x16x32_bf16 v[28:31], v[132:135], v[190:193], v[28:31]
	v_mfma_f32_16x16x32_bf16 v[24:27], v[166:169], v[190:193], v[24:27]
	v_mfma_f32_16x16x32_bf16 v[12:15], v[132:135], v[198:201], v[12:15]
	v_mfma_f32_16x16x32_bf16 v[8:11], v[166:169], v[198:201], v[8:11]
	s_barrier
	s_add_u32 s28, s28, 0x80080
	s_addc_u32 s29, s29, 0
	s_add_i32 s34, s35, s71
	s_mov_b32 m0, s34
	s_nop 0
	global_load_lds_dwordx4 v138, s[28:29]
	s_add_i32 m0, s34, 0x2000
	s_nop 0
	global_load_lds_dwordx4 v142, s[28:29]
	s_waitcnt vmcnt(6)
	s_barrier
	v_mfma_f32_16x16x32_bf16 v[52:55], v[202:205], v[170:173], v[52:55]
	v_mfma_f32_16x16x32_bf16 v[48:51], v[242:245], v[170:173], v[48:51]
	v_mfma_f32_16x16x32_bf16 v[36:39], v[202:205], v[178:181], v[36:39]
	v_mfma_f32_16x16x32_bf16 v[32:35], v[242:245], v[178:181], v[32:35]
	v_mfma_f32_16x16x32_bf16 v[20:23], v[202:205], v[186:189], v[20:23]
	v_mfma_f32_16x16x32_bf16 v[16:19], v[242:245], v[186:189], v[16:19]
	v_mfma_f32_16x16x32_bf16 v[4:7], v[202:205], v[194:197], v[4:7]
	v_mfma_f32_16x16x32_bf16 v[0:3], v[242:245], v[194:197], v[0:3]
	v_mfma_f32_16x16x32_bf16 v[52:55], v[238:241], v[174:177], v[52:55]
	v_mfma_f32_16x16x32_bf16 v[48:51], v[246:249], v[174:177], v[48:51]
	v_mfma_f32_16x16x32_bf16 v[36:39], v[238:241], v[182:185], v[36:39]
	v_mfma_f32_16x16x32_bf16 v[32:35], v[246:249], v[182:185], v[32:35]
	v_mfma_f32_16x16x32_bf16 v[20:23], v[238:241], v[190:193], v[20:23]
	v_mfma_f32_16x16x32_bf16 v[16:19], v[246:249], v[190:193], v[16:19]
	v_mfma_f32_16x16x32_bf16 v[4:7], v[238:241], v[198:201], v[4:7]
	v_mfma_f32_16x16x32_bf16 v[0:3], v[246:249], v[198:201], v[0:3]
	s_barrier
	s_add_i32 s39, s39, 2
	s_add_u32 s26, s26, 0x100
	s_addc_u32 s27, s27, 0
	s_add_u32 s31, s31, 0x100
	s_addc_u32 s38, s38, 0
	s_cmp_gt_u32 s39, 29
	s_cbranch_scc0 .LBB0_672
	s_mov_b64 s[26:27], -1
	s_cmp_gt_i32 s64, 35
	v_lshl_add_u32 v156, s46, 8, v162
	s_movk_i32 s95, 0x1ff
	s_cbranch_scc0 .LBB0_723
	v_mov_b32_e32 v220, v156
	v_ashrrev_i32_e32 v221, 31, v156
	v_lshlrev_b64 v[220:221], 7, v[220:221]
	v_lshl_add_u64 v[200:201], v[146:147], 0, v[220:221]
	v_lshl_add_u64 v[202:203], v[148:149], 0, v[220:221]
	s_mov_b64 s[98:99], 0x1000
	v_lshl_add_u64 v[204:205], v[200:201], 0, s[98:99]
	v_lshl_add_u64 v[206:207], v[202:203], 0, s[98:99]
	global_load_dwordx4 v[168:171], v[200:201], off
	global_load_dwordx4 v[172:175], v[202:203], off
	global_load_dwordx4 v[176:179], v[200:201], off offset:2048
	global_load_dwordx4 v[180:183], v[202:203], off offset:2048
	global_load_dwordx4 v[184:187], v[204:205], off
	global_load_dwordx4 v[188:191], v[206:207], off
	global_load_dwordx4 v[192:195], v[204:205], off offset:2048
	global_load_dwordx4 v[196:199], v[206:207], off offset:2048
	s_mov_b64 s[98:99], 0x4000
	v_lshl_add_u64 v[200:201], v[200:201], 0, s[98:99]
	v_lshl_add_u64 v[202:203], v[202:203], 0, s[98:99]
	v_lshl_add_u64 v[204:205], v[204:205], 0, s[98:99]
	v_lshl_add_u64 v[206:207], v[206:207], 0, s[98:99]
	s_and_b64 vcc, exec, s[52:53]
	s_cbranch_vccz .LBB0_678
	s_and_saveexec_b64 s[26:27], s[54:55]
	s_cbranch_execz .LBB0_677
	v_ashrrev_i32_e32 v157, 31, v156
	v_lshlrev_b64 v[128:129], 6, v[156:157]
	v_lshl_add_u64 v[128:129], v[144:145], 0, v[128:129]
	global_store_dwordx4 v[128:129], v[124:127], off offset:-256
	global_store_dwordx4 v[128:129], v[120:123], off offset:-240

; #define PG8_STAGE(bufoff, gbase, voff) do { _Pragma("unroll") for (int _i = 0; _i < 2; ++_i) \
;         __builtin_amdgcn_global_load_lds((const unsigned*)((const char*)(gbase) + (voff)[_i]), (LAS unsigned*)(lds + (bufoff) + ldsw + _i * 8192), 16, 0, 0); } while (0)
; #define PG8_LDA(dst, b, h) do { _Pragma("unroll") for (int m = 0; m < 4; ++m) _Pragma("unroll") for (int k = 0; k < 2; ++k) dst[m][k] = *(const LAS bf16x8*)(lds + PG8_SA(b, h) + aoff + m * 2048 + k * 1024); } while (0)
; #define PG8_LDB(dst, b, h) do { _Pragma("unroll") for (int n = 0; n < 2; ++n) _Pragma("unroll") for (int k = 0; k < 2; ++k) dst[n][k] = *(const LAS bf16x8*)(lds + PG8_SB(b, h) + boff + n * 2048 + k * 1024); } while (0)
; #define PG8_MMA(ai, bj, At, Bt) do { __builtin_amdgcn_s_setprio(1); _Pragma("unroll") for (int m = 0; m < 4; ++m) _Pragma("unroll") for (int n = 0; n < 2; ++n) _Pragma("unroll") for (int k = 0; k < 2; ++k) \
;         acc[ai][bj][m][n] = __builtin_amdgcn_mfma_f32_16x16x32_bf16(Bt[n][k], At[m][k], acc[ai][bj][m][n], 0, 0, 0); __builtin_amdgcn_s_setprio(0); } while (0)
; #define PG8_WAIT_V(n) asm volatile("s_waitcnt vmcnt(" #n ")" ::: "memory")
; template <class Epi>
; __device__ __forceinline__ void gemm_phase(LAS unsigned char* lds, const Gemm g, const Epi& E) {
;     ...
;             PG8_LDB(B0, 0, 0); PG8_SCHED; PG8_LDA(At, 0, 0); PG8_STAGE(PG8_SA(1, 1), a1 + hstep, voffA);
;             PG8_WAIT_L(8); PG8_BAR; PG8_WAIT_L(0); PG8_MMA(0, 0, At, B0); PG8_BAR; PG8_SCHED;
;             PG8_LDB(B1, 0, 1); PG8_STAGE(PG8_SB(0, 0), b2, voffB);
;             PG8_BAR; PG8_WAIT_L(0); PG8_MMA(0, 1, At, B1); PG8_BAR;
;             PG8_LDA(At, 0, 1); PG8_STAGE(PG8_SA(0, 0), a2, voffA);
;             PG8_BAR; PG8_WAIT_L(0); PG8_MMA(1, 0, At, B0); PG8_BAR; PG8_SCHED;
;             PG8_STAGE(PG8_SB(0, 1), b2 + hstep, voffB);
;             PG8_WAIT_V(6); PG8_BAR; PG8_MMA(1, 1, At, B1); PG8_BAR;
;             PG8_LDB(B0, 1, 0); PG8_SCHED; PG8_LDA(At, 1, 0); PG8_STAGE(PG8_SA(0, 1), a2 + hstep, voffA);
;             PG8_WAIT_L(8); PG8_BAR; PG8_WAIT_L(0); PG8_MMA(0, 0, At, B0); PG8_BAR; PG8_SCHED;
;             PG8_LDB(B1, 1, 1); PG8_STAGE(PG8_SB(1, 0), b3, voffB);
;             PG8_BAR; PG8_WAIT_L(0); PG8_MMA(0, 1, At, B1); PG8_BAR;
;             PG8_LDA(At, 1, 1); PG8_STAGE(PG8_SA(1, 0), a3, voffA);
;             PG8_BAR; PG8_WAIT_L(0); PG8_MMA(1, 0, At, B0); PG8_BAR; PG8_SCHED;
.LBB0_873:
	s_add_u32 s28, s26, 0x100
	s_addc_u32 s29, s27, 0
	s_add_i32 s34, 0, 0x10000
	v_add_u32_e32 v140, s34, v160
	ds_read_b128 v[128:131], v140
	ds_read_b128 v[132:135], v140 offset:1024
	ds_read_b128 v[136:139], v140 offset:2048
	ds_read_b128 v[140:143], v140 offset:3072
	s_cmpk_eq_i32 s82, 0x54
	s_cselect_b32 s39, s1, s29
	s_cselect_b32 s38, s0, s28
	s_cselect_b32 s37, s43, s79
	s_cselect_b32 s36, s42, s78
	s_add_i32 m0, s44, 0xc000
	ds_read_b128 v[156:159], v161
	ds_read_b128 v[164:167], v161 offset:1024
	ds_read_b128 v[168:171], v161 offset:2048
	ds_read_b128 v[172:175], v161 offset:3072
	ds_read_b128 v[176:179], v161 offset:4096
	ds_read_b128 v[180:183], v161 offset:5120
	ds_read_b128 v[184:187], v161 offset:6144
	ds_read_b128 v[188:191], v161 offset:7168
	global_load_lds_dwordx4 v152, s[26:27]
	s_add_i32 m0, s44, 0xe000
	s_nop 0
	global_load_lds_dwordx4 v154, s[26:27]
	s_waitcnt lgkmcnt(8)
	s_barrier
	s_waitcnt lgkmcnt(0)
	v_mfma_f32_16x16x32_bf16 v[124:127], v[128:131], v[156:159], v[124:127]
	v_mfma_f32_16x16x32_bf16 v[120:123], v[136:139], v[156:159], v[120:123]
	v_mfma_f32_16x16x32_bf16 v[108:111], v[128:131], v[168:171], v[108:111]
	v_mfma_f32_16x16x32_bf16 v[104:107], v[136:139], v[168:171], v[104:107]
	v_mfma_f32_16x16x32_bf16 v[92:95], v[128:131], v[176:179], v[92:95]
	v_mfma_f32_16x16x32_bf16 v[88:91], v[136:139], v[176:179], v[88:91]
	v_mfma_f32_16x16x32_bf16 v[76:79], v[128:131], v[184:187], v[76:79]
	v_mfma_f32_16x16x32_bf16 v[72:75], v[136:139], v[184:187], v[72:75]
	v_mfma_f32_16x16x32_bf16 v[124:127], v[132:135], v[164:167], v[124:127]
	v_mfma_f32_16x16x32_bf16 v[120:123], v[140:143], v[164:167], v[120:123]
	v_mfma_f32_16x16x32_bf16 v[108:111], v[132:135], v[172:175], v[108:111]
	v_mfma_f32_16x16x32_bf16 v[104:107], v[140:143], v[172:175], v[104:107]
	v_mfma_f32_16x16x32_bf16 v[92:95], v[132:135], v[180:183], v[92:95]
	v_mfma_f32_16x16x32_bf16 v[88:91], v[140:143], v[180:183], v[88:91]
	v_mfma_f32_16x16x32_bf16 v[76:79], v[132:135], v[188:191], v[76:79]
	v_mfma_f32_16x16x32_bf16 v[72:75], v[140:143], v[188:191], v[72:75]
	s_barrier
	s_add_i32 s35, 0, 0x14000
	s_add_i32 s26, s34, s31
	v_add_u32_e32 v163, s35, v160
	s_mov_b32 m0, s26
	ds_read_b128 v[192:195], v163
	ds_read_b128 v[196:199], v163 offset:1024
	ds_read_b128 v[200:203], v163 offset:2048
	ds_read_b128 v[204:207], v163 offset:3072
	global_load_lds_dwordx4 v208, s[36:37]
	s_add_i32 m0, s26, 0x2000
	s_nop 0
	global_load_lds_dwordx4 v148, s[36:37]
	s_barrier
	s_waitcnt lgkmcnt(0)
	v_mfma_f32_16x16x32_bf16 v[116:119], v[192:195], v[156:159], v[116:119]
	v_mfma_f32_16x16x32_bf16 v[112:115], v[200:203], v[156:159], v[112:115]
	v_mfma_f32_16x16x32_bf16 v[100:103], v[192:195], v[168:171], v[100:103]
	v_mfma_f32_16x16x32_bf16 v[96:99], v[200:203], v[168:171], v[96:99]
	v_mfma_f32_16x16x32_bf16 v[84:87], v[192:195], v[176:179], v[84:87]
	v_mfma_f32_16x16x32_bf16 v[80:83], v[200:203], v[176:179], v[80:83]
	v_mfma_f32_16x16x32_bf16 v[68:71], v[192:195], v[184:187], v[68:71]
	v_mfma_f32_16x16x32_bf16 v[64:67], v[200:203], v[184:187], v[64:67]
	v_mfma_f32_16x16x32_bf16 v[116:119], v[196:199], v[164:167], v[116:119]
	v_mfma_f32_16x16x32_bf16 v[112:115], v[204:207], v[164:167], v[112:115]
	v_mfma_f32_16x16x32_bf16 v[100:103], v[196:199], v[172:175], v[100:103]
	v_mfma_f32_16x16x32_bf16 v[96:99], v[204:207], v[172:175], v[96:99]
	v_mfma_f32_16x16x32_bf16 v[84:87], v[196:199], v[180:183], v[84:87]
	v_mfma_f32_16x16x32_bf16 v[80:83], v[204:207], v[180:183], v[80:83]
	v_mfma_f32_16x16x32_bf16 v[68:71], v[196:199], v[188:191], v[68:71]
	v_mfma_f32_16x16x32_bf16 v[64:67], v[204:207], v[188:191], v[64:67]
	s_barrier
	s_mov_b32 m0, s44
	ds_read_b128 v[156:159], v161 offset:16384
	ds_read_b128 v[164:167], v161 offset:17408
	ds_read_b128 v[168:171], v161 offset:18432
	ds_read_b128 v[172:175], v161 offset:19456
	ds_read_b128 v[176:179], v161 offset:20480
	ds_read_b128 v[180:183], v161 offset:21504
	ds_read_b128 v[184:187], v161 offset:22528
	ds_read_b128 v[188:191], v161 offset:23552
	global_load_lds_dwordx4 v144, s[38:39]
	s_mov_b32 m0, s45
	s_nop 0
	global_load_lds_dwordx4 v146, s[38:39]
	s_barrier
	s_waitcnt lgkmcnt(0)
	v_mfma_f32_16x16x32_bf16 v[60:63], v[128:131], v[156:159], v[60:63]
	v_mfma_f32_16x16x32_bf16 v[56:59], v[136:139], v[156:159], v[56:59]
	v_mfma_f32_16x16x32_bf16 v[44:47], v[128:131], v[168:171], v[44:47]
	v_mfma_f32_16x16x32_bf16 v[40:43], v[136:139], v[168:171], v[40:43]
	v_mfma_f32_16x16x32_bf16 v[28:31], v[128:131], v[176:179], v[28:31]
	v_mfma_f32_16x16x32_bf16 v[24:27], v[136:139], v[176:179], v[24:27]
	v_mfma_f32_16x16x32_bf16 v[12:15], v[128:131], v[184:187], v[12:15]
	v_mfma_f32_16x16x32_bf16 v[8:11], v[136:139], v[184:187], v[8:11]
	v_mfma_f32_16x16x32_bf16 v[60:63], v[132:135], v[164:167], v[60:63]
	v_mfma_f32_16x16x32_bf16 v[56:59], v[140:143], v[164:167], v[56:59]
	v_mfma_f32_16x16x32_bf16 v[44:47], v[132:135], v[172:175], v[44:47]
	v_mfma_f32_16x16x32_bf16 v[40:43], v[140:143], v[172:175], v[40:43]
	v_mfma_f32_16x16x32_bf16 v[28:31], v[132:135], v[180:183], v[28:31]
	v_mfma_f32_16x16x32_bf16 v[24:27], v[140:143], v[180:183], v[24:27]
	v_mfma_f32_16x16x32_bf16 v[12:15], v[132:135], v[188:191], v[12:15]
	v_mfma_f32_16x16x32_bf16 v[8:11], v[140:143], v[188:191], v[8:11]
	s_barrier
	s_add_u32 s26, s36, 0x160000
	s_addc_u32 s27, s37, 0
	s_add_i32 s34, s35, s31
	s_mov_b32 m0, s34
	s_nop 0
	global_load_lds_dwordx4 v208, s[26:27]
	s_add_i32 m0, s34, 0x2000
	s_nop 0
	global_load_lds_dwordx4 v148, s[26:27]
	s_waitcnt vmcnt(6)
	s_barrier
; #define PG8_STAGE(bufoff, gbase, voff) do { _Pragma("unroll") for (int _i = 0; _i < 2; ++_i) \
;         __builtin_amdgcn_global_load_lds((const unsigned*)((const char*)(gbase) + (voff)[_i]), (LAS unsigned*)(lds + (bufoff) + ldsw + _i * 8192), 16, 0, 0); } while (0)
; #define PG8_LDA(dst, b, h) do { _Pragma("unroll") for (int m = 0; m < 4; ++m) _Pragma("unroll") for (int k = 0; k < 2; ++k) dst[m][k] = *(const LAS bf16x8*)(lds + PG8_SA(b, h) + aoff + m * 2048 + k * 1024); } while (0)
; #define PG8_LDB(dst, b, h) do { _Pragma("unroll") for (int n = 0; n < 2; ++n) _Pragma("unroll") for (int k = 0; k < 2; ++k) dst[n][k] = *(const LAS bf16x8*)(lds + PG8_SB(b, h) + boff + n * 2048 + k * 1024); } while (0)
; #define PG8_MMA(ai, bj, At, Bt) do { __builtin_amdgcn_s_setprio(1); _Pragma("unroll") for (int m = 0; m < 4; ++m) _Pragma("unroll") for (int n = 0; n < 2; ++n) _Pragma("unroll") for (int k = 0; k < 2; ++k) \
;         acc[ai][bj][m][n] = __builtin_amdgcn_mfma_f32_16x16x32_bf16(Bt[n][k], At[m][k], acc[ai][bj][m][n], 0, 0, 0); __builtin_amdgcn_s_setprio(0); } while (0)
; #define PG8_WAIT_V(n) asm volatile("s_waitcnt vmcnt(" #n ")" ::: "memory")
; #define PG8_WAIT_L(n) asm volatile("s_waitcnt lgkmcnt(" #n ")" ::: "memory")
; #define PG8_BAR __builtin_amdgcn_s_barrier()
; #define PG8_SCHED __builtin_amdgcn_sched_barrier(0)
; template <class Epi>
; __device__ __forceinline__ void gemm_phase(LAS unsigned char* lds, const Gemm g, const Epi& E) {
;     ...
;             PG8_WAIT_V(6); PG8_BAR; PG8_MMA(1, 1, At, B1); PG8_BAR;
;             PG8_LDB(B0, 1, 0); PG8_SCHED; PG8_LDA(At, 1, 0); PG8_STAGE(PG8_SA(0, 1), a2 + hstep, voffA);
;             PG8_WAIT_L(8); PG8_BAR; PG8_WAIT_L(0); PG8_MMA(0, 0, At, B0); PG8_BAR; PG8_SCHED;
;             PG8_LDB(B1, 1, 1); PG8_STAGE(PG8_SB(1, 0), b3, voffB);
;             PG8_BAR; PG8_WAIT_L(0); PG8_MMA(0, 1, At, B1); PG8_BAR;
;             PG8_LDA(At, 1, 1); PG8_STAGE(PG8_SA(1, 0), a3, voffA);
;             PG8_BAR; PG8_WAIT_L(0); PG8_MMA(1, 0, At, B0); PG8_BAR; PG8_SCHED;
;             PG8_STAGE(PG8_SB(1, 1), b3 + hstep, voffB);
;             PG8_WAIT_V(6); PG8_BAR; PG8_MMA(1, 1, At, B1); PG8_BAR;
	v_mfma_f32_16x16x32_bf16 v[52:55], v[192:195], v[156:159], v[52:55]
	v_mfma_f32_16x16x32_bf16 v[48:51], v[200:203], v[156:159], v[48:51]
	v_mfma_f32_16x16x32_bf16 v[36:39], v[192:195], v[168:171], v[36:39]
	v_mfma_f32_16x16x32_bf16 v[32:35], v[200:203], v[168:171], v[32:35]
	v_mfma_f32_16x16x32_bf16 v[20:23], v[192:195], v[176:179], v[20:23]
	v_mfma_f32_16x16x32_bf16 v[16:19], v[200:203], v[176:179], v[16:19]
	v_mfma_f32_16x16x32_bf16 v[4:7], v[192:195], v[184:187], v[4:7]
	v_mfma_f32_16x16x32_bf16 v[0:3], v[200:203], v[184:187], v[0:3]
	v_mfma_f32_16x16x32_bf16 v[52:55], v[196:199], v[164:167], v[52:55]
	v_mfma_f32_16x16x32_bf16 v[48:51], v[204:207], v[164:167], v[48:51]
	v_mfma_f32_16x16x32_bf16 v[36:39], v[196:199], v[172:175], v[36:39]
	v_mfma_f32_16x16x32_bf16 v[32:35], v[204:207], v[172:175], v[32:35]
	v_mfma_f32_16x16x32_bf16 v[20:23], v[196:199], v[180:183], v[20:23]
	v_mfma_f32_16x16x32_bf16 v[16:19], v[204:207], v[180:183], v[16:19]
	v_mfma_f32_16x16x32_bf16 v[4:7], v[196:199], v[188:191], v[4:7]
	v_mfma_f32_16x16x32_bf16 v[0:3], v[204:207], v[188:191], v[0:3]
	s_barrier
	s_add_i32 s34, 0, 0x18000
	v_add_u32_e32 v140, s34, v160
	ds_read_b128 v[128:131], v140
	ds_read_b128 v[132:135], v140 offset:1024
	ds_read_b128 v[136:139], v140 offset:2048
	ds_read_b128 v[140:143], v140 offset:3072
	s_add_u32 s26, s38, 0x160000
	s_addc_u32 s27, s39, 0
	s_mov_b32 m0, s46
	ds_read_b128 v[156:159], v161 offset:32768
	ds_read_b128 v[164:167], v161 offset:33792
	ds_read_b128 v[168:171], v161 offset:34816
	ds_read_b128 v[172:175], v161 offset:35840
	ds_read_b128 v[176:179], v161 offset:36864
	ds_read_b128 v[180:183], v161 offset:37888
	ds_read_b128 v[184:187], v161 offset:38912
	ds_read_b128 v[188:191], v161 offset:39936
	global_load_lds_dwordx4 v144, s[26:27]
	s_mov_b32 m0, s47
	s_nop 0
	global_load_lds_dwordx4 v146, s[26:27]
	s_waitcnt lgkmcnt(8)
	s_barrier
	s_waitcnt lgkmcnt(0)
	v_mfma_f32_16x16x32_bf16 v[124:127], v[128:131], v[156:159], v[124:127]
	v_mfma_f32_16x16x32_bf16 v[120:123], v[136:139], v[156:159], v[120:123]
	v_mfma_f32_16x16x32_bf16 v[108:111], v[128:131], v[168:171], v[108:111]
	v_mfma_f32_16x16x32_bf16 v[104:107], v[136:139], v[168:171], v[104:107]
	v_mfma_f32_16x16x32_bf16 v[92:95], v[128:131], v[176:179], v[92:95]
	v_mfma_f32_16x16x32_bf16 v[88:91], v[136:139], v[176:179], v[88:91]
	v_mfma_f32_16x16x32_bf16 v[76:79], v[128:131], v[184:187], v[76:79]
	v_mfma_f32_16x16x32_bf16 v[72:75], v[136:139], v[184:187], v[72:75]
	v_mfma_f32_16x16x32_bf16 v[124:127], v[132:135], v[164:167], v[124:127]
	v_mfma_f32_16x16x32_bf16 v[120:123], v[140:143], v[164:167], v[120:123]
	v_mfma_f32_16x16x32_bf16 v[108:111], v[132:135], v[172:175], v[108:111]
	v_mfma_f32_16x16x32_bf16 v[104:107], v[140:143], v[172:175], v[104:107]
	v_mfma_f32_16x16x32_bf16 v[92:95], v[132:135], v[180:183], v[92:95]
	v_mfma_f32_16x16x32_bf16 v[88:91], v[140:143], v[180:183], v[88:91]
	v_mfma_f32_16x16x32_bf16 v[76:79], v[132:135], v[188:191], v[76:79]
	v_mfma_f32_16x16x32_bf16 v[72:75], v[140:143], v[188:191], v[72:75]
	s_barrier
	s_add_i32 s35, 0, 0x1c000
	s_add_i32 s26, s34, s31
	v_add_u32_e32 v163, s35, v160
	s_mov_b32 m0, s26
	ds_read_b128 v[192:195], v163
	ds_read_b128 v[196:199], v163 offset:1024
	ds_read_b128 v[200:203], v163 offset:2048
	ds_read_b128 v[204:207], v163 offset:3072
	s_add_u32 s98, s36, 0x80
	s_addc_u32 s99, s37, 0
	global_load_lds_dwordx4 v208, s[98:99]
	s_add_i32 m0, s26, 0x2000
	s_add_u32 s100, s36, 0x80
	s_addc_u32 s101, s37, 0
	global_load_lds_dwordx4 v148, s[100:101]
	s_barrier
	s_waitcnt lgkmcnt(0)
	v_mfma_f32_16x16x32_bf16 v[116:119], v[192:195], v[156:159], v[116:119]
	v_mfma_f32_16x16x32_bf16 v[112:115], v[200:203], v[156:159], v[112:115]
	v_mfma_f32_16x16x32_bf16 v[100:103], v[192:195], v[168:171], v[100:103]
	v_mfma_f32_16x16x32_bf16 v[96:99], v[200:203], v[168:171], v[96:99]
	v_mfma_f32_16x16x32_bf16 v[84:87], v[192:195], v[176:179], v[84:87]
	v_mfma_f32_16x16x32_bf16 v[80:83], v[200:203], v[176:179], v[80:83]
	v_mfma_f32_16x16x32_bf16 v[68:71], v[192:195], v[184:187], v[68:71]
	v_mfma_f32_16x16x32_bf16 v[64:67], v[200:203], v[184:187], v[64:67]
	v_mfma_f32_16x16x32_bf16 v[116:119], v[196:199], v[164:167], v[116:119]
	v_mfma_f32_16x16x32_bf16 v[112:115], v[204:207], v[164:167], v[112:115]
	v_mfma_f32_16x16x32_bf16 v[100:103], v[196:199], v[172:175], v[100:103]
	v_mfma_f32_16x16x32_bf16 v[96:99], v[204:207], v[172:175], v[96:99]
	v_mfma_f32_16x16x32_bf16 v[84:87], v[196:199], v[180:183], v[84:87]
	v_mfma_f32_16x16x32_bf16 v[80:83], v[204:207], v[180:183], v[80:83]
	v_mfma_f32_16x16x32_bf16 v[68:71], v[196:199], v[188:191], v[68:71]
	v_mfma_f32_16x16x32_bf16 v[64:67], v[204:207], v[188:191], v[64:67]
	s_barrier
	s_mov_b32 m0, s64
	ds_read_b128 v[156:159], v161 offset:49152
	ds_read_b128 v[164:167], v161 offset:50176
	ds_read_b128 v[168:171], v161 offset:51200
	ds_read_b128 v[172:175], v161 offset:52224
	ds_read_b128 v[176:179], v161 offset:53248
	ds_read_b128 v[180:183], v161 offset:54272
	ds_read_b128 v[184:187], v161 offset:55296
	ds_read_b128 v[188:191], v161 offset:56320
	s_add_u32 s98, s38, 0x80
	s_addc_u32 s99, s39, 0
	global_load_lds_dwordx4 v144, s[98:99]
	s_mov_b32 m0, s65
	s_add_u32 s100, s38, 0x80
	s_addc_u32 s101, s39, 0
	global_load_lds_dwordx4 v146, s[100:101]
	s_barrier
; __device__ __forceinline__ float bflo(unsigned w) { return __uint_as_float(w << 16); }
; __device__ __forceinline__ float bfhi(unsigned w) { return __uint_as_float(w & 0xffff0000u); }
; __device__ __forceinline__ u32x4 pack8u(f32x4 a, f32x4 b) { u32x4 w = {cvt_pk_bf16(a[0], a[1]), cvt_pk_bf16(a[2], a[3]), cvt_pk_bf16(b[0], b[1]), cvt_pk_bf16(b[2], b[3])}; return w; }
; #define PG8_STAGE(bufoff, gbase, voff) do { _Pragma("unroll") for (int _i = 0; _i < 2; ++_i) \
;         __builtin_amdgcn_global_load_lds((const unsigned*)((const char*)(gbase) + (voff)[_i]), (LAS unsigned*)(lds + (bufoff) + ldsw + _i * 8192), 16, 0, 0); } while (0)
; #define PG8_WAIT_V(n) asm volatile("s_waitcnt vmcnt(" #n ")" ::: "memory")
; #define PG8_WAIT_L(n) asm volatile("s_waitcnt lgkmcnt(" #n ")" ::: "memory")
; template <class Epi>
; __device__ __forceinline__ void gemm_phase(LAS unsigned char* lds, const Gemm g, const Epi& E) {
;     ...
;             PG8_BAR; PG8_WAIT_L(0); PG8_MMA(1, 0, At, B0); PG8_BAR; PG8_SCHED;
;             PG8_STAGE(PG8_SB(1, 1), b3 + hstep, voffB);
;             PG8_WAIT_V(6); PG8_BAR; PG8_MMA(1, 1, At, B1); PG8_BAR;
;     __device__ __forceinline__ void operator()(const AccT& acc, const Unit& u, int wr, int wc, int fr, int fq) const {
;         const int b = (u.pm * 256) / SEQ;
;         f32x4 gt[2][2];
; #pragma unroll
;         for (int bj = 0; bj < 2; ++bj)
; #pragma unroll
;             for (int n = 0; n < 2; ++n) gt[bj][n] = *(const f32x4*)(GT + (size_t)b * 6 * D + u.pn * 256 + bj * 128 + wc * 32 + fq * 8 + 4 * n);
; #pragma unroll
;         for (int ai = 0; ai < 2; ++ai)
; #pragma unroll
;             for (int m = 0; m < 4; ++m) {
;                 const int row = u.pm * 256 + ai * 128 + wr * 64 + m * 16 + fr;
; #pragma unroll
;                 for (int bj = 0; bj < 2; ++bj) {
;                     const size_t off = (size_t)row * D + u.pn * 256 + bj * 128 + wc * 32 + fq * 8;
;                     f32x4 x0, x1;
;                     if (XINF) { x0 = *(const f32x4*)(XINF + off); x1 = *(const f32x4*)(XINF + off + 4); }
;                     else { const u32x4 w = *(const u32x4*)(XIN16 + off); x0 = (f32x4){bflo(w[0]), bfhi(w[0]), bflo(w[1]), bfhi(w[1])}; x1 = (f32x4){bflo(w[2]), bfhi(w[2]), bflo(w[3]), bfhi(w[3])}; }
;                     *(u32x4*)(XOUT + off) = pack8u(x0 + gt[bj][0] * acc[ai][bj][m][0], x1 + gt[bj][1] * acc[ai][bj][m][1]);
	s_waitcnt lgkmcnt(0)
	v_mfma_f32_16x16x32_bf16 v[60:63], v[128:131], v[156:159], v[60:63]
	v_mfma_f32_16x16x32_bf16 v[56:59], v[136:139], v[156:159], v[56:59]
	v_mfma_f32_16x16x32_bf16 v[44:47], v[128:131], v[168:171], v[44:47]
	v_mfma_f32_16x16x32_bf16 v[40:43], v[136:139], v[168:171], v[40:43]
	v_mfma_f32_16x16x32_bf16 v[28:31], v[128:131], v[176:179], v[28:31]
	v_mfma_f32_16x16x32_bf16 v[24:27], v[136:139], v[176:179], v[24:27]
	v_mfma_f32_16x16x32_bf16 v[12:15], v[128:131], v[184:187], v[12:15]
	v_mfma_f32_16x16x32_bf16 v[8:11], v[136:139], v[184:187], v[8:11]
	v_mfma_f32_16x16x32_bf16 v[60:63], v[132:135], v[164:167], v[60:63]
	v_mfma_f32_16x16x32_bf16 v[56:59], v[140:143], v[164:167], v[56:59]
	v_mfma_f32_16x16x32_bf16 v[44:47], v[132:135], v[172:175], v[44:47]
	v_mfma_f32_16x16x32_bf16 v[40:43], v[140:143], v[172:175], v[40:43]
	v_mfma_f32_16x16x32_bf16 v[28:31], v[132:135], v[180:183], v[28:31]
	v_mfma_f32_16x16x32_bf16 v[24:27], v[140:143], v[180:183], v[24:27]
	v_mfma_f32_16x16x32_bf16 v[12:15], v[132:135], v[188:191], v[12:15]
	v_mfma_f32_16x16x32_bf16 v[8:11], v[140:143], v[188:191], v[8:11]
	s_barrier
	s_add_u32 s26, s36, 0x160080
	s_addc_u32 s27, s37, 0
	s_add_i32 s34, s35, s31
	s_mov_b32 m0, s34
	s_nop 0
	global_load_lds_dwordx4 v208, s[26:27]
	s_add_i32 m0, s34, 0x2000
	s_nop 0
	global_load_lds_dwordx4 v148, s[26:27]
	s_waitcnt vmcnt(6)
	s_barrier
	v_mfma_f32_16x16x32_bf16 v[52:55], v[192:195], v[156:159], v[52:55]
	v_mfma_f32_16x16x32_bf16 v[48:51], v[200:203], v[156:159], v[48:51]
	v_mfma_f32_16x16x32_bf16 v[36:39], v[192:195], v[168:171], v[36:39]
	v_mfma_f32_16x16x32_bf16 v[32:35], v[200:203], v[168:171], v[32:35]
	v_mfma_f32_16x16x32_bf16 v[20:23], v[192:195], v[176:179], v[20:23]
	v_mfma_f32_16x16x32_bf16 v[16:19], v[200:203], v[176:179], v[16:19]
	v_mfma_f32_16x16x32_bf16 v[4:7], v[192:195], v[184:187], v[4:7]
	v_mfma_f32_16x16x32_bf16 v[0:3], v[200:203], v[184:187], v[0:3]
	v_mfma_f32_16x16x32_bf16 v[52:55], v[196:199], v[164:167], v[52:55]
	v_mfma_f32_16x16x32_bf16 v[48:51], v[204:207], v[164:167], v[48:51]
	v_mfma_f32_16x16x32_bf16 v[36:39], v[196:199], v[172:175], v[36:39]
	v_mfma_f32_16x16x32_bf16 v[32:35], v[204:207], v[172:175], v[32:35]
	v_mfma_f32_16x16x32_bf16 v[20:23], v[196:199], v[180:183], v[20:23]
	v_mfma_f32_16x16x32_bf16 v[16:19], v[204:207], v[180:183], v[16:19]
	v_mfma_f32_16x16x32_bf16 v[4:7], v[196:199], v[188:191], v[4:7]
	v_mfma_f32_16x16x32_bf16 v[0:3], v[204:207], v[188:191], v[0:3]
	s_add_i32 s82, s82, 2
	s_add_u32 s78, s78, 0x100
	s_addc_u32 s79, s79, 0
	s_cmpk_gt_u32 s82, 0x55
	s_mov_b64 s[26:27], s[28:29]
	s_barrier
	s_cbranch_scc0 .LBB0_873
	s_ashr_i32 s26, s74, 31
	s_lshr_b32 s26, s26, 29
	s_add_i32 s26, s74, s26
	s_ashr_i32 s26, s26, 3
	s_mul_i32 s26, s26, 6
	s_ashr_i32 s27, s26, 31
	s_lshl_b64 s[26:27], s[26:27], 13
	s_add_u32 s28, s48, s26
	s_addc_u32 s29, s49, s27
	s_lshl_b32 s26, s76, 8
	s_ashr_i32 s27, s26, 31
	v_lshl_add_u32 v157, s74, 8, v151
	v_or_b32_e32 v158, s26, v150
	s_lshl_b64 s[26:27], s[26:27], 2
	s_add_u32 s26, s28, s26
	s_addc_u32 s27, s29, s27
	s_add_u32 s26, s26, s69
	s_addc_u32 s27, s27, 0
	global_load_dwordx4 v[140:143], v162, s[26:27]
	global_load_dwordx4 v[136:139], v162, s[26:27] offset:16
	global_load_dwordx4 v[132:135], v162, s[26:27] offset:512
	global_load_dwordx4 v[128:131], v162, s[26:27] offset:528
	v_lshlrev_b32_e32 v156, 1, v158
	v_lshl_add_u32 v156, v157, 12, v156
	v_add_u32_e32 v157, 0x0, v156
	global_load_dwordx4 v[164:167], v157, s[96:97] offset:0
	v_add_u32_e32 v157, 0x0, v156
	global_load_dwordx4 v[168:171], v157, s[96:97] offset:256
	v_add_u32_e32 v157, 0x10000, v156
	global_load_dwordx4 v[172:175], v157, s[96:97] offset:0
	v_add_u32_e32 v157, 0x10000, v156
	global_load_dwordx4 v[184:187], v157, s[96:97] offset:256
	v_add_u32_e32 v157, 0x20000, v156
	global_load_dwordx4 v[188:191], v157, s[96:97] offset:0
	v_add_u32_e32 v157, 0x20000, v156
	global_load_dwordx4 v[192:195], v157, s[96:97] offset:256
	v_add_u32_e32 v157, 0x30000, v156
	global_load_dwordx4 v[196:199], v157, s[96:97] offset:0
	v_add_u32_e32 v157, 0x30000, v156
	global_load_dwordx4 v[200:203], v157, s[96:97] offset:256
	v_add_u32_e32 v157, 0x80000, v156
	global_load_dwordx4 v[204:207], v157, s[96:97] offset:0
	v_add_u32_e32 v157, 0x80000, v156
	global_load_dwordx4 v[228:231], v157, s[96:97] offset:256
	s_waitcnt vmcnt(9)
	v_lshlrev_b32_e32 v176, 16, v164
	v_and_b32_e32 v177, 0xffff0000, v164
	v_lshlrev_b32_e32 v178, 16, v165
	v_and_b32_e32 v179, 0xffff0000, v165
	v_lshlrev_b32_e32 v180, 16, v166
	v_and_b32_e32 v181, 0xffff0000, v166
	v_lshlrev_b32_e32 v182, 16, v167
	v_and_b32_e32 v183, 0xffff0000, v167
	v_pk_fma_f32 v[124:125], v[124:125], v[140:141], v[176:177]
	v_pk_fma_f32 v[126:127], v[126:127], v[142:143], v[178:179]
	v_pk_fma_f32 v[120:121], v[120:121], v[136:137], v[180:181]
	v_pk_fma_f32 v[122:123], v[122:123], v[138:139], v[182:183]
	v_cvt_pk_bf16_f32 v124, v124, v125
	v_cvt_pk_bf16_f32 v125, v126, v127
	v_cvt_pk_bf16_f32 v126, v120, v121
	v_cvt_pk_bf16_f32 v127, v122, v123
	v_add_u32_e32 v158, 0x0, v156
	global_store_dwordx4 v158, v[124:127], s[96:97] offset:0
	v_add_u32_e32 v157, 0x90000, v156
	global_load_dwordx4 v[164:167], v157, s[96:97] offset:0
	v_add_u32_e32 v157, 0x90000, v156
	global_load_dwordx4 v[120:123], v157, s[96:97] offset:256
	s_waitcnt vmcnt(11)
; __device__ __forceinline__ float bflo(unsigned w) { return __uint_as_float(w << 16); }
; __device__ __forceinline__ float bfhi(unsigned w) { return __uint_as_float(w & 0xffff0000u); }
; __device__ __forceinline__ u32x4 pack8u(f32x4 a, f32x4 b) { u32x4 w = {cvt_pk_bf16(a[0], a[1]), cvt_pk_bf16(a[2], a[3]), cvt_pk_bf16(b[0], b[1]), cvt_pk_bf16(b[2], b[3])}; return w; }
;     __device__ __forceinline__ void operator()(const AccT& acc, const Unit& u, int wr, int wc, int fr, int fq) const {
;     ...
;                 for (int bj = 0; bj < 2; ++bj) {
;                     const size_t off = (size_t)row * D + u.pn * 256 + bj * 128 + wc * 32 + fq * 8;
;                     f32x4 x0, x1;
;                     if (XINF) { x0 = *(const f32x4*)(XINF + off); x1 = *(const f32x4*)(XINF + off + 4); }
;                     else { const u32x4 w = *(const u32x4*)(XIN16 + off); x0 = (f32x4){bflo(w[0]), bfhi(w[0]), bflo(w[1]), bfhi(w[1])}; x1 = (f32x4){bflo(w[2]), bfhi(w[2]), bflo(w[3]), bfhi(w[3])}; }
;                     *(u32x4*)(XOUT + off) = pack8u(x0 + gt[bj][0] * acc[ai][bj][m][0], x1 + gt[bj][1] * acc[ai][bj][m][1]);
	v_lshlrev_b32_e32 v176, 16, v168
	v_and_b32_e32 v177, 0xffff0000, v168
	v_lshlrev_b32_e32 v178, 16, v169
	v_and_b32_e32 v179, 0xffff0000, v169
	v_lshlrev_b32_e32 v180, 16, v170
	v_and_b32_e32 v181, 0xffff0000, v170
	v_lshlrev_b32_e32 v182, 16, v171
	v_and_b32_e32 v183, 0xffff0000, v171
	v_pk_fma_f32 v[116:117], v[116:117], v[132:133], v[176:177]
	v_pk_fma_f32 v[118:119], v[118:119], v[134:135], v[178:179]
	v_pk_fma_f32 v[112:113], v[112:113], v[128:129], v[180:181]
	v_pk_fma_f32 v[114:115], v[114:115], v[130:131], v[182:183]
	v_cvt_pk_bf16_f32 v116, v116, v117
	v_cvt_pk_bf16_f32 v117, v118, v119
	v_cvt_pk_bf16_f32 v118, v112, v113
	v_cvt_pk_bf16_f32 v119, v114, v115
	v_add_u32_e32 v158, 0x0, v156
	global_store_dwordx4 v158, v[116:119], s[96:97] offset:256
	v_add_u32_e32 v157, 0xa0000, v156
	global_load_dwordx4 v[168:171], v157, s[96:97] offset:0
	v_add_u32_e32 v157, 0xa0000, v156
	global_load_dwordx4 v[112:115], v157, s[96:97] offset:256
	s_waitcnt vmcnt(13)
	v_lshlrev_b32_e32 v176, 16, v172
	v_and_b32_e32 v177, 0xffff0000, v172
	v_lshlrev_b32_e32 v178, 16, v173
	v_and_b32_e32 v179, 0xffff0000, v173
	v_lshlrev_b32_e32 v180, 16, v174
	v_and_b32_e32 v181, 0xffff0000, v174
	v_lshlrev_b32_e32 v182, 16, v175
	v_and_b32_e32 v183, 0xffff0000, v175
	v_pk_fma_f32 v[108:109], v[108:109], v[140:141], v[176:177]
	v_pk_fma_f32 v[110:111], v[110:111], v[142:143], v[178:179]
	v_pk_fma_f32 v[104:105], v[104:105], v[136:137], v[180:181]
	v_pk_fma_f32 v[106:107], v[106:107], v[138:139], v[182:183]
	v_cvt_pk_bf16_f32 v108, v108, v109
	v_cvt_pk_bf16_f32 v109, v110, v111
	v_cvt_pk_bf16_f32 v110, v104, v105
	v_cvt_pk_bf16_f32 v111, v106, v107
	v_add_u32_e32 v158, 0x10000, v156
	global_store_dwordx4 v158, v[108:111], s[96:97] offset:0
	v_add_u32_e32 v157, 0xb0000, v156
	global_load_dwordx4 v[172:175], v157, s[96:97] offset:0
	v_add_u32_e32 v157, 0xb0000, v156
	global_load_dwordx4 v[104:107], v157, s[96:97] offset:256
	s_waitcnt vmcnt(15)
	v_lshlrev_b32_e32 v176, 16, v184
	v_and_b32_e32 v177, 0xffff0000, v184
	v_lshlrev_b32_e32 v178, 16, v185
	v_and_b32_e32 v179, 0xffff0000, v185
	v_lshlrev_b32_e32 v180, 16, v186
	v_and_b32_e32 v181, 0xffff0000, v186
	v_lshlrev_b32_e32 v182, 16, v187
	v_and_b32_e32 v183, 0xffff0000, v187
	v_pk_fma_f32 v[100:101], v[100:101], v[132:133], v[176:177]
	v_pk_fma_f32 v[102:103], v[102:103], v[134:135], v[178:179]
	v_pk_fma_f32 v[96:97], v[96:97], v[128:129], v[180:181]
	v_pk_fma_f32 v[98:99], v[98:99], v[130:131], v[182:183]
	v_cvt_pk_bf16_f32 v100, v100, v101
	v_cvt_pk_bf16_f32 v101, v102, v103
	v_cvt_pk_bf16_f32 v102, v96, v97
	v_cvt_pk_bf16_f32 v103, v98, v99
	v_add_u32_e32 v158, 0x10000, v156
	global_store_dwordx4 v158, v[100:103], s[96:97] offset:256
	s_waitcnt vmcnt(15)
	v_lshlrev_b32_e32 v176, 16, v188
	v_and_b32_e32 v177, 0xffff0000, v188
	v_lshlrev_b32_e32 v178, 16, v189
	v_and_b32_e32 v179, 0xffff0000, v189
	v_lshlrev_b32_e32 v180, 16, v190
	v_and_b32_e32 v181, 0xffff0000, v190
	v_lshlrev_b32_e32 v182, 16, v191
	v_and_b32_e32 v183, 0xffff0000, v191
	v_pk_fma_f32 v[92:93], v[92:93], v[140:141], v[176:177]
	v_pk_fma_f32 v[94:95], v[94:95], v[142:143], v[178:179]
	v_pk_fma_f32 v[88:89], v[88:89], v[136:137], v[180:181]
	v_pk_fma_f32 v[90:91], v[90:91], v[138:139], v[182:183]
	v_cvt_pk_bf16_f32 v92, v92, v93
	v_cvt_pk_bf16_f32 v93, v94, v95
	v_cvt_pk_bf16_f32 v94, v88, v89
	v_cvt_pk_bf16_f32 v95, v90, v91
	v_add_u32_e32 v158, 0x20000, v156
	global_store_dwordx4 v158, v[92:95], s[96:97] offset:0
	s_waitcnt vmcnt(15)
	v_lshlrev_b32_e32 v176, 16, v192
	v_and_b32_e32 v177, 0xffff0000, v192
	v_lshlrev_b32_e32 v178, 16, v193
	v_and_b32_e32 v179, 0xffff0000, v193
	v_lshlrev_b32_e32 v180, 16, v194
	v_and_b32_e32 v181, 0xffff0000, v194
	v_lshlrev_b32_e32 v182, 16, v195
	v_and_b32_e32 v183, 0xffff0000, v195
	v_pk_fma_f32 v[84:85], v[84:85], v[132:133], v[176:177]
	v_pk_fma_f32 v[86:87], v[86:87], v[134:135], v[178:179]
	v_pk_fma_f32 v[80:81], v[80:81], v[128:129], v[180:181]
	v_pk_fma_f32 v[82:83], v[82:83], v[130:131], v[182:183]
	v_cvt_pk_bf16_f32 v84, v84, v85
	v_cvt_pk_bf16_f32 v85, v86, v87
	v_cvt_pk_bf16_f32 v86, v80, v81
	v_cvt_pk_bf16_f32 v87, v82, v83
	v_add_u32_e32 v158, 0x20000, v156
	global_store_dwordx4 v158, v[84:87], s[96:97] offset:256
	s_waitcnt vmcnt(15)
	v_lshlrev_b32_e32 v176, 16, v196
	v_and_b32_e32 v177, 0xffff0000, v196
	v_lshlrev_b32_e32 v178, 16, v197
	v_and_b32_e32 v179, 0xffff0000, v197
	v_lshlrev_b32_e32 v180, 16, v198
	v_and_b32_e32 v181, 0xffff0000, v198
	v_lshlrev_b32_e32 v182, 16, v199
	v_and_b32_e32 v183, 0xffff0000, v199
	v_pk_fma_f32 v[76:77], v[76:77], v[140:141], v[176:177]
	v_pk_fma_f32 v[78:79], v[78:79], v[142:143], v[178:179]
	v_pk_fma_f32 v[72:73], v[72:73], v[136:137], v[180:181]
	v_pk_fma_f32 v[74:75], v[74:75], v[138:139], v[182:183]
	v_cvt_pk_bf16_f32 v76, v76, v77
	v_cvt_pk_bf16_f32 v77, v78, v79
	v_cvt_pk_bf16_f32 v78, v72, v73
	v_cvt_pk_bf16_f32 v79, v74, v75
	v_add_u32_e32 v158, 0x30000, v156
	global_store_dwordx4 v158, v[76:79], s[96:97] offset:0
	s_waitcnt vmcnt(15)
	v_lshlrev_b32_e32 v176, 16, v200
	v_and_b32_e32 v177, 0xffff0000, v200
	v_lshlrev_b32_e32 v178, 16, v201
	v_and_b32_e32 v179, 0xffff0000, v201
	v_lshlrev_b32_e32 v180, 16, v202
	v_and_b32_e32 v181, 0xffff0000, v202
	v_lshlrev_b32_e32 v182, 16, v203
	v_and_b32_e32 v183, 0xffff0000, v203
	v_pk_fma_f32 v[68:69], v[68:69], v[132:133], v[176:177]
	v_pk_fma_f32 v[70:71], v[70:71], v[134:135], v[178:179]
	v_pk_fma_f32 v[64:65], v[64:65], v[128:129], v[180:181]
	v_pk_fma_f32 v[66:67], v[66:67], v[130:131], v[182:183]
	v_cvt_pk_bf16_f32 v68, v68, v69
	v_cvt_pk_bf16_f32 v69, v70, v71
	v_cvt_pk_bf16_f32 v70, v64, v65
	v_cvt_pk_bf16_f32 v71, v66, v67
	v_add_u32_e32 v158, 0x30000, v156
	global_store_dwordx4 v158, v[68:71], s[96:97] offset:256
	s_waitcnt vmcnt(15)
; __device__ __forceinline__ float bflo(unsigned w) { return __uint_as_float(w << 16); }
; __device__ __forceinline__ float bfhi(unsigned w) { return __uint_as_float(w & 0xffff0000u); }
; __device__ __forceinline__ u32x4 pack8u(f32x4 a, f32x4 b) { u32x4 w = {cvt_pk_bf16(a[0], a[1]), cvt_pk_bf16(a[2], a[3]), cvt_pk_bf16(b[0], b[1]), cvt_pk_bf16(b[2], b[3])}; return w; }
; #define PG8_WAIT_V(n) asm volatile("s_waitcnt vmcnt(" #n ")" ::: "memory")
; #define PG8_BAR __builtin_amdgcn_s_barrier()
; template <class Epi>
; __device__ __forceinline__ void gemm_phase(LAS unsigned char* lds, const Gemm g, const Epi& E) {
;     ...
;         if (!has_next) break;
; #pragma unroll
;         for (int a = 0; a < 2; ++a)
; #pragma unroll
;             for (int b = 0; b < 2; ++b)
; #pragma unroll
;                 for (int m = 0; m < 4; ++m)
; #pragma unroll
;                     for (int n = 0; n < 2; ++n) acc[a][b][m][n] = (f32x4){0.f, 0.f, 0.f, 0.f};
;         cur = nxt; cA = nA; cB = nB; ++ui;
;     }
;     PG8_WAIT_V(0);
;     if (wr == 0) PG8_BAR;
;     __device__ __forceinline__ void operator()(const AccT& acc, const Unit& u, int wr, int wc, int fr, int fq) const {
;     ...
;                 for (int bj = 0; bj < 2; ++bj) {
;                     const size_t off = (size_t)row * D + u.pn * 256 + bj * 128 + wc * 32 + fq * 8;
;                     f32x4 x0, x1;
;                     if (XINF) { x0 = *(const f32x4*)(XINF + off); x1 = *(const f32x4*)(XINF + off + 4); }
;                     else { const u32x4 w = *(const u32x4*)(XIN16 + off); x0 = (f32x4){bflo(w[0]), bfhi(w[0]), bflo(w[1]), bfhi(w[1])}; x1 = (f32x4){bflo(w[2]), bfhi(w[2]), bflo(w[3]), bfhi(w[3])}; }
;                     *(u32x4*)(XOUT + off) = pack8u(x0 + gt[bj][0] * acc[ai][bj][m][0], x1 + gt[bj][1] * acc[ai][bj][m][1]);
	v_lshlrev_b32_e32 v176, 16, v204
	v_and_b32_e32 v177, 0xffff0000, v204
	v_lshlrev_b32_e32 v178, 16, v205
	v_and_b32_e32 v179, 0xffff0000, v205
	v_lshlrev_b32_e32 v180, 16, v206
	v_and_b32_e32 v181, 0xffff0000, v206
	v_lshlrev_b32_e32 v182, 16, v207
	v_and_b32_e32 v183, 0xffff0000, v207
	v_pk_fma_f32 v[60:61], v[60:61], v[140:141], v[176:177]
	v_pk_fma_f32 v[62:63], v[62:63], v[142:143], v[178:179]
	v_pk_fma_f32 v[56:57], v[56:57], v[136:137], v[180:181]
	v_pk_fma_f32 v[58:59], v[58:59], v[138:139], v[182:183]
	v_cvt_pk_bf16_f32 v60, v60, v61
	v_cvt_pk_bf16_f32 v61, v62, v63
	v_cvt_pk_bf16_f32 v62, v56, v57
	v_cvt_pk_bf16_f32 v63, v58, v59
	v_add_u32_e32 v158, 0x80000, v156
	global_store_dwordx4 v158, v[60:63], s[96:97] offset:0
	s_waitcnt vmcnt(15)
	v_lshlrev_b32_e32 v176, 16, v228
	v_and_b32_e32 v177, 0xffff0000, v228
	v_lshlrev_b32_e32 v178, 16, v229
	v_and_b32_e32 v179, 0xffff0000, v229
	v_lshlrev_b32_e32 v180, 16, v230
	v_and_b32_e32 v181, 0xffff0000, v230
	v_lshlrev_b32_e32 v182, 16, v231
	v_and_b32_e32 v183, 0xffff0000, v231
	v_pk_fma_f32 v[52:53], v[52:53], v[132:133], v[176:177]
	v_pk_fma_f32 v[54:55], v[54:55], v[134:135], v[178:179]
	v_pk_fma_f32 v[48:49], v[48:49], v[128:129], v[180:181]
	v_pk_fma_f32 v[50:51], v[50:51], v[130:131], v[182:183]
	v_cvt_pk_bf16_f32 v52, v52, v53
	v_cvt_pk_bf16_f32 v53, v54, v55
	v_cvt_pk_bf16_f32 v54, v48, v49
	v_cvt_pk_bf16_f32 v55, v50, v51
	v_add_u32_e32 v158, 0x80000, v156
	global_store_dwordx4 v158, v[52:55], s[96:97] offset:256
	s_waitcnt vmcnt(14)
	v_lshlrev_b32_e32 v176, 16, v164
	v_and_b32_e32 v177, 0xffff0000, v164
	v_lshlrev_b32_e32 v178, 16, v165
	v_and_b32_e32 v179, 0xffff0000, v165
	v_lshlrev_b32_e32 v180, 16, v166
	v_and_b32_e32 v181, 0xffff0000, v166
	v_lshlrev_b32_e32 v182, 16, v167
	v_and_b32_e32 v183, 0xffff0000, v167
	v_pk_fma_f32 v[44:45], v[44:45], v[140:141], v[176:177]
	v_pk_fma_f32 v[46:47], v[46:47], v[142:143], v[178:179]
	v_pk_fma_f32 v[40:41], v[40:41], v[136:137], v[180:181]
	v_pk_fma_f32 v[42:43], v[42:43], v[138:139], v[182:183]
	v_cvt_pk_bf16_f32 v44, v44, v45
	v_cvt_pk_bf16_f32 v45, v46, v47
	v_cvt_pk_bf16_f32 v46, v40, v41
	v_cvt_pk_bf16_f32 v47, v42, v43
	v_add_u32_e32 v158, 0x90000, v156
	global_store_dwordx4 v158, v[44:47], s[96:97] offset:0
	s_waitcnt vmcnt(14)
	v_lshlrev_b32_e32 v176, 16, v120
	v_and_b32_e32 v177, 0xffff0000, v120
	v_lshlrev_b32_e32 v178, 16, v121
	v_and_b32_e32 v179, 0xffff0000, v121
	v_lshlrev_b32_e32 v180, 16, v122
	v_and_b32_e32 v181, 0xffff0000, v122
	v_lshlrev_b32_e32 v182, 16, v123
	v_and_b32_e32 v183, 0xffff0000, v123
	v_pk_fma_f32 v[36:37], v[36:37], v[132:133], v[176:177]
	v_pk_fma_f32 v[38:39], v[38:39], v[134:135], v[178:179]
	v_pk_fma_f32 v[32:33], v[32:33], v[128:129], v[180:181]
	v_pk_fma_f32 v[34:35], v[34:35], v[130:131], v[182:183]
	v_cvt_pk_bf16_f32 v36, v36, v37
	v_cvt_pk_bf16_f32 v37, v38, v39
	v_cvt_pk_bf16_f32 v38, v32, v33
	v_cvt_pk_bf16_f32 v39, v34, v35
	v_add_u32_e32 v158, 0x90000, v156
	global_store_dwordx4 v158, v[36:39], s[96:97] offset:256
	s_waitcnt vmcnt(13)
	v_lshlrev_b32_e32 v176, 16, v168
	v_and_b32_e32 v177, 0xffff0000, v168
	v_lshlrev_b32_e32 v178, 16, v169
	v_and_b32_e32 v179, 0xffff0000, v169
	v_lshlrev_b32_e32 v180, 16, v170
	v_and_b32_e32 v181, 0xffff0000, v170
	v_lshlrev_b32_e32 v182, 16, v171
	v_and_b32_e32 v183, 0xffff0000, v171
	v_pk_fma_f32 v[28:29], v[28:29], v[140:141], v[176:177]
	v_pk_fma_f32 v[30:31], v[30:31], v[142:143], v[178:179]
	v_pk_fma_f32 v[24:25], v[24:25], v[136:137], v[180:181]
	v_pk_fma_f32 v[26:27], v[26:27], v[138:139], v[182:183]
	v_cvt_pk_bf16_f32 v28, v28, v29
	v_cvt_pk_bf16_f32 v29, v30, v31
	v_cvt_pk_bf16_f32 v30, v24, v25
	v_cvt_pk_bf16_f32 v31, v26, v27
	v_add_u32_e32 v158, 0xa0000, v156
	global_store_dwordx4 v158, v[28:31], s[96:97] offset:0
	s_waitcnt vmcnt(13)
	v_lshlrev_b32_e32 v176, 16, v112
	v_and_b32_e32 v177, 0xffff0000, v112
	v_lshlrev_b32_e32 v178, 16, v113
	v_and_b32_e32 v179, 0xffff0000, v113
	v_lshlrev_b32_e32 v180, 16, v114
	v_and_b32_e32 v181, 0xffff0000, v114
	v_lshlrev_b32_e32 v182, 16, v115
	v_and_b32_e32 v183, 0xffff0000, v115
	v_pk_fma_f32 v[20:21], v[20:21], v[132:133], v[176:177]
	v_pk_fma_f32 v[22:23], v[22:23], v[134:135], v[178:179]
	v_pk_fma_f32 v[16:17], v[16:17], v[128:129], v[180:181]
	v_pk_fma_f32 v[18:19], v[18:19], v[130:131], v[182:183]
	v_cvt_pk_bf16_f32 v20, v20, v21
	v_cvt_pk_bf16_f32 v21, v22, v23
	v_cvt_pk_bf16_f32 v22, v16, v17
	v_cvt_pk_bf16_f32 v23, v18, v19
	v_add_u32_e32 v158, 0xa0000, v156
	global_store_dwordx4 v158, v[20:23], s[96:97] offset:256
	s_waitcnt vmcnt(12)
	v_lshlrev_b32_e32 v176, 16, v172
	v_and_b32_e32 v177, 0xffff0000, v172
	v_lshlrev_b32_e32 v178, 16, v173
	v_and_b32_e32 v179, 0xffff0000, v173
	v_lshlrev_b32_e32 v180, 16, v174
	v_and_b32_e32 v181, 0xffff0000, v174
	v_lshlrev_b32_e32 v182, 16, v175
	v_and_b32_e32 v183, 0xffff0000, v175
	v_pk_fma_f32 v[12:13], v[12:13], v[140:141], v[176:177]
	v_pk_fma_f32 v[14:15], v[14:15], v[142:143], v[178:179]
	v_pk_fma_f32 v[8:9], v[8:9], v[136:137], v[180:181]
	v_pk_fma_f32 v[10:11], v[10:11], v[138:139], v[182:183]
	v_cvt_pk_bf16_f32 v12, v12, v13
	v_cvt_pk_bf16_f32 v13, v14, v15
	v_cvt_pk_bf16_f32 v14, v8, v9
	v_cvt_pk_bf16_f32 v15, v10, v11
	v_add_u32_e32 v158, 0xb0000, v156
	global_store_dwordx4 v158, v[12:15], s[96:97] offset:0
	s_waitcnt vmcnt(12)
	v_lshlrev_b32_e32 v176, 16, v104
	v_and_b32_e32 v177, 0xffff0000, v104
	v_lshlrev_b32_e32 v178, 16, v105
	v_and_b32_e32 v179, 0xffff0000, v105
	v_lshlrev_b32_e32 v180, 16, v106
	v_and_b32_e32 v181, 0xffff0000, v106
	v_lshlrev_b32_e32 v182, 16, v107
	v_and_b32_e32 v183, 0xffff0000, v107
	v_pk_fma_f32 v[4:5], v[4:5], v[132:133], v[176:177]
	v_pk_fma_f32 v[6:7], v[6:7], v[134:135], v[178:179]
	v_pk_fma_f32 v[0:1], v[0:1], v[128:129], v[180:181]
	v_pk_fma_f32 v[2:3], v[2:3], v[130:131], v[182:183]
	v_cvt_pk_bf16_f32 v4, v4, v5
	v_cvt_pk_bf16_f32 v5, v6, v7
	v_cvt_pk_bf16_f32 v6, v0, v1
	v_cvt_pk_bf16_f32 v7, v2, v3
	v_add_u32_e32 v158, 0xb0000, v156
	global_store_dwordx4 v158, v[4:7], s[96:97] offset:256
	s_mov_b64 s[28:29], s[42:43]
	s_mov_b64 s[26:27], s[0:1]
	s_mov_b32 s74, s71
	s_mov_b32 s76, s70
	s_and_b64 vcc, exec, s[40:41]
	v_readlane_b32 s82, v255, 24
	v_readlane_b32 s83, v255, 25
	s_cbranch_vccz .LBB0_862
	s_waitcnt vmcnt(0)
	s_cmpk_gt_u32 s3, 0xff
	s_cbranch_scc1 .LBB0_877
	s_barrier
